# all GEMM K-loops: per-segment s_setprio toggling removed (224 instructions); attention static priority kept
# speedup vs baseline: 1.0053x; 1.0031x over previous
.Lzgo_1:
	s_add_u32 s22, s22, 0x80
	s_addc_u32 s23, s23, 0
	s_add_u32 vcc_lo, s66, 0x100
	s_addc_u32 vcc_hi, s67, 0
	s_mov_b32 s66, 0
	s_add_i32 s88, s66, 2
	s_add_u32 s62, s22, 0x80
	s_addc_u32 s63, s23, 0
	s_add_i32 s89, 0, 0x10000
	s_cmp_eq_u32 s93, s66
	s_cselect_b32 s67, s3, s63
	s_cselect_b32 s66, s2, s62
	v_add_u32_e32 v149, s89, v146
	s_cselect_b32 s63, s21, vcc_hi
	s_cselect_b32 s62, s20, vcc_lo
	s_add_i32 s31, 0, 0x14000
	ds_read_b128 v[142:145], v149
	ds_read_b128 v[150:153], v149 offset:1024
	ds_read_b128 v[154:157], v149 offset:2048
	ds_read_b128 v[158:161], v149 offset:3072
	v_add_u32_e32 v149, s31, v146
	ds_read_b128 v[162:165], v149
	ds_read_b128 v[166:169], v149 offset:1024
	ds_read_b128 v[170:173], v149 offset:2048
	ds_read_b128 v[174:177], v149 offset:3072
	v_lshl_add_u64 v[218:219], s[22:23], 0, v[138:139]
	s_add_i32 m0, s77, 0xc000
	ds_read_b128 v[178:181], v148
	ds_read_b128 v[182:185], v148 offset:1024
	ds_read_b128 v[186:189], v148 offset:2048
	ds_read_b128 v[190:193], v148 offset:3072
	ds_read_b128 v[194:197], v148 offset:4096
	ds_read_b128 v[198:201], v148 offset:5120
	ds_read_b128 v[202:205], v148 offset:6144
	ds_read_b128 v[214:217], v148 offset:7168
	global_load_lds_dwordx4 v[218:219], off
	v_lshl_add_u64 v[218:219], s[22:23], 0, v[140:141]
	s_add_i32 m0, s77, 0xe000
	s_nop 0
	global_load_lds_dwordx4 v[218:219], off
	s_waitcnt vmcnt(8)
	s_waitcnt lgkmcnt(0)
	s_barrier
	s_waitcnt lgkmcnt(0)
	v_mfma_f32_16x16x32_bf16 v[122:125], v[142:145], v[178:181], 0
	v_mfma_f32_16x16x32_bf16 v[118:121], v[154:157], v[178:181], 0
	v_mfma_f32_16x16x32_bf16 v[110:113], v[142:145], v[186:189], 0
	v_mfma_f32_16x16x32_bf16 v[102:105], v[154:157], v[186:189], 0
	v_mfma_f32_16x16x32_bf16 v[94:97], v[142:145], v[194:197], 0
	v_mfma_f32_16x16x32_bf16 v[86:89], v[154:157], v[194:197], 0
	v_mfma_f32_16x16x32_bf16 v[78:81], v[142:145], v[202:205], 0
	v_mfma_f32_16x16x32_bf16 v[70:73], v[154:157], v[202:205], 0
	v_mfma_f32_16x16x32_bf16 v[122:125], v[150:153], v[182:185], v[122:125]
	v_mfma_f32_16x16x32_bf16 v[118:121], v[158:161], v[182:185], v[118:121]
	v_mfma_f32_16x16x32_bf16 v[110:113], v[150:153], v[190:193], v[110:113]
	v_mfma_f32_16x16x32_bf16 v[102:105], v[158:161], v[190:193], v[102:105]
	v_mfma_f32_16x16x32_bf16 v[94:97], v[150:153], v[198:201], v[94:97]
	v_mfma_f32_16x16x32_bf16 v[86:89], v[158:161], v[198:201], v[86:89]
	v_mfma_f32_16x16x32_bf16 v[78:81], v[150:153], v[214:217], v[78:81]
	v_mfma_f32_16x16x32_bf16 v[70:73], v[158:161], v[214:217], v[70:73]
	v_mfma_f32_16x16x32_bf16 v[126:129], v[162:165], v[178:181], 0
	v_mfma_f32_16x16x32_bf16 v[114:117], v[170:173], v[178:181], 0
	v_mfma_f32_16x16x32_bf16 v[106:109], v[162:165], v[186:189], 0
	v_mfma_f32_16x16x32_bf16 v[98:101], v[170:173], v[186:189], 0
	v_mfma_f32_16x16x32_bf16 v[90:93], v[162:165], v[194:197], 0
	v_mfma_f32_16x16x32_bf16 v[82:85], v[170:173], v[194:197], 0
	v_mfma_f32_16x16x32_bf16 v[74:77], v[162:165], v[202:205], 0
	v_mfma_f32_16x16x32_bf16 v[66:69], v[170:173], v[202:205], 0
	v_mfma_f32_16x16x32_bf16 v[126:129], v[166:169], v[182:185], v[126:129]
	v_mfma_f32_16x16x32_bf16 v[114:117], v[174:177], v[182:185], v[114:117]
	v_mfma_f32_16x16x32_bf16 v[106:109], v[166:169], v[190:193], v[106:109]
	v_mfma_f32_16x16x32_bf16 v[98:101], v[174:177], v[190:193], v[98:101]
	v_mfma_f32_16x16x32_bf16 v[90:93], v[166:169], v[198:201], v[90:93]
	v_mfma_f32_16x16x32_bf16 v[82:85], v[174:177], v[198:201], v[82:85]
	v_mfma_f32_16x16x32_bf16 v[74:77], v[166:169], v[214:217], v[74:77]
	v_mfma_f32_16x16x32_bf16 v[66:69], v[174:177], v[214:217], v[66:69]
	s_barrier
	s_add_i32 s89, s89, s74
	v_lshl_add_u64 v[218:219], s[62:63], 0, v[134:135]
	s_mov_b32 m0, s89
	ds_read_b128 v[178:181], v148 offset:16384
	ds_read_b128 v[182:185], v148 offset:17408
	ds_read_b128 v[186:189], v148 offset:18432
	ds_read_b128 v[190:193], v148 offset:19456
	ds_read_b128 v[194:197], v148 offset:20480
	ds_read_b128 v[198:201], v148 offset:21504
	ds_read_b128 v[202:205], v148 offset:22528
	ds_read_b128 v[214:217], v148 offset:23552
	global_load_lds_dwordx4 v[218:219], off
	s_add_i32 m0, s89, 0x2000
	v_lshl_add_u64 v[220:221], s[62:63], 0, v[130:131]
	s_add_u32 s62, s62, s8
	s_addc_u32 s63, s63, s9
	s_add_i32 s31, s31, s74
	global_load_lds_dwordx4 v[220:221], off
	v_lshl_add_u64 v[222:223], s[62:63], 0, v[134:135]
	s_mov_b32 m0, s31
	v_lshl_add_u64 v[224:225], s[62:63], 0, v[130:131]
	global_load_lds_dwordx4 v[222:223], off
	s_add_i32 m0, s31, 0x2000
	v_lshl_add_u64 v[226:227], s[66:67], 0, v[136:137]
	global_load_lds_dwordx4 v[224:225], off
	s_mov_b32 m0, s77
	v_lshl_add_u64 v[236:237], s[66:67], 0, v[132:133]
	global_load_lds_dwordx4 v[226:227], off
	s_mov_b32 m0, s78
	s_nop 0
	global_load_lds_dwordx4 v[236:237], off
	s_waitcnt vmcnt(8)
	s_waitcnt lgkmcnt(0)
	s_barrier
	s_waitcnt lgkmcnt(0)
	v_mfma_f32_16x16x32_bf16 v[62:65], v[142:145], v[178:181], 0
	v_mfma_f32_16x16x32_bf16 v[54:57], v[154:157], v[178:181], 0
	v_mfma_f32_16x16x32_bf16 v[46:49], v[142:145], v[186:189], 0
	v_mfma_f32_16x16x32_bf16 v[38:41], v[154:157], v[186:189], 0
	v_mfma_f32_16x16x32_bf16 v[30:33], v[142:145], v[194:197], 0
	v_mfma_f32_16x16x32_bf16 v[22:25], v[154:157], v[194:197], 0
	v_mfma_f32_16x16x32_bf16 v[14:17], v[142:145], v[202:205], 0
	v_mfma_f32_16x16x32_bf16 v[6:9], v[154:157], v[202:205], 0
	v_mfma_f32_16x16x32_bf16 v[62:65], v[150:153], v[182:185], v[62:65]
	v_mfma_f32_16x16x32_bf16 v[54:57], v[158:161], v[182:185], v[54:57]
	v_mfma_f32_16x16x32_bf16 v[46:49], v[150:153], v[190:193], v[46:49]
	v_mfma_f32_16x16x32_bf16 v[38:41], v[158:161], v[190:193], v[38:41]
	v_mfma_f32_16x16x32_bf16 v[30:33], v[150:153], v[198:201], v[30:33]
	v_mfma_f32_16x16x32_bf16 v[22:25], v[158:161], v[198:201], v[22:25]
	v_mfma_f32_16x16x32_bf16 v[14:17], v[150:153], v[214:217], v[14:17]
	v_mfma_f32_16x16x32_bf16 v[6:9], v[158:161], v[214:217], v[6:9]
	v_mfma_f32_16x16x32_bf16 v[58:61], v[162:165], v[178:181], 0
	v_mfma_f32_16x16x32_bf16 v[50:53], v[170:173], v[178:181], 0
	v_mfma_f32_16x16x32_bf16 v[42:45], v[162:165], v[186:189], 0
	v_mfma_f32_16x16x32_bf16 v[34:37], v[170:173], v[186:189], 0
	v_mfma_f32_16x16x32_bf16 v[26:29], v[162:165], v[194:197], 0
	v_mfma_f32_16x16x32_bf16 v[18:21], v[170:173], v[194:197], 0
	v_mfma_f32_16x16x32_bf16 v[10:13], v[162:165], v[202:205], 0
	v_mfma_f32_16x16x32_bf16 v[2:5], v[170:173], v[202:205], 0
	v_mfma_f32_16x16x32_bf16 v[58:61], v[166:169], v[182:185], v[58:61]
	v_mfma_f32_16x16x32_bf16 v[50:53], v[174:177], v[182:185], v[50:53]
	v_mfma_f32_16x16x32_bf16 v[42:45], v[166:169], v[190:193], v[42:45]
	v_mfma_f32_16x16x32_bf16 v[34:37], v[174:177], v[190:193], v[34:37]
	v_mfma_f32_16x16x32_bf16 v[26:29], v[166:169], v[198:201], v[26:29]
	v_mfma_f32_16x16x32_bf16 v[18:21], v[174:177], v[198:201], v[18:21]
	v_mfma_f32_16x16x32_bf16 v[10:13], v[166:169], v[214:217], v[10:13]
	v_mfma_f32_16x16x32_bf16 v[2:5], v[174:177], v[214:217], v[2:5]
	s_barrier
	s_add_i32 s31, 0, 0x18000
	v_add_u32_e32 v149, s31, v146
	s_add_i32 s89, 0, 0x1c000
	ds_read_b128 v[142:145], v149
	ds_read_b128 v[150:153], v149 offset:1024
	ds_read_b128 v[154:157], v149 offset:2048
	ds_read_b128 v[158:161], v149 offset:3072
	v_add_u32_e32 v149, s89, v146
	ds_read_b128 v[162:165], v149
	ds_read_b128 v[166:169], v149 offset:1024
	ds_read_b128 v[170:173], v149 offset:2048
	ds_read_b128 v[174:177], v149 offset:3072
	s_add_u32 s62, s66, s8
	s_addc_u32 s63, s67, s9
	s_mov_b32 m0, s79
	v_lshl_add_u64 v[238:239], s[62:63], 0, v[136:137]
	ds_read_b128 v[178:181], v148 offset:32768
	ds_read_b128 v[182:185], v148 offset:33792
	ds_read_b128 v[186:189], v148 offset:34816
	ds_read_b128 v[190:193], v148 offset:35840
	ds_read_b128 v[194:197], v148 offset:36864
	ds_read_b128 v[198:201], v148 offset:37888
	ds_read_b128 v[202:205], v148 offset:38912
	ds_read_b128 v[214:217], v148 offset:39936
	global_load_lds_dwordx4 v[238:239], off
	v_lshl_add_u64 v[238:239], s[62:63], 0, v[132:133]
	s_mov_b32 m0, s90
	s_nop 0
	global_load_lds_dwordx4 v[238:239], off
	s_waitcnt vmcnt(8)
	s_waitcnt lgkmcnt(0)
	s_barrier
	s_waitcnt lgkmcnt(0)
	v_mfma_f32_16x16x32_bf16 v[122:125], v[142:145], v[178:181], v[122:125]
	v_mfma_f32_16x16x32_bf16 v[118:121], v[154:157], v[178:181], v[118:121]
	v_mfma_f32_16x16x32_bf16 v[110:113], v[142:145], v[186:189], v[110:113]
	v_mfma_f32_16x16x32_bf16 v[102:105], v[154:157], v[186:189], v[102:105]
	v_mfma_f32_16x16x32_bf16 v[94:97], v[142:145], v[194:197], v[94:97]
	v_mfma_f32_16x16x32_bf16 v[86:89], v[154:157], v[194:197], v[86:89]
	v_mfma_f32_16x16x32_bf16 v[78:81], v[142:145], v[202:205], v[78:81]
	v_mfma_f32_16x16x32_bf16 v[70:73], v[154:157], v[202:205], v[70:73]
	v_mfma_f32_16x16x32_bf16 v[122:125], v[150:153], v[182:185], v[122:125]
	v_mfma_f32_16x16x32_bf16 v[118:121], v[158:161], v[182:185], v[118:121]
	v_mfma_f32_16x16x32_bf16 v[110:113], v[150:153], v[190:193], v[110:113]
	v_mfma_f32_16x16x32_bf16 v[102:105], v[158:161], v[190:193], v[102:105]
	v_mfma_f32_16x16x32_bf16 v[94:97], v[150:153], v[198:201], v[94:97]
	v_mfma_f32_16x16x32_bf16 v[86:89], v[158:161], v[198:201], v[86:89]
	v_mfma_f32_16x16x32_bf16 v[78:81], v[150:153], v[214:217], v[78:81]
	v_mfma_f32_16x16x32_bf16 v[70:73], v[158:161], v[214:217], v[70:73]
	v_mfma_f32_16x16x32_bf16 v[126:129], v[162:165], v[178:181], v[126:129]
	v_mfma_f32_16x16x32_bf16 v[114:117], v[170:173], v[178:181], v[114:117]
	v_mfma_f32_16x16x32_bf16 v[106:109], v[162:165], v[186:189], v[106:109]
	v_mfma_f32_16x16x32_bf16 v[98:101], v[170:173], v[186:189], v[98:101]
	v_mfma_f32_16x16x32_bf16 v[90:93], v[162:165], v[194:197], v[90:93]
	v_mfma_f32_16x16x32_bf16 v[82:85], v[170:173], v[194:197], v[82:85]
	v_mfma_f32_16x16x32_bf16 v[74:77], v[162:165], v[202:205], v[74:77]
	v_mfma_f32_16x16x32_bf16 v[66:69], v[170:173], v[202:205], v[66:69]
	v_mfma_f32_16x16x32_bf16 v[126:129], v[166:169], v[182:185], v[126:129]
	v_mfma_f32_16x16x32_bf16 v[114:117], v[174:177], v[182:185], v[114:117]
	v_mfma_f32_16x16x32_bf16 v[106:109], v[166:169], v[190:193], v[106:109]
	v_mfma_f32_16x16x32_bf16 v[98:101], v[174:177], v[190:193], v[98:101]
	v_mfma_f32_16x16x32_bf16 v[90:93], v[166:169], v[198:201], v[90:93]
	v_mfma_f32_16x16x32_bf16 v[82:85], v[174:177], v[198:201], v[82:85]
	v_mfma_f32_16x16x32_bf16 v[74:77], v[166:169], v[214:217], v[74:77]
	v_mfma_f32_16x16x32_bf16 v[66:69], v[174:177], v[214:217], v[66:69]
	s_barrier
	s_add_i32 s31, s31, s74
	v_lshl_add_u64 v[218:219], v[218:219], 0, s[60:61]
	s_mov_b32 m0, s31
	ds_read_b128 v[178:181], v148 offset:49152
	ds_read_b128 v[182:185], v148 offset:50176
	ds_read_b128 v[186:189], v148 offset:51200
	ds_read_b128 v[190:193], v148 offset:52224
	ds_read_b128 v[194:197], v148 offset:53248
	ds_read_b128 v[198:201], v148 offset:54272
	ds_read_b128 v[202:205], v148 offset:55296
	ds_read_b128 v[214:217], v148 offset:56320
	global_load_lds_dwordx4 v[218:219], off
	v_lshl_add_u64 v[218:219], v[220:221], 0, s[60:61]
	s_add_i32 m0, s31, 0x2000
	s_add_i32 s31, s89, s74
	global_load_lds_dwordx4 v[218:219], off
	v_lshl_add_u64 v[218:219], v[222:223], 0, s[60:61]
	s_mov_b32 m0, s31
	s_nop 0
	global_load_lds_dwordx4 v[218:219], off
	v_lshl_add_u64 v[218:219], v[224:225], 0, s[60:61]
	s_add_i32 m0, s31, 0x2000
	s_nop 0
	global_load_lds_dwordx4 v[218:219], off
	v_lshl_add_u64 v[218:219], v[226:227], 0, s[60:61]
	s_mov_b32 m0, s91
	s_nop 0
	global_load_lds_dwordx4 v[218:219], off
	v_lshl_add_u64 v[218:219], v[236:237], 0, s[60:61]
	s_mov_b32 m0, s92
	s_nop 0
	global_load_lds_dwordx4 v[218:219], off
	s_waitcnt vmcnt(8)
	s_waitcnt lgkmcnt(0)
	s_barrier
	s_waitcnt lgkmcnt(0)
	v_mfma_f32_16x16x32_bf16 v[62:65], v[142:145], v[178:181], v[62:65]
	v_mfma_f32_16x16x32_bf16 v[54:57], v[154:157], v[178:181], v[54:57]
	v_mfma_f32_16x16x32_bf16 v[46:49], v[142:145], v[186:189], v[46:49]
	v_mfma_f32_16x16x32_bf16 v[38:41], v[154:157], v[186:189], v[38:41]
	v_mfma_f32_16x16x32_bf16 v[30:33], v[142:145], v[194:197], v[30:33]
	v_mfma_f32_16x16x32_bf16 v[22:25], v[154:157], v[194:197], v[22:25]
	v_mfma_f32_16x16x32_bf16 v[14:17], v[142:145], v[202:205], v[14:17]
	v_mfma_f32_16x16x32_bf16 v[6:9], v[154:157], v[202:205], v[6:9]
	v_mfma_f32_16x16x32_bf16 v[62:65], v[150:153], v[182:185], v[62:65]
	v_mfma_f32_16x16x32_bf16 v[54:57], v[158:161], v[182:185], v[54:57]
	v_mfma_f32_16x16x32_bf16 v[46:49], v[150:153], v[190:193], v[46:49]
	v_mfma_f32_16x16x32_bf16 v[38:41], v[158:161], v[190:193], v[38:41]
	v_mfma_f32_16x16x32_bf16 v[30:33], v[150:153], v[198:201], v[30:33]
	v_mfma_f32_16x16x32_bf16 v[22:25], v[158:161], v[198:201], v[22:25]
	v_mfma_f32_16x16x32_bf16 v[14:17], v[150:153], v[214:217], v[14:17]
	v_mfma_f32_16x16x32_bf16 v[6:9], v[158:161], v[214:217], v[6:9]
	v_mfma_f32_16x16x32_bf16 v[58:61], v[162:165], v[178:181], v[58:61]
	v_mfma_f32_16x16x32_bf16 v[50:53], v[170:173], v[178:181], v[50:53]
	v_mfma_f32_16x16x32_bf16 v[42:45], v[162:165], v[186:189], v[42:45]
	v_mfma_f32_16x16x32_bf16 v[34:37], v[170:173], v[186:189], v[34:37]
	v_mfma_f32_16x16x32_bf16 v[26:29], v[162:165], v[194:197], v[26:29]
	v_mfma_f32_16x16x32_bf16 v[18:21], v[170:173], v[194:197], v[18:21]
	v_mfma_f32_16x16x32_bf16 v[10:13], v[162:165], v[202:205], v[10:13]
	v_mfma_f32_16x16x32_bf16 v[2:5], v[170:173], v[202:205], v[2:5]
	v_mfma_f32_16x16x32_bf16 v[58:61], v[166:169], v[182:185], v[58:61]
	v_mfma_f32_16x16x32_bf16 v[50:53], v[174:177], v[182:185], v[50:53]
	v_mfma_f32_16x16x32_bf16 v[42:45], v[166:169], v[190:193], v[42:45]
	v_mfma_f32_16x16x32_bf16 v[34:37], v[174:177], v[190:193], v[34:37]
	v_mfma_f32_16x16x32_bf16 v[26:29], v[166:169], v[198:201], v[26:29]
	v_mfma_f32_16x16x32_bf16 v[18:21], v[174:177], v[198:201], v[18:21]
	v_mfma_f32_16x16x32_bf16 v[10:13], v[166:169], v[214:217], v[10:13]
	v_mfma_f32_16x16x32_bf16 v[2:5], v[174:177], v[214:217], v[2:5]
	s_barrier
	s_add_u32 s22, s22, 0x100
	s_addc_u32 s23, s23, 0
	s_add_u32 vcc_lo, vcc_lo, 0x100
	s_addc_u32 vcc_hi, vcc_hi, 0
	s_cmp_ge_i32 s88, s52
	s_mov_b32 s66, s88
	s_cbranch_scc1 .LBB0_288
.LBB0_287:
	s_add_i32 s88, s66, 2
	s_add_u32 s62, s22, 0x80
	s_addc_u32 s63, s23, 0
	s_add_i32 s89, 0, 0x10000
	s_cmp_eq_u32 s93, s66
	s_cselect_b32 s67, s3, s63
	s_cselect_b32 s66, s2, s62
	v_add_u32_e32 v149, s89, v146
	s_cselect_b32 s63, s21, vcc_hi
	s_cselect_b32 s62, s20, vcc_lo
	s_add_i32 s31, 0, 0x14000
	ds_read_b128 v[142:145], v149
	ds_read_b128 v[150:153], v149 offset:1024
	ds_read_b128 v[154:157], v149 offset:2048
	ds_read_b128 v[158:161], v149 offset:3072
	v_add_u32_e32 v149, s31, v146
	ds_read_b128 v[162:165], v149
	ds_read_b128 v[166:169], v149 offset:1024
	ds_read_b128 v[170:173], v149 offset:2048
	ds_read_b128 v[174:177], v149 offset:3072
	v_lshl_add_u64 v[218:219], s[22:23], 0, v[138:139]
	s_add_i32 m0, s77, 0xc000
	ds_read_b128 v[178:181], v148
	ds_read_b128 v[182:185], v148 offset:1024
	ds_read_b128 v[186:189], v148 offset:2048
	ds_read_b128 v[190:193], v148 offset:3072
	ds_read_b128 v[194:197], v148 offset:4096
	ds_read_b128 v[198:201], v148 offset:5120
	ds_read_b128 v[202:205], v148 offset:6144
	ds_read_b128 v[214:217], v148 offset:7168
	global_load_lds_dwordx4 v[218:219], off
	v_lshl_add_u64 v[218:219], s[22:23], 0, v[140:141]
	s_add_i32 m0, s77, 0xe000
	s_nop 0
	global_load_lds_dwordx4 v[218:219], off
	s_waitcnt vmcnt(8)
	s_waitcnt lgkmcnt(0)
	s_barrier
	s_waitcnt lgkmcnt(0)
	v_mfma_f32_16x16x32_bf16 v[122:125], v[142:145], v[178:181], v[122:125]
	v_mfma_f32_16x16x32_bf16 v[118:121], v[154:157], v[178:181], v[118:121]
	v_mfma_f32_16x16x32_bf16 v[110:113], v[142:145], v[186:189], v[110:113]
	v_mfma_f32_16x16x32_bf16 v[102:105], v[154:157], v[186:189], v[102:105]
	v_mfma_f32_16x16x32_bf16 v[94:97], v[142:145], v[194:197], v[94:97]
	v_mfma_f32_16x16x32_bf16 v[86:89], v[154:157], v[194:197], v[86:89]
	v_mfma_f32_16x16x32_bf16 v[78:81], v[142:145], v[202:205], v[78:81]
	v_mfma_f32_16x16x32_bf16 v[70:73], v[154:157], v[202:205], v[70:73]
	v_mfma_f32_16x16x32_bf16 v[122:125], v[150:153], v[182:185], v[122:125]
	v_mfma_f32_16x16x32_bf16 v[118:121], v[158:161], v[182:185], v[118:121]
	v_mfma_f32_16x16x32_bf16 v[110:113], v[150:153], v[190:193], v[110:113]
	v_mfma_f32_16x16x32_bf16 v[102:105], v[158:161], v[190:193], v[102:105]
	v_mfma_f32_16x16x32_bf16 v[94:97], v[150:153], v[198:201], v[94:97]
	v_mfma_f32_16x16x32_bf16 v[86:89], v[158:161], v[198:201], v[86:89]
	v_mfma_f32_16x16x32_bf16 v[78:81], v[150:153], v[214:217], v[78:81]
	v_mfma_f32_16x16x32_bf16 v[70:73], v[158:161], v[214:217], v[70:73]
	v_mfma_f32_16x16x32_bf16 v[126:129], v[162:165], v[178:181], v[126:129]
	v_mfma_f32_16x16x32_bf16 v[114:117], v[170:173], v[178:181], v[114:117]
	v_mfma_f32_16x16x32_bf16 v[106:109], v[162:165], v[186:189], v[106:109]
	v_mfma_f32_16x16x32_bf16 v[98:101], v[170:173], v[186:189], v[98:101]
	v_mfma_f32_16x16x32_bf16 v[90:93], v[162:165], v[194:197], v[90:93]
	v_mfma_f32_16x16x32_bf16 v[82:85], v[170:173], v[194:197], v[82:85]
	v_mfma_f32_16x16x32_bf16 v[74:77], v[162:165], v[202:205], v[74:77]
	v_mfma_f32_16x16x32_bf16 v[66:69], v[170:173], v[202:205], v[66:69]
	v_mfma_f32_16x16x32_bf16 v[126:129], v[166:169], v[182:185], v[126:129]
	v_mfma_f32_16x16x32_bf16 v[114:117], v[174:177], v[182:185], v[114:117]
	v_mfma_f32_16x16x32_bf16 v[106:109], v[166:169], v[190:193], v[106:109]
	v_mfma_f32_16x16x32_bf16 v[98:101], v[174:177], v[190:193], v[98:101]
	v_mfma_f32_16x16x32_bf16 v[90:93], v[166:169], v[198:201], v[90:93]
	v_mfma_f32_16x16x32_bf16 v[82:85], v[174:177], v[198:201], v[82:85]
	v_mfma_f32_16x16x32_bf16 v[74:77], v[166:169], v[214:217], v[74:77]
	v_mfma_f32_16x16x32_bf16 v[66:69], v[174:177], v[214:217], v[66:69]
	s_barrier
	s_add_i32 s89, s89, s74
	v_lshl_add_u64 v[218:219], s[62:63], 0, v[134:135]
	s_mov_b32 m0, s89
	ds_read_b128 v[178:181], v148 offset:16384
	ds_read_b128 v[182:185], v148 offset:17408
	ds_read_b128 v[186:189], v148 offset:18432
	ds_read_b128 v[190:193], v148 offset:19456
	ds_read_b128 v[194:197], v148 offset:20480
	ds_read_b128 v[198:201], v148 offset:21504
	ds_read_b128 v[202:205], v148 offset:22528
	ds_read_b128 v[214:217], v148 offset:23552
	global_load_lds_dwordx4 v[218:219], off
	s_add_i32 m0, s89, 0x2000
	v_lshl_add_u64 v[220:221], s[62:63], 0, v[130:131]
	s_add_u32 s62, s62, s8
	s_addc_u32 s63, s63, s9
	s_add_i32 s31, s31, s74
	global_load_lds_dwordx4 v[220:221], off
	v_lshl_add_u64 v[222:223], s[62:63], 0, v[134:135]
	s_mov_b32 m0, s31
	v_lshl_add_u64 v[224:225], s[62:63], 0, v[130:131]
	global_load_lds_dwordx4 v[222:223], off
	s_add_i32 m0, s31, 0x2000
	v_lshl_add_u64 v[226:227], s[66:67], 0, v[136:137]
	global_load_lds_dwordx4 v[224:225], off
	s_mov_b32 m0, s77
	v_lshl_add_u64 v[236:237], s[66:67], 0, v[132:133]
	global_load_lds_dwordx4 v[226:227], off
	s_mov_b32 m0, s78
	s_nop 0
	global_load_lds_dwordx4 v[236:237], off
	s_waitcnt vmcnt(8)
	s_waitcnt lgkmcnt(0)
	s_barrier
	s_waitcnt lgkmcnt(0)
	v_mfma_f32_16x16x32_bf16 v[62:65], v[142:145], v[178:181], v[62:65]
	v_mfma_f32_16x16x32_bf16 v[54:57], v[154:157], v[178:181], v[54:57]
	v_mfma_f32_16x16x32_bf16 v[46:49], v[142:145], v[186:189], v[46:49]
	v_mfma_f32_16x16x32_bf16 v[38:41], v[154:157], v[186:189], v[38:41]
	v_mfma_f32_16x16x32_bf16 v[30:33], v[142:145], v[194:197], v[30:33]
	v_mfma_f32_16x16x32_bf16 v[22:25], v[154:157], v[194:197], v[22:25]
	v_mfma_f32_16x16x32_bf16 v[14:17], v[142:145], v[202:205], v[14:17]
	v_mfma_f32_16x16x32_bf16 v[6:9], v[154:157], v[202:205], v[6:9]
	v_mfma_f32_16x16x32_bf16 v[62:65], v[150:153], v[182:185], v[62:65]
	v_mfma_f32_16x16x32_bf16 v[54:57], v[158:161], v[182:185], v[54:57]
	v_mfma_f32_16x16x32_bf16 v[46:49], v[150:153], v[190:193], v[46:49]
	v_mfma_f32_16x16x32_bf16 v[38:41], v[158:161], v[190:193], v[38:41]
	v_mfma_f32_16x16x32_bf16 v[30:33], v[150:153], v[198:201], v[30:33]
	v_mfma_f32_16x16x32_bf16 v[22:25], v[158:161], v[198:201], v[22:25]
	v_mfma_f32_16x16x32_bf16 v[14:17], v[150:153], v[214:217], v[14:17]
	v_mfma_f32_16x16x32_bf16 v[6:9], v[158:161], v[214:217], v[6:9]
	v_mfma_f32_16x16x32_bf16 v[58:61], v[162:165], v[178:181], v[58:61]
	v_mfma_f32_16x16x32_bf16 v[50:53], v[170:173], v[178:181], v[50:53]
	v_mfma_f32_16x16x32_bf16 v[42:45], v[162:165], v[186:189], v[42:45]
	v_mfma_f32_16x16x32_bf16 v[34:37], v[170:173], v[186:189], v[34:37]
	v_mfma_f32_16x16x32_bf16 v[26:29], v[162:165], v[194:197], v[26:29]
	v_mfma_f32_16x16x32_bf16 v[18:21], v[170:173], v[194:197], v[18:21]
	v_mfma_f32_16x16x32_bf16 v[10:13], v[162:165], v[202:205], v[10:13]
	v_mfma_f32_16x16x32_bf16 v[2:5], v[170:173], v[202:205], v[2:5]
	v_mfma_f32_16x16x32_bf16 v[58:61], v[166:169], v[182:185], v[58:61]
	v_mfma_f32_16x16x32_bf16 v[50:53], v[174:177], v[182:185], v[50:53]
	v_mfma_f32_16x16x32_bf16 v[42:45], v[166:169], v[190:193], v[42:45]
	v_mfma_f32_16x16x32_bf16 v[34:37], v[174:177], v[190:193], v[34:37]
	v_mfma_f32_16x16x32_bf16 v[26:29], v[166:169], v[198:201], v[26:29]
	v_mfma_f32_16x16x32_bf16 v[18:21], v[174:177], v[198:201], v[18:21]
	v_mfma_f32_16x16x32_bf16 v[10:13], v[166:169], v[214:217], v[10:13]
	v_mfma_f32_16x16x32_bf16 v[2:5], v[174:177], v[214:217], v[2:5]
	s_barrier
	s_add_i32 s31, 0, 0x18000
	v_add_u32_e32 v149, s31, v146
	s_add_i32 s89, 0, 0x1c000
	ds_read_b128 v[142:145], v149
	ds_read_b128 v[150:153], v149 offset:1024
	ds_read_b128 v[154:157], v149 offset:2048
	ds_read_b128 v[158:161], v149 offset:3072
	v_add_u32_e32 v149, s89, v146
	ds_read_b128 v[162:165], v149
	ds_read_b128 v[166:169], v149 offset:1024
	ds_read_b128 v[170:173], v149 offset:2048
	ds_read_b128 v[174:177], v149 offset:3072
	s_add_u32 s62, s66, s8
	s_addc_u32 s63, s67, s9
	s_mov_b32 m0, s79
	v_lshl_add_u64 v[238:239], s[62:63], 0, v[136:137]
	ds_read_b128 v[178:181], v148 offset:32768
	ds_read_b128 v[182:185], v148 offset:33792
	ds_read_b128 v[186:189], v148 offset:34816
	ds_read_b128 v[190:193], v148 offset:35840
	ds_read_b128 v[194:197], v148 offset:36864
	ds_read_b128 v[198:201], v148 offset:37888
	ds_read_b128 v[202:205], v148 offset:38912
	ds_read_b128 v[214:217], v148 offset:39936
	global_load_lds_dwordx4 v[238:239], off
	v_lshl_add_u64 v[238:239], s[62:63], 0, v[132:133]
	s_mov_b32 m0, s90
	s_nop 0
	global_load_lds_dwordx4 v[238:239], off
	s_waitcnt vmcnt(8)
	s_waitcnt lgkmcnt(0)
	s_barrier
	s_waitcnt lgkmcnt(0)
	v_mfma_f32_16x16x32_bf16 v[122:125], v[142:145], v[178:181], v[122:125]
	v_mfma_f32_16x16x32_bf16 v[118:121], v[154:157], v[178:181], v[118:121]
	v_mfma_f32_16x16x32_bf16 v[110:113], v[142:145], v[186:189], v[110:113]
	v_mfma_f32_16x16x32_bf16 v[102:105], v[154:157], v[186:189], v[102:105]
	v_mfma_f32_16x16x32_bf16 v[94:97], v[142:145], v[194:197], v[94:97]
	v_mfma_f32_16x16x32_bf16 v[86:89], v[154:157], v[194:197], v[86:89]
	v_mfma_f32_16x16x32_bf16 v[78:81], v[142:145], v[202:205], v[78:81]
	v_mfma_f32_16x16x32_bf16 v[70:73], v[154:157], v[202:205], v[70:73]
	v_mfma_f32_16x16x32_bf16 v[122:125], v[150:153], v[182:185], v[122:125]
	v_mfma_f32_16x16x32_bf16 v[118:121], v[158:161], v[182:185], v[118:121]
	v_mfma_f32_16x16x32_bf16 v[110:113], v[150:153], v[190:193], v[110:113]
	v_mfma_f32_16x16x32_bf16 v[102:105], v[158:161], v[190:193], v[102:105]
	v_mfma_f32_16x16x32_bf16 v[94:97], v[150:153], v[198:201], v[94:97]
	v_mfma_f32_16x16x32_bf16 v[86:89], v[158:161], v[198:201], v[86:89]
	v_mfma_f32_16x16x32_bf16 v[78:81], v[150:153], v[214:217], v[78:81]
	v_mfma_f32_16x16x32_bf16 v[70:73], v[158:161], v[214:217], v[70:73]
	v_mfma_f32_16x16x32_bf16 v[126:129], v[162:165], v[178:181], v[126:129]
	v_mfma_f32_16x16x32_bf16 v[114:117], v[170:173], v[178:181], v[114:117]
	v_mfma_f32_16x16x32_bf16 v[106:109], v[162:165], v[186:189], v[106:109]
	v_mfma_f32_16x16x32_bf16 v[98:101], v[170:173], v[186:189], v[98:101]
	v_mfma_f32_16x16x32_bf16 v[90:93], v[162:165], v[194:197], v[90:93]
	v_mfma_f32_16x16x32_bf16 v[82:85], v[170:173], v[194:197], v[82:85]
	v_mfma_f32_16x16x32_bf16 v[74:77], v[162:165], v[202:205], v[74:77]
	v_mfma_f32_16x16x32_bf16 v[66:69], v[170:173], v[202:205], v[66:69]
	v_mfma_f32_16x16x32_bf16 v[126:129], v[166:169], v[182:185], v[126:129]
	v_mfma_f32_16x16x32_bf16 v[114:117], v[174:177], v[182:185], v[114:117]
	v_mfma_f32_16x16x32_bf16 v[106:109], v[166:169], v[190:193], v[106:109]
	v_mfma_f32_16x16x32_bf16 v[98:101], v[174:177], v[190:193], v[98:101]
	v_mfma_f32_16x16x32_bf16 v[90:93], v[166:169], v[198:201], v[90:93]
	v_mfma_f32_16x16x32_bf16 v[82:85], v[174:177], v[198:201], v[82:85]
	v_mfma_f32_16x16x32_bf16 v[74:77], v[166:169], v[214:217], v[74:77]
	v_mfma_f32_16x16x32_bf16 v[66:69], v[174:177], v[214:217], v[66:69]
	s_barrier
	s_add_i32 s31, s31, s74
	v_lshl_add_u64 v[218:219], v[218:219], 0, s[60:61]
	s_mov_b32 m0, s31
	ds_read_b128 v[178:181], v148 offset:49152
	ds_read_b128 v[182:185], v148 offset:50176
	ds_read_b128 v[186:189], v148 offset:51200
	ds_read_b128 v[190:193], v148 offset:52224
	ds_read_b128 v[194:197], v148 offset:53248
	ds_read_b128 v[198:201], v148 offset:54272
	ds_read_b128 v[202:205], v148 offset:55296
	ds_read_b128 v[214:217], v148 offset:56320
	global_load_lds_dwordx4 v[218:219], off
	v_lshl_add_u64 v[218:219], v[220:221], 0, s[60:61]
	s_add_i32 m0, s31, 0x2000
	s_add_i32 s31, s89, s74
	global_load_lds_dwordx4 v[218:219], off
	v_lshl_add_u64 v[218:219], v[222:223], 0, s[60:61]
	s_mov_b32 m0, s31
	s_nop 0
	global_load_lds_dwordx4 v[218:219], off
	v_lshl_add_u64 v[218:219], v[224:225], 0, s[60:61]
	s_add_i32 m0, s31, 0x2000
	s_nop 0
	global_load_lds_dwordx4 v[218:219], off
	v_lshl_add_u64 v[218:219], v[226:227], 0, s[60:61]
	s_mov_b32 m0, s91
	s_nop 0
	global_load_lds_dwordx4 v[218:219], off
	v_lshl_add_u64 v[218:219], v[236:237], 0, s[60:61]
	s_mov_b32 m0, s92
	s_nop 0
	global_load_lds_dwordx4 v[218:219], off
	s_waitcnt vmcnt(8)
	s_waitcnt lgkmcnt(0)
	s_barrier
	s_waitcnt lgkmcnt(0)
	v_mfma_f32_16x16x32_bf16 v[62:65], v[142:145], v[178:181], v[62:65]
	v_mfma_f32_16x16x32_bf16 v[54:57], v[154:157], v[178:181], v[54:57]
	v_mfma_f32_16x16x32_bf16 v[46:49], v[142:145], v[186:189], v[46:49]
	v_mfma_f32_16x16x32_bf16 v[38:41], v[154:157], v[186:189], v[38:41]
	v_mfma_f32_16x16x32_bf16 v[30:33], v[142:145], v[194:197], v[30:33]
	v_mfma_f32_16x16x32_bf16 v[22:25], v[154:157], v[194:197], v[22:25]
	v_mfma_f32_16x16x32_bf16 v[14:17], v[142:145], v[202:205], v[14:17]
	v_mfma_f32_16x16x32_bf16 v[6:9], v[154:157], v[202:205], v[6:9]
	v_mfma_f32_16x16x32_bf16 v[62:65], v[150:153], v[182:185], v[62:65]
	v_mfma_f32_16x16x32_bf16 v[54:57], v[158:161], v[182:185], v[54:57]
	v_mfma_f32_16x16x32_bf16 v[46:49], v[150:153], v[190:193], v[46:49]
	v_mfma_f32_16x16x32_bf16 v[38:41], v[158:161], v[190:193], v[38:41]
	v_mfma_f32_16x16x32_bf16 v[30:33], v[150:153], v[198:201], v[30:33]
	v_mfma_f32_16x16x32_bf16 v[22:25], v[158:161], v[198:201], v[22:25]
	v_mfma_f32_16x16x32_bf16 v[14:17], v[150:153], v[214:217], v[14:17]
	v_mfma_f32_16x16x32_bf16 v[6:9], v[158:161], v[214:217], v[6:9]
	v_mfma_f32_16x16x32_bf16 v[58:61], v[162:165], v[178:181], v[58:61]
	v_mfma_f32_16x16x32_bf16 v[50:53], v[170:173], v[178:181], v[50:53]
	v_mfma_f32_16x16x32_bf16 v[42:45], v[162:165], v[186:189], v[42:45]
	v_mfma_f32_16x16x32_bf16 v[34:37], v[170:173], v[186:189], v[34:37]
	v_mfma_f32_16x16x32_bf16 v[26:29], v[162:165], v[194:197], v[26:29]
	v_mfma_f32_16x16x32_bf16 v[18:21], v[170:173], v[194:197], v[18:21]
	v_mfma_f32_16x16x32_bf16 v[10:13], v[162:165], v[202:205], v[10:13]
	v_mfma_f32_16x16x32_bf16 v[2:5], v[170:173], v[202:205], v[2:5]
	v_mfma_f32_16x16x32_bf16 v[58:61], v[166:169], v[182:185], v[58:61]
	v_mfma_f32_16x16x32_bf16 v[50:53], v[174:177], v[182:185], v[50:53]
	v_mfma_f32_16x16x32_bf16 v[42:45], v[166:169], v[190:193], v[42:45]
	v_mfma_f32_16x16x32_bf16 v[34:37], v[174:177], v[190:193], v[34:37]
	v_mfma_f32_16x16x32_bf16 v[26:29], v[166:169], v[198:201], v[26:29]
	v_mfma_f32_16x16x32_bf16 v[18:21], v[174:177], v[198:201], v[18:21]
	v_mfma_f32_16x16x32_bf16 v[10:13], v[166:169], v[214:217], v[10:13]
	v_mfma_f32_16x16x32_bf16 v[2:5], v[174:177], v[214:217], v[2:5]
	s_barrier
	s_add_u32 s22, s22, 0x100
	s_addc_u32 s23, s23, 0
	s_add_u32 vcc_lo, vcc_lo, 0x100
	s_addc_u32 vcc_hi, vcc_hi, 0
	s_cmp_ge_i32 s88, s52
	s_mov_b32 s66, s88
	s_cbranch_scc0 .LBB0_287

.Lzgo_2:
	s_add_u32 s20, s20, 0x80
	s_addc_u32 s21, s21, 0
	s_add_u32 vcc_lo, s22, 0x100
	s_addc_u32 vcc_hi, s23, 0
	s_mov_b32 s22, 0
	s_add_i32 s88, s22, 2
	s_add_u32 s31, s20, 0x80
	s_addc_u32 s23, s21, 0
	s_add_i32 s89, 0, 0x10000
	s_cmp_eq_u32 s90, s22
	s_cselect_b32 s23, s3, s23
	s_cselect_b32 s22, s2, s31
	v_add_u32_e32 v146, s89, v148
	s_cselect_b32 s63, s19, vcc_hi
	s_cselect_b32 s62, s18, vcc_lo
	s_add_i32 s31, 0, 0x14000
	ds_read_b128 v[138:141], v146
	ds_read_b128 v[142:145], v146 offset:1024
	ds_read_b128 v[152:155], v146 offset:2048
	ds_read_b128 v[156:159], v146 offset:3072
	v_add_u32_e32 v146, s31, v148
	ds_read_b128 v[160:163], v146
	ds_read_b128 v[164:167], v146 offset:1024
	ds_read_b128 v[168:171], v146 offset:2048
	ds_read_b128 v[172:175], v146 offset:3072
	v_lshl_add_u64 v[146:147], s[20:21], 0, v[134:135]
	s_add_i32 m0, s67, 0xc000
	ds_read_b128 v[176:179], v150
	ds_read_b128 v[180:183], v150 offset:1024
	ds_read_b128 v[184:187], v150 offset:2048
	ds_read_b128 v[188:191], v150 offset:3072
	ds_read_b128 v[192:195], v150 offset:4096
	ds_read_b128 v[196:199], v150 offset:5120
	ds_read_b128 v[200:203], v150 offset:6144
	ds_read_b128 v[214:217], v150 offset:7168
	global_load_lds_dwordx4 v[146:147], off
	v_lshl_add_u64 v[146:147], s[20:21], 0, v[136:137]
	s_add_i32 m0, s67, 0xe000
	s_nop 0
	global_load_lds_dwordx4 v[146:147], off
	s_waitcnt vmcnt(8)
	s_waitcnt lgkmcnt(0)
	s_barrier
	s_waitcnt lgkmcnt(0)
	v_mfma_f32_16x16x32_bf16 v[126:129], v[138:141], v[176:179], 0
	v_mfma_f32_16x16x32_bf16 v[94:97], v[152:155], v[176:179], 0
	v_mfma_f32_16x16x32_bf16 v[122:125], v[138:141], v[184:187], 0
	v_mfma_f32_16x16x32_bf16 v[90:93], v[152:155], v[184:187], 0
	v_mfma_f32_16x16x32_bf16 v[118:121], v[138:141], v[192:195], 0
	v_mfma_f32_16x16x32_bf16 v[86:89], v[152:155], v[192:195], 0
	v_mfma_f32_16x16x32_bf16 v[114:117], v[138:141], v[200:203], 0
	v_mfma_f32_16x16x32_bf16 v[82:85], v[152:155], v[200:203], 0
	v_mfma_f32_16x16x32_bf16 v[126:129], v[142:145], v[180:183], v[126:129]
	v_mfma_f32_16x16x32_bf16 v[94:97], v[156:159], v[180:183], v[94:97]
	v_mfma_f32_16x16x32_bf16 v[122:125], v[142:145], v[188:191], v[122:125]
	v_mfma_f32_16x16x32_bf16 v[90:93], v[156:159], v[188:191], v[90:93]
	v_mfma_f32_16x16x32_bf16 v[118:121], v[142:145], v[196:199], v[118:121]
	v_mfma_f32_16x16x32_bf16 v[86:89], v[156:159], v[196:199], v[86:89]
	v_mfma_f32_16x16x32_bf16 v[114:117], v[142:145], v[214:217], v[114:117]
	v_mfma_f32_16x16x32_bf16 v[82:85], v[156:159], v[214:217], v[82:85]
	v_mfma_f32_16x16x32_bf16 v[62:65], v[160:163], v[176:179], 0
	v_mfma_f32_16x16x32_bf16 v[30:33], v[168:171], v[176:179], 0
	v_mfma_f32_16x16x32_bf16 v[58:61], v[160:163], v[184:187], 0
	v_mfma_f32_16x16x32_bf16 v[26:29], v[168:171], v[184:187], 0
	v_mfma_f32_16x16x32_bf16 v[54:57], v[160:163], v[192:195], 0
	v_mfma_f32_16x16x32_bf16 v[22:25], v[168:171], v[192:195], 0
	v_mfma_f32_16x16x32_bf16 v[50:53], v[160:163], v[200:203], 0
	v_mfma_f32_16x16x32_bf16 v[18:21], v[168:171], v[200:203], 0
	v_mfma_f32_16x16x32_bf16 v[62:65], v[164:167], v[180:183], v[62:65]
	v_mfma_f32_16x16x32_bf16 v[30:33], v[172:175], v[180:183], v[30:33]
	v_mfma_f32_16x16x32_bf16 v[58:61], v[164:167], v[188:191], v[58:61]
	v_mfma_f32_16x16x32_bf16 v[26:29], v[172:175], v[188:191], v[26:29]
	v_mfma_f32_16x16x32_bf16 v[54:57], v[164:167], v[196:199], v[54:57]
	v_mfma_f32_16x16x32_bf16 v[22:25], v[172:175], v[196:199], v[22:25]
	v_mfma_f32_16x16x32_bf16 v[50:53], v[164:167], v[214:217], v[50:53]
	v_mfma_f32_16x16x32_bf16 v[18:21], v[172:175], v[214:217], v[18:21]
	s_barrier
	s_add_i32 s89, s89, s56
	v_lshl_add_u64 v[146:147], s[62:63], 0, v[132:133]
	s_mov_b32 m0, s89
	ds_read_b128 v[176:179], v150 offset:16384
	ds_read_b128 v[180:183], v150 offset:17408
	ds_read_b128 v[184:187], v150 offset:18432
	ds_read_b128 v[188:191], v150 offset:19456
	ds_read_b128 v[192:195], v150 offset:20480
	ds_read_b128 v[196:199], v150 offset:21504
	ds_read_b128 v[200:203], v150 offset:22528
	ds_read_b128 v[214:217], v150 offset:23552
	global_load_lds_dwordx4 v[146:147], off
	s_add_i32 m0, s89, 0x2000
	v_lshl_add_u64 v[204:205], s[62:63], 0, v[130:131]
	s_add_u32 s62, s62, s8
	s_addc_u32 s63, s63, s9
	s_add_i32 s31, s31, s56
	global_load_lds_dwordx4 v[204:205], off
	v_lshl_add_u64 v[218:219], s[62:63], 0, v[132:133]
	s_mov_b32 m0, s31
	v_lshl_add_u64 v[220:221], s[62:63], 0, v[130:131]
	global_load_lds_dwordx4 v[218:219], off
	s_add_i32 m0, s31, 0x2000
	v_lshl_add_u64 v[222:223], s[22:23], 0, v[132:133]
	global_load_lds_dwordx4 v[220:221], off
	s_mov_b32 m0, s67
	v_lshl_add_u64 v[224:225], s[22:23], 0, v[130:131]
	global_load_lds_dwordx4 v[222:223], off
	s_mov_b32 m0, s72
	s_nop 0
	global_load_lds_dwordx4 v[224:225], off
	s_waitcnt vmcnt(8)
	s_waitcnt lgkmcnt(0)
	s_barrier
	s_waitcnt lgkmcnt(0)
	v_mfma_f32_16x16x32_bf16 v[110:113], v[138:141], v[176:179], 0
	v_mfma_f32_16x16x32_bf16 v[78:81], v[152:155], v[176:179], 0
	v_mfma_f32_16x16x32_bf16 v[106:109], v[138:141], v[184:187], 0
	v_mfma_f32_16x16x32_bf16 v[74:77], v[152:155], v[184:187], 0
	v_mfma_f32_16x16x32_bf16 v[102:105], v[138:141], v[192:195], 0
	v_mfma_f32_16x16x32_bf16 v[70:73], v[152:155], v[192:195], 0
	v_mfma_f32_16x16x32_bf16 v[98:101], v[138:141], v[200:203], 0
	v_mfma_f32_16x16x32_bf16 v[66:69], v[152:155], v[200:203], 0
	v_mfma_f32_16x16x32_bf16 v[110:113], v[142:145], v[180:183], v[110:113]
	v_mfma_f32_16x16x32_bf16 v[78:81], v[156:159], v[180:183], v[78:81]
	v_mfma_f32_16x16x32_bf16 v[106:109], v[142:145], v[188:191], v[106:109]
	v_mfma_f32_16x16x32_bf16 v[74:77], v[156:159], v[188:191], v[74:77]
	v_mfma_f32_16x16x32_bf16 v[102:105], v[142:145], v[196:199], v[102:105]
	v_mfma_f32_16x16x32_bf16 v[70:73], v[156:159], v[196:199], v[70:73]
	v_mfma_f32_16x16x32_bf16 v[98:101], v[142:145], v[214:217], v[98:101]
	v_mfma_f32_16x16x32_bf16 v[66:69], v[156:159], v[214:217], v[66:69]
	v_mfma_f32_16x16x32_bf16 v[46:49], v[160:163], v[176:179], 0
	v_mfma_f32_16x16x32_bf16 v[14:17], v[168:171], v[176:179], 0
	v_mfma_f32_16x16x32_bf16 v[42:45], v[160:163], v[184:187], 0
	v_mfma_f32_16x16x32_bf16 v[10:13], v[168:171], v[184:187], 0
	v_mfma_f32_16x16x32_bf16 v[38:41], v[160:163], v[192:195], 0
	v_mfma_f32_16x16x32_bf16 v[6:9], v[168:171], v[192:195], 0
	v_mfma_f32_16x16x32_bf16 v[34:37], v[160:163], v[200:203], 0
	v_mfma_f32_16x16x32_bf16 v[2:5], v[168:171], v[200:203], 0
	v_mfma_f32_16x16x32_bf16 v[46:49], v[164:167], v[180:183], v[46:49]
	v_mfma_f32_16x16x32_bf16 v[14:17], v[172:175], v[180:183], v[14:17]
	v_mfma_f32_16x16x32_bf16 v[42:45], v[164:167], v[188:191], v[42:45]
	v_mfma_f32_16x16x32_bf16 v[10:13], v[172:175], v[188:191], v[10:13]
	v_mfma_f32_16x16x32_bf16 v[38:41], v[164:167], v[196:199], v[38:41]
	v_mfma_f32_16x16x32_bf16 v[6:9], v[172:175], v[196:199], v[6:9]
	v_mfma_f32_16x16x32_bf16 v[34:37], v[164:167], v[214:217], v[34:37]
	v_mfma_f32_16x16x32_bf16 v[2:5], v[172:175], v[214:217], v[2:5]
	s_barrier
	s_add_i32 s31, 0, 0x18000
	v_add_u32_e32 v151, s31, v148
	s_add_i32 s62, 0, 0x1c000
	ds_read_b128 v[138:141], v151
	ds_read_b128 v[142:145], v151 offset:1024
	ds_read_b128 v[152:155], v151 offset:2048
	ds_read_b128 v[156:159], v151 offset:3072
	v_add_u32_e32 v151, s62, v148
	ds_read_b128 v[160:163], v151
	ds_read_b128 v[164:167], v151 offset:1024
	ds_read_b128 v[168:171], v151 offset:2048
	ds_read_b128 v[172:175], v151 offset:3072
	s_add_u32 s22, s22, s8
	s_addc_u32 s23, s23, s9
	s_mov_b32 m0, s73
	v_lshl_add_u64 v[226:227], s[22:23], 0, v[132:133]
	ds_read_b128 v[176:179], v150 offset:32768
	ds_read_b128 v[180:183], v150 offset:33792
	ds_read_b128 v[184:187], v150 offset:34816
	ds_read_b128 v[188:191], v150 offset:35840
	ds_read_b128 v[192:195], v150 offset:36864
	ds_read_b128 v[196:199], v150 offset:37888
	ds_read_b128 v[200:203], v150 offset:38912
	ds_read_b128 v[214:217], v150 offset:39936
	global_load_lds_dwordx4 v[226:227], off
	v_lshl_add_u64 v[226:227], s[22:23], 0, v[130:131]
	s_mov_b32 m0, s74
	s_nop 0
	global_load_lds_dwordx4 v[226:227], off
	s_waitcnt vmcnt(8)
	s_waitcnt lgkmcnt(0)
	s_barrier
	s_waitcnt lgkmcnt(0)
	v_mfma_f32_16x16x32_bf16 v[126:129], v[138:141], v[176:179], v[126:129]
	v_mfma_f32_16x16x32_bf16 v[94:97], v[152:155], v[176:179], v[94:97]
	v_mfma_f32_16x16x32_bf16 v[122:125], v[138:141], v[184:187], v[122:125]
	v_mfma_f32_16x16x32_bf16 v[90:93], v[152:155], v[184:187], v[90:93]
	v_mfma_f32_16x16x32_bf16 v[118:121], v[138:141], v[192:195], v[118:121]
	v_mfma_f32_16x16x32_bf16 v[86:89], v[152:155], v[192:195], v[86:89]
	v_mfma_f32_16x16x32_bf16 v[114:117], v[138:141], v[200:203], v[114:117]
	v_mfma_f32_16x16x32_bf16 v[82:85], v[152:155], v[200:203], v[82:85]
	v_mfma_f32_16x16x32_bf16 v[126:129], v[142:145], v[180:183], v[126:129]
	v_mfma_f32_16x16x32_bf16 v[94:97], v[156:159], v[180:183], v[94:97]
	v_mfma_f32_16x16x32_bf16 v[122:125], v[142:145], v[188:191], v[122:125]
	v_mfma_f32_16x16x32_bf16 v[90:93], v[156:159], v[188:191], v[90:93]
	v_mfma_f32_16x16x32_bf16 v[118:121], v[142:145], v[196:199], v[118:121]
	v_mfma_f32_16x16x32_bf16 v[86:89], v[156:159], v[196:199], v[86:89]
	v_mfma_f32_16x16x32_bf16 v[114:117], v[142:145], v[214:217], v[114:117]
	v_mfma_f32_16x16x32_bf16 v[82:85], v[156:159], v[214:217], v[82:85]
	v_mfma_f32_16x16x32_bf16 v[62:65], v[160:163], v[176:179], v[62:65]
	v_mfma_f32_16x16x32_bf16 v[30:33], v[168:171], v[176:179], v[30:33]
	v_mfma_f32_16x16x32_bf16 v[58:61], v[160:163], v[184:187], v[58:61]
	v_mfma_f32_16x16x32_bf16 v[26:29], v[168:171], v[184:187], v[26:29]
	v_mfma_f32_16x16x32_bf16 v[54:57], v[160:163], v[192:195], v[54:57]
	v_mfma_f32_16x16x32_bf16 v[22:25], v[168:171], v[192:195], v[22:25]
	v_mfma_f32_16x16x32_bf16 v[50:53], v[160:163], v[200:203], v[50:53]
	v_mfma_f32_16x16x32_bf16 v[18:21], v[168:171], v[200:203], v[18:21]
	v_mfma_f32_16x16x32_bf16 v[62:65], v[164:167], v[180:183], v[62:65]
	v_mfma_f32_16x16x32_bf16 v[30:33], v[172:175], v[180:183], v[30:33]
	v_mfma_f32_16x16x32_bf16 v[58:61], v[164:167], v[188:191], v[58:61]
	v_mfma_f32_16x16x32_bf16 v[26:29], v[172:175], v[188:191], v[26:29]
	v_mfma_f32_16x16x32_bf16 v[54:57], v[164:167], v[196:199], v[54:57]
	v_mfma_f32_16x16x32_bf16 v[22:25], v[172:175], v[196:199], v[22:25]
	v_mfma_f32_16x16x32_bf16 v[50:53], v[164:167], v[214:217], v[50:53]
	v_mfma_f32_16x16x32_bf16 v[18:21], v[172:175], v[214:217], v[18:21]
	s_barrier
	s_add_i32 s22, s31, s56
	v_lshl_add_u64 v[146:147], v[146:147], 0, s[60:61]
	s_mov_b32 m0, s22
	ds_read_b128 v[176:179], v150 offset:49152
	ds_read_b128 v[180:183], v150 offset:50176
	ds_read_b128 v[184:187], v150 offset:51200
	ds_read_b128 v[188:191], v150 offset:52224
	ds_read_b128 v[192:195], v150 offset:53248
	ds_read_b128 v[196:199], v150 offset:54272
	ds_read_b128 v[200:203], v150 offset:55296
	ds_read_b128 v[214:217], v150 offset:56320
	global_load_lds_dwordx4 v[146:147], off
	v_lshl_add_u64 v[146:147], v[204:205], 0, s[60:61]
	s_add_i32 m0, s22, 0x2000
	s_add_i32 s22, s62, s56
	global_load_lds_dwordx4 v[146:147], off
	v_lshl_add_u64 v[146:147], v[218:219], 0, s[60:61]
	s_mov_b32 m0, s22
	s_nop 0
	global_load_lds_dwordx4 v[146:147], off
	v_lshl_add_u64 v[146:147], v[220:221], 0, s[60:61]
	s_add_i32 m0, s22, 0x2000
	s_nop 0
	global_load_lds_dwordx4 v[146:147], off
	v_lshl_add_u64 v[146:147], v[222:223], 0, s[60:61]
	s_mov_b32 m0, s77
	s_nop 0
	global_load_lds_dwordx4 v[146:147], off
	v_lshl_add_u64 v[146:147], v[224:225], 0, s[60:61]
	s_mov_b32 m0, s78
	s_nop 0
	global_load_lds_dwordx4 v[146:147], off
	s_waitcnt vmcnt(8)
	s_waitcnt lgkmcnt(0)
	s_barrier
	s_waitcnt lgkmcnt(0)
	v_mfma_f32_16x16x32_bf16 v[110:113], v[138:141], v[176:179], v[110:113]
	v_mfma_f32_16x16x32_bf16 v[78:81], v[152:155], v[176:179], v[78:81]
	v_mfma_f32_16x16x32_bf16 v[106:109], v[138:141], v[184:187], v[106:109]
	v_mfma_f32_16x16x32_bf16 v[74:77], v[152:155], v[184:187], v[74:77]
	v_mfma_f32_16x16x32_bf16 v[102:105], v[138:141], v[192:195], v[102:105]
	v_mfma_f32_16x16x32_bf16 v[70:73], v[152:155], v[192:195], v[70:73]
	v_mfma_f32_16x16x32_bf16 v[98:101], v[138:141], v[200:203], v[98:101]
	v_mfma_f32_16x16x32_bf16 v[66:69], v[152:155], v[200:203], v[66:69]
	v_mfma_f32_16x16x32_bf16 v[110:113], v[142:145], v[180:183], v[110:113]
	v_mfma_f32_16x16x32_bf16 v[78:81], v[156:159], v[180:183], v[78:81]
	v_mfma_f32_16x16x32_bf16 v[106:109], v[142:145], v[188:191], v[106:109]
	v_mfma_f32_16x16x32_bf16 v[74:77], v[156:159], v[188:191], v[74:77]
	v_mfma_f32_16x16x32_bf16 v[102:105], v[142:145], v[196:199], v[102:105]
	v_mfma_f32_16x16x32_bf16 v[70:73], v[156:159], v[196:199], v[70:73]
	v_mfma_f32_16x16x32_bf16 v[98:101], v[142:145], v[214:217], v[98:101]
	v_mfma_f32_16x16x32_bf16 v[66:69], v[156:159], v[214:217], v[66:69]
	v_mfma_f32_16x16x32_bf16 v[46:49], v[160:163], v[176:179], v[46:49]
	v_mfma_f32_16x16x32_bf16 v[14:17], v[168:171], v[176:179], v[14:17]
	v_mfma_f32_16x16x32_bf16 v[42:45], v[160:163], v[184:187], v[42:45]
	v_mfma_f32_16x16x32_bf16 v[10:13], v[168:171], v[184:187], v[10:13]
	v_mfma_f32_16x16x32_bf16 v[38:41], v[160:163], v[192:195], v[38:41]
	v_mfma_f32_16x16x32_bf16 v[6:9], v[168:171], v[192:195], v[6:9]
	v_mfma_f32_16x16x32_bf16 v[34:37], v[160:163], v[200:203], v[34:37]
	v_mfma_f32_16x16x32_bf16 v[2:5], v[168:171], v[200:203], v[2:5]
	v_mfma_f32_16x16x32_bf16 v[46:49], v[164:167], v[180:183], v[46:49]
	v_mfma_f32_16x16x32_bf16 v[14:17], v[172:175], v[180:183], v[14:17]
	v_mfma_f32_16x16x32_bf16 v[42:45], v[164:167], v[188:191], v[42:45]
	v_mfma_f32_16x16x32_bf16 v[10:13], v[172:175], v[188:191], v[10:13]
	v_mfma_f32_16x16x32_bf16 v[38:41], v[164:167], v[196:199], v[38:41]
	v_mfma_f32_16x16x32_bf16 v[6:9], v[172:175], v[196:199], v[6:9]
	v_mfma_f32_16x16x32_bf16 v[34:37], v[164:167], v[214:217], v[34:37]
	v_mfma_f32_16x16x32_bf16 v[2:5], v[172:175], v[214:217], v[2:5]
	s_barrier
	s_add_u32 s20, s20, 0x100
	s_addc_u32 s21, s21, 0
	s_add_u32 vcc_lo, vcc_lo, 0x100
	s_addc_u32 vcc_hi, vcc_hi, 0
	s_cmp_ge_i32 s88, s79
	s_mov_b32 s22, s88
	s_cbranch_scc1 .LBB0_361
.LBB0_360:
	s_add_i32 s88, s22, 2
	s_add_u32 s31, s20, 0x80
	s_addc_u32 s23, s21, 0
	s_add_i32 s89, 0, 0x10000
	s_cmp_eq_u32 s90, s22
	s_cselect_b32 s23, s3, s23
	s_cselect_b32 s22, s2, s31
	v_add_u32_e32 v146, s89, v148
	s_cselect_b32 s63, s19, vcc_hi
	s_cselect_b32 s62, s18, vcc_lo
	s_add_i32 s31, 0, 0x14000
	ds_read_b128 v[138:141], v146
	ds_read_b128 v[142:145], v146 offset:1024
	ds_read_b128 v[152:155], v146 offset:2048
	ds_read_b128 v[156:159], v146 offset:3072
	v_add_u32_e32 v146, s31, v148
	ds_read_b128 v[160:163], v146
	ds_read_b128 v[164:167], v146 offset:1024
	ds_read_b128 v[168:171], v146 offset:2048
	ds_read_b128 v[172:175], v146 offset:3072
	v_lshl_add_u64 v[146:147], s[20:21], 0, v[134:135]
	s_add_i32 m0, s67, 0xc000
	ds_read_b128 v[176:179], v150
	ds_read_b128 v[180:183], v150 offset:1024
	ds_read_b128 v[184:187], v150 offset:2048
	ds_read_b128 v[188:191], v150 offset:3072
	ds_read_b128 v[192:195], v150 offset:4096
	ds_read_b128 v[196:199], v150 offset:5120
	ds_read_b128 v[200:203], v150 offset:6144
	ds_read_b128 v[214:217], v150 offset:7168
	global_load_lds_dwordx4 v[146:147], off
	v_lshl_add_u64 v[146:147], s[20:21], 0, v[136:137]
	s_add_i32 m0, s67, 0xe000
	s_nop 0
	global_load_lds_dwordx4 v[146:147], off
	s_waitcnt vmcnt(8)
	s_waitcnt lgkmcnt(0)
	s_barrier
	s_waitcnt lgkmcnt(0)
	v_mfma_f32_16x16x32_bf16 v[126:129], v[138:141], v[176:179], v[126:129]
	v_mfma_f32_16x16x32_bf16 v[94:97], v[152:155], v[176:179], v[94:97]
	v_mfma_f32_16x16x32_bf16 v[122:125], v[138:141], v[184:187], v[122:125]
	v_mfma_f32_16x16x32_bf16 v[90:93], v[152:155], v[184:187], v[90:93]
	v_mfma_f32_16x16x32_bf16 v[118:121], v[138:141], v[192:195], v[118:121]
	v_mfma_f32_16x16x32_bf16 v[86:89], v[152:155], v[192:195], v[86:89]
	v_mfma_f32_16x16x32_bf16 v[114:117], v[138:141], v[200:203], v[114:117]
	v_mfma_f32_16x16x32_bf16 v[82:85], v[152:155], v[200:203], v[82:85]
	v_mfma_f32_16x16x32_bf16 v[126:129], v[142:145], v[180:183], v[126:129]
	v_mfma_f32_16x16x32_bf16 v[94:97], v[156:159], v[180:183], v[94:97]
	v_mfma_f32_16x16x32_bf16 v[122:125], v[142:145], v[188:191], v[122:125]
	v_mfma_f32_16x16x32_bf16 v[90:93], v[156:159], v[188:191], v[90:93]
	v_mfma_f32_16x16x32_bf16 v[118:121], v[142:145], v[196:199], v[118:121]
	v_mfma_f32_16x16x32_bf16 v[86:89], v[156:159], v[196:199], v[86:89]
	v_mfma_f32_16x16x32_bf16 v[114:117], v[142:145], v[214:217], v[114:117]
	v_mfma_f32_16x16x32_bf16 v[82:85], v[156:159], v[214:217], v[82:85]
	v_mfma_f32_16x16x32_bf16 v[62:65], v[160:163], v[176:179], v[62:65]
	v_mfma_f32_16x16x32_bf16 v[30:33], v[168:171], v[176:179], v[30:33]
	v_mfma_f32_16x16x32_bf16 v[58:61], v[160:163], v[184:187], v[58:61]
	v_mfma_f32_16x16x32_bf16 v[26:29], v[168:171], v[184:187], v[26:29]
	v_mfma_f32_16x16x32_bf16 v[54:57], v[160:163], v[192:195], v[54:57]
	v_mfma_f32_16x16x32_bf16 v[22:25], v[168:171], v[192:195], v[22:25]
	v_mfma_f32_16x16x32_bf16 v[50:53], v[160:163], v[200:203], v[50:53]
	v_mfma_f32_16x16x32_bf16 v[18:21], v[168:171], v[200:203], v[18:21]
	v_mfma_f32_16x16x32_bf16 v[62:65], v[164:167], v[180:183], v[62:65]
	v_mfma_f32_16x16x32_bf16 v[30:33], v[172:175], v[180:183], v[30:33]
	v_mfma_f32_16x16x32_bf16 v[58:61], v[164:167], v[188:191], v[58:61]
	v_mfma_f32_16x16x32_bf16 v[26:29], v[172:175], v[188:191], v[26:29]
	v_mfma_f32_16x16x32_bf16 v[54:57], v[164:167], v[196:199], v[54:57]
	v_mfma_f32_16x16x32_bf16 v[22:25], v[172:175], v[196:199], v[22:25]
	v_mfma_f32_16x16x32_bf16 v[50:53], v[164:167], v[214:217], v[50:53]
	v_mfma_f32_16x16x32_bf16 v[18:21], v[172:175], v[214:217], v[18:21]
	s_barrier
	s_add_i32 s89, s89, s56
	v_lshl_add_u64 v[146:147], s[62:63], 0, v[132:133]
	s_mov_b32 m0, s89
	ds_read_b128 v[176:179], v150 offset:16384
	ds_read_b128 v[180:183], v150 offset:17408
	ds_read_b128 v[184:187], v150 offset:18432
	ds_read_b128 v[188:191], v150 offset:19456
	ds_read_b128 v[192:195], v150 offset:20480
	ds_read_b128 v[196:199], v150 offset:21504
	ds_read_b128 v[200:203], v150 offset:22528
	ds_read_b128 v[214:217], v150 offset:23552
	global_load_lds_dwordx4 v[146:147], off
	s_add_i32 m0, s89, 0x2000
	v_lshl_add_u64 v[204:205], s[62:63], 0, v[130:131]
	s_add_u32 s62, s62, s8
	s_addc_u32 s63, s63, s9
	s_add_i32 s31, s31, s56
	global_load_lds_dwordx4 v[204:205], off
	v_lshl_add_u64 v[218:219], s[62:63], 0, v[132:133]
	s_mov_b32 m0, s31
	v_lshl_add_u64 v[220:221], s[62:63], 0, v[130:131]
	global_load_lds_dwordx4 v[218:219], off
	s_add_i32 m0, s31, 0x2000
	v_lshl_add_u64 v[222:223], s[22:23], 0, v[132:133]
	global_load_lds_dwordx4 v[220:221], off
	s_mov_b32 m0, s67
	v_lshl_add_u64 v[224:225], s[22:23], 0, v[130:131]
	global_load_lds_dwordx4 v[222:223], off
	s_mov_b32 m0, s72
	s_nop 0
	global_load_lds_dwordx4 v[224:225], off
	s_waitcnt vmcnt(8)
	s_waitcnt lgkmcnt(0)
	s_barrier
	s_waitcnt lgkmcnt(0)
	v_mfma_f32_16x16x32_bf16 v[110:113], v[138:141], v[176:179], v[110:113]
	v_mfma_f32_16x16x32_bf16 v[78:81], v[152:155], v[176:179], v[78:81]
	v_mfma_f32_16x16x32_bf16 v[106:109], v[138:141], v[184:187], v[106:109]
	v_mfma_f32_16x16x32_bf16 v[74:77], v[152:155], v[184:187], v[74:77]
	v_mfma_f32_16x16x32_bf16 v[102:105], v[138:141], v[192:195], v[102:105]
	v_mfma_f32_16x16x32_bf16 v[70:73], v[152:155], v[192:195], v[70:73]
	v_mfma_f32_16x16x32_bf16 v[98:101], v[138:141], v[200:203], v[98:101]
	v_mfma_f32_16x16x32_bf16 v[66:69], v[152:155], v[200:203], v[66:69]
	v_mfma_f32_16x16x32_bf16 v[110:113], v[142:145], v[180:183], v[110:113]
	v_mfma_f32_16x16x32_bf16 v[78:81], v[156:159], v[180:183], v[78:81]
	v_mfma_f32_16x16x32_bf16 v[106:109], v[142:145], v[188:191], v[106:109]
	v_mfma_f32_16x16x32_bf16 v[74:77], v[156:159], v[188:191], v[74:77]
	v_mfma_f32_16x16x32_bf16 v[102:105], v[142:145], v[196:199], v[102:105]
	v_mfma_f32_16x16x32_bf16 v[70:73], v[156:159], v[196:199], v[70:73]
	v_mfma_f32_16x16x32_bf16 v[98:101], v[142:145], v[214:217], v[98:101]
	v_mfma_f32_16x16x32_bf16 v[66:69], v[156:159], v[214:217], v[66:69]
	v_mfma_f32_16x16x32_bf16 v[46:49], v[160:163], v[176:179], v[46:49]
	v_mfma_f32_16x16x32_bf16 v[14:17], v[168:171], v[176:179], v[14:17]
	v_mfma_f32_16x16x32_bf16 v[42:45], v[160:163], v[184:187], v[42:45]
	v_mfma_f32_16x16x32_bf16 v[10:13], v[168:171], v[184:187], v[10:13]
	v_mfma_f32_16x16x32_bf16 v[38:41], v[160:163], v[192:195], v[38:41]
	v_mfma_f32_16x16x32_bf16 v[6:9], v[168:171], v[192:195], v[6:9]
	v_mfma_f32_16x16x32_bf16 v[34:37], v[160:163], v[200:203], v[34:37]
	v_mfma_f32_16x16x32_bf16 v[2:5], v[168:171], v[200:203], v[2:5]
	v_mfma_f32_16x16x32_bf16 v[46:49], v[164:167], v[180:183], v[46:49]
	v_mfma_f32_16x16x32_bf16 v[14:17], v[172:175], v[180:183], v[14:17]
	v_mfma_f32_16x16x32_bf16 v[42:45], v[164:167], v[188:191], v[42:45]
	v_mfma_f32_16x16x32_bf16 v[10:13], v[172:175], v[188:191], v[10:13]
	v_mfma_f32_16x16x32_bf16 v[38:41], v[164:167], v[196:199], v[38:41]
	v_mfma_f32_16x16x32_bf16 v[6:9], v[172:175], v[196:199], v[6:9]
	v_mfma_f32_16x16x32_bf16 v[34:37], v[164:167], v[214:217], v[34:37]
	v_mfma_f32_16x16x32_bf16 v[2:5], v[172:175], v[214:217], v[2:5]
	s_barrier
	s_add_i32 s31, 0, 0x18000
	v_add_u32_e32 v151, s31, v148
	s_add_i32 s62, 0, 0x1c000
	ds_read_b128 v[138:141], v151
	ds_read_b128 v[142:145], v151 offset:1024
	ds_read_b128 v[152:155], v151 offset:2048
	ds_read_b128 v[156:159], v151 offset:3072
	v_add_u32_e32 v151, s62, v148
	ds_read_b128 v[160:163], v151
	ds_read_b128 v[164:167], v151 offset:1024
	ds_read_b128 v[168:171], v151 offset:2048
	ds_read_b128 v[172:175], v151 offset:3072
	s_add_u32 s22, s22, s8
	s_addc_u32 s23, s23, s9
	s_mov_b32 m0, s73
	v_lshl_add_u64 v[226:227], s[22:23], 0, v[132:133]
	ds_read_b128 v[176:179], v150 offset:32768
	ds_read_b128 v[180:183], v150 offset:33792
	ds_read_b128 v[184:187], v150 offset:34816
	ds_read_b128 v[188:191], v150 offset:35840
	ds_read_b128 v[192:195], v150 offset:36864
	ds_read_b128 v[196:199], v150 offset:37888
	ds_read_b128 v[200:203], v150 offset:38912
	ds_read_b128 v[214:217], v150 offset:39936
	global_load_lds_dwordx4 v[226:227], off
	v_lshl_add_u64 v[226:227], s[22:23], 0, v[130:131]
	s_mov_b32 m0, s74
	s_nop 0
	global_load_lds_dwordx4 v[226:227], off
	s_waitcnt vmcnt(8)
	s_waitcnt lgkmcnt(0)
	s_barrier
	s_waitcnt lgkmcnt(0)
	v_mfma_f32_16x16x32_bf16 v[126:129], v[138:141], v[176:179], v[126:129]
	v_mfma_f32_16x16x32_bf16 v[94:97], v[152:155], v[176:179], v[94:97]
	v_mfma_f32_16x16x32_bf16 v[122:125], v[138:141], v[184:187], v[122:125]
	v_mfma_f32_16x16x32_bf16 v[90:93], v[152:155], v[184:187], v[90:93]
	v_mfma_f32_16x16x32_bf16 v[118:121], v[138:141], v[192:195], v[118:121]
	v_mfma_f32_16x16x32_bf16 v[86:89], v[152:155], v[192:195], v[86:89]
	v_mfma_f32_16x16x32_bf16 v[114:117], v[138:141], v[200:203], v[114:117]
	v_mfma_f32_16x16x32_bf16 v[82:85], v[152:155], v[200:203], v[82:85]
	v_mfma_f32_16x16x32_bf16 v[126:129], v[142:145], v[180:183], v[126:129]
	v_mfma_f32_16x16x32_bf16 v[94:97], v[156:159], v[180:183], v[94:97]
	v_mfma_f32_16x16x32_bf16 v[122:125], v[142:145], v[188:191], v[122:125]
	v_mfma_f32_16x16x32_bf16 v[90:93], v[156:159], v[188:191], v[90:93]
	v_mfma_f32_16x16x32_bf16 v[118:121], v[142:145], v[196:199], v[118:121]
	v_mfma_f32_16x16x32_bf16 v[86:89], v[156:159], v[196:199], v[86:89]
	v_mfma_f32_16x16x32_bf16 v[114:117], v[142:145], v[214:217], v[114:117]
	v_mfma_f32_16x16x32_bf16 v[82:85], v[156:159], v[214:217], v[82:85]
	v_mfma_f32_16x16x32_bf16 v[62:65], v[160:163], v[176:179], v[62:65]
	v_mfma_f32_16x16x32_bf16 v[30:33], v[168:171], v[176:179], v[30:33]
	v_mfma_f32_16x16x32_bf16 v[58:61], v[160:163], v[184:187], v[58:61]
	v_mfma_f32_16x16x32_bf16 v[26:29], v[168:171], v[184:187], v[26:29]
	v_mfma_f32_16x16x32_bf16 v[54:57], v[160:163], v[192:195], v[54:57]
	v_mfma_f32_16x16x32_bf16 v[22:25], v[168:171], v[192:195], v[22:25]
	v_mfma_f32_16x16x32_bf16 v[50:53], v[160:163], v[200:203], v[50:53]
	v_mfma_f32_16x16x32_bf16 v[18:21], v[168:171], v[200:203], v[18:21]
	v_mfma_f32_16x16x32_bf16 v[62:65], v[164:167], v[180:183], v[62:65]
	v_mfma_f32_16x16x32_bf16 v[30:33], v[172:175], v[180:183], v[30:33]
	v_mfma_f32_16x16x32_bf16 v[58:61], v[164:167], v[188:191], v[58:61]
	v_mfma_f32_16x16x32_bf16 v[26:29], v[172:175], v[188:191], v[26:29]
	v_mfma_f32_16x16x32_bf16 v[54:57], v[164:167], v[196:199], v[54:57]
	v_mfma_f32_16x16x32_bf16 v[22:25], v[172:175], v[196:199], v[22:25]
	v_mfma_f32_16x16x32_bf16 v[50:53], v[164:167], v[214:217], v[50:53]
	v_mfma_f32_16x16x32_bf16 v[18:21], v[172:175], v[214:217], v[18:21]
	s_barrier
	s_add_i32 s22, s31, s56
	v_lshl_add_u64 v[146:147], v[146:147], 0, s[60:61]
	s_mov_b32 m0, s22
	ds_read_b128 v[176:179], v150 offset:49152
	ds_read_b128 v[180:183], v150 offset:50176
	ds_read_b128 v[184:187], v150 offset:51200
	ds_read_b128 v[188:191], v150 offset:52224
	ds_read_b128 v[192:195], v150 offset:53248
	ds_read_b128 v[196:199], v150 offset:54272
	ds_read_b128 v[200:203], v150 offset:55296
	ds_read_b128 v[214:217], v150 offset:56320
	global_load_lds_dwordx4 v[146:147], off
	v_lshl_add_u64 v[146:147], v[204:205], 0, s[60:61]
	s_add_i32 m0, s22, 0x2000
	s_add_i32 s22, s62, s56
	global_load_lds_dwordx4 v[146:147], off
	v_lshl_add_u64 v[146:147], v[218:219], 0, s[60:61]
	s_mov_b32 m0, s22
	s_nop 0
	global_load_lds_dwordx4 v[146:147], off
	v_lshl_add_u64 v[146:147], v[220:221], 0, s[60:61]
	s_add_i32 m0, s22, 0x2000
	s_nop 0
	global_load_lds_dwordx4 v[146:147], off
	v_lshl_add_u64 v[146:147], v[222:223], 0, s[60:61]
	s_mov_b32 m0, s77
	s_nop 0
	global_load_lds_dwordx4 v[146:147], off
	v_lshl_add_u64 v[146:147], v[224:225], 0, s[60:61]
	s_mov_b32 m0, s78
	s_nop 0
	global_load_lds_dwordx4 v[146:147], off
	s_waitcnt vmcnt(8)
	s_waitcnt lgkmcnt(0)
	s_barrier
	s_waitcnt lgkmcnt(0)
	v_mfma_f32_16x16x32_bf16 v[110:113], v[138:141], v[176:179], v[110:113]
	v_mfma_f32_16x16x32_bf16 v[78:81], v[152:155], v[176:179], v[78:81]
	v_mfma_f32_16x16x32_bf16 v[106:109], v[138:141], v[184:187], v[106:109]
	v_mfma_f32_16x16x32_bf16 v[74:77], v[152:155], v[184:187], v[74:77]
	v_mfma_f32_16x16x32_bf16 v[102:105], v[138:141], v[192:195], v[102:105]
	v_mfma_f32_16x16x32_bf16 v[70:73], v[152:155], v[192:195], v[70:73]
	v_mfma_f32_16x16x32_bf16 v[98:101], v[138:141], v[200:203], v[98:101]
	v_mfma_f32_16x16x32_bf16 v[66:69], v[152:155], v[200:203], v[66:69]
	v_mfma_f32_16x16x32_bf16 v[110:113], v[142:145], v[180:183], v[110:113]
	v_mfma_f32_16x16x32_bf16 v[78:81], v[156:159], v[180:183], v[78:81]
	v_mfma_f32_16x16x32_bf16 v[106:109], v[142:145], v[188:191], v[106:109]
	v_mfma_f32_16x16x32_bf16 v[74:77], v[156:159], v[188:191], v[74:77]
	v_mfma_f32_16x16x32_bf16 v[102:105], v[142:145], v[196:199], v[102:105]
	v_mfma_f32_16x16x32_bf16 v[70:73], v[156:159], v[196:199], v[70:73]
	v_mfma_f32_16x16x32_bf16 v[98:101], v[142:145], v[214:217], v[98:101]
	v_mfma_f32_16x16x32_bf16 v[66:69], v[156:159], v[214:217], v[66:69]
	v_mfma_f32_16x16x32_bf16 v[46:49], v[160:163], v[176:179], v[46:49]
	v_mfma_f32_16x16x32_bf16 v[14:17], v[168:171], v[176:179], v[14:17]
	v_mfma_f32_16x16x32_bf16 v[42:45], v[160:163], v[184:187], v[42:45]
	v_mfma_f32_16x16x32_bf16 v[10:13], v[168:171], v[184:187], v[10:13]
	v_mfma_f32_16x16x32_bf16 v[38:41], v[160:163], v[192:195], v[38:41]
	v_mfma_f32_16x16x32_bf16 v[6:9], v[168:171], v[192:195], v[6:9]
	v_mfma_f32_16x16x32_bf16 v[34:37], v[160:163], v[200:203], v[34:37]
	v_mfma_f32_16x16x32_bf16 v[2:5], v[168:171], v[200:203], v[2:5]
	v_mfma_f32_16x16x32_bf16 v[46:49], v[164:167], v[180:183], v[46:49]
	v_mfma_f32_16x16x32_bf16 v[14:17], v[172:175], v[180:183], v[14:17]
	v_mfma_f32_16x16x32_bf16 v[42:45], v[164:167], v[188:191], v[42:45]
	v_mfma_f32_16x16x32_bf16 v[10:13], v[172:175], v[188:191], v[10:13]
	v_mfma_f32_16x16x32_bf16 v[38:41], v[164:167], v[196:199], v[38:41]
	v_mfma_f32_16x16x32_bf16 v[6:9], v[172:175], v[196:199], v[6:9]
	v_mfma_f32_16x16x32_bf16 v[34:37], v[164:167], v[214:217], v[34:37]
	v_mfma_f32_16x16x32_bf16 v[2:5], v[172:175], v[214:217], v[2:5]
	s_barrier
	s_add_u32 s20, s20, 0x100
	s_addc_u32 s21, s21, 0
	s_add_u32 vcc_lo, vcc_lo, 0x100
	s_addc_u32 vcc_hi, vcc_hi, 0
	s_cmp_ge_i32 s88, s79
	s_mov_b32 s22, s88
	s_cbranch_scc0 .LBB0_360

.Lzgo_3:
	s_add_u32 s18, s18, 0x80
	s_addc_u32 s19, s19, 0
	s_add_u32 s71, s20, 0x100
	s_addc_u32 s72, s21, 0
	s_mov_b32 s20, 0
	s_add_i32 s73, s20, 2
	s_add_u32 s31, s18, 0x80
	s_addc_u32 s21, s19, 0
	s_add_i32 s74, 0, 0x10000
	s_cmp_eq_u32 s11, s20
	s_cselect_b32 s21, s3, s21
	s_cselect_b32 s20, s2, s31
	v_add_u32_e32 v145, s74, v142
	s_cselect_b32 s63, s17, s72
	s_cselect_b32 s62, s16, s71
	s_add_i32 s31, 0, 0x14000
	ds_read_b128 v[146:149], v145
	ds_read_b128 v[150:153], v145 offset:1024
	ds_read_b128 v[154:157], v145 offset:2048
	ds_read_b128 v[158:161], v145 offset:3072
	v_add_u32_e32 v145, s31, v142
	ds_read_b128 v[162:165], v145
	ds_read_b128 v[166:169], v145 offset:1024
	ds_read_b128 v[170:173], v145 offset:2048
	ds_read_b128 v[174:177], v145 offset:3072
	v_lshl_add_u64 v[218:219], s[18:19], 0, v[138:139]
	s_add_i32 m0, s23, 0xc000
	ds_read_b128 v[178:181], v144
	ds_read_b128 v[182:185], v144 offset:1024
	ds_read_b128 v[186:189], v144 offset:2048
	ds_read_b128 v[190:193], v144 offset:3072
	ds_read_b128 v[194:197], v144 offset:4096
	ds_read_b128 v[198:201], v144 offset:5120
	ds_read_b128 v[202:205], v144 offset:6144
	ds_read_b128 v[214:217], v144 offset:7168
	global_load_lds_dwordx4 v[218:219], off
	v_lshl_add_u64 v[218:219], s[18:19], 0, v[140:141]
	s_add_i32 m0, s23, 0xe000
	s_nop 0
	global_load_lds_dwordx4 v[218:219], off
	s_waitcnt vmcnt(8)
	s_waitcnt lgkmcnt(0)
	s_barrier
	s_waitcnt lgkmcnt(0)
	v_mfma_f32_16x16x32_bf16 v[122:125], v[146:149], v[178:181], 0
	v_mfma_f32_16x16x32_bf16 v[126:129], v[154:157], v[178:181], 0
	v_mfma_f32_16x16x32_bf16 v[118:121], v[146:149], v[186:189], 0
	v_mfma_f32_16x16x32_bf16 v[114:117], v[154:157], v[186:189], 0
	v_mfma_f32_16x16x32_bf16 v[110:113], v[146:149], v[194:197], 0
	v_mfma_f32_16x16x32_bf16 v[106:109], v[154:157], v[194:197], 0
	v_mfma_f32_16x16x32_bf16 v[102:105], v[146:149], v[202:205], 0
	v_mfma_f32_16x16x32_bf16 v[98:101], v[154:157], v[202:205], 0
	v_mfma_f32_16x16x32_bf16 v[122:125], v[150:153], v[182:185], v[122:125]
	v_mfma_f32_16x16x32_bf16 v[126:129], v[158:161], v[182:185], v[126:129]
	v_mfma_f32_16x16x32_bf16 v[118:121], v[150:153], v[190:193], v[118:121]
	v_mfma_f32_16x16x32_bf16 v[114:117], v[158:161], v[190:193], v[114:117]
	v_mfma_f32_16x16x32_bf16 v[110:113], v[150:153], v[198:201], v[110:113]
	v_mfma_f32_16x16x32_bf16 v[106:109], v[158:161], v[198:201], v[106:109]
	v_mfma_f32_16x16x32_bf16 v[102:105], v[150:153], v[214:217], v[102:105]
	v_mfma_f32_16x16x32_bf16 v[98:101], v[158:161], v[214:217], v[98:101]
	v_mfma_f32_16x16x32_bf16 v[62:65], v[162:165], v[178:181], 0
	v_mfma_f32_16x16x32_bf16 v[58:61], v[170:173], v[178:181], 0
	v_mfma_f32_16x16x32_bf16 v[54:57], v[162:165], v[186:189], 0
	v_mfma_f32_16x16x32_bf16 v[50:53], v[170:173], v[186:189], 0
	v_mfma_f32_16x16x32_bf16 v[46:49], v[162:165], v[194:197], 0
	v_mfma_f32_16x16x32_bf16 v[42:45], v[170:173], v[194:197], 0
	v_mfma_f32_16x16x32_bf16 v[38:41], v[162:165], v[202:205], 0
	v_mfma_f32_16x16x32_bf16 v[34:37], v[170:173], v[202:205], 0
	v_mfma_f32_16x16x32_bf16 v[62:65], v[166:169], v[182:185], v[62:65]
	v_mfma_f32_16x16x32_bf16 v[58:61], v[174:177], v[182:185], v[58:61]
	v_mfma_f32_16x16x32_bf16 v[54:57], v[166:169], v[190:193], v[54:57]
	v_mfma_f32_16x16x32_bf16 v[50:53], v[174:177], v[190:193], v[50:53]
	v_mfma_f32_16x16x32_bf16 v[46:49], v[166:169], v[198:201], v[46:49]
	v_mfma_f32_16x16x32_bf16 v[42:45], v[174:177], v[198:201], v[42:45]
	v_mfma_f32_16x16x32_bf16 v[38:41], v[166:169], v[214:217], v[38:41]
	v_mfma_f32_16x16x32_bf16 v[34:37], v[174:177], v[214:217], v[34:37]
	s_barrier
	s_add_i32 s74, s74, s22
	v_lshl_add_u64 v[218:219], s[62:63], 0, v[134:135]
	s_mov_b32 m0, s74
	ds_read_b128 v[178:181], v144 offset:16384
	ds_read_b128 v[182:185], v144 offset:17408
	ds_read_b128 v[186:189], v144 offset:18432
	ds_read_b128 v[190:193], v144 offset:19456
	ds_read_b128 v[194:197], v144 offset:20480
	ds_read_b128 v[198:201], v144 offset:21504
	ds_read_b128 v[202:205], v144 offset:22528
	ds_read_b128 v[214:217], v144 offset:23552
	global_load_lds_dwordx4 v[218:219], off
	s_add_i32 m0, s74, 0x2000
	v_lshl_add_u64 v[220:221], s[62:63], 0, v[130:131]
	s_add_u32 s62, s62, s4
	s_addc_u32 s63, s63, s5
	s_add_i32 s31, s31, s22
	global_load_lds_dwordx4 v[220:221], off
	v_lshl_add_u64 v[222:223], s[62:63], 0, v[134:135]
	s_mov_b32 m0, s31
	v_lshl_add_u64 v[224:225], s[62:63], 0, v[130:131]
	global_load_lds_dwordx4 v[222:223], off
	s_add_i32 m0, s31, 0x2000
	v_lshl_add_u64 v[226:227], s[20:21], 0, v[136:137]
	global_load_lds_dwordx4 v[224:225], off
	s_mov_b32 m0, s23
	v_lshl_add_u64 v[236:237], s[20:21], 0, v[132:133]
	global_load_lds_dwordx4 v[226:227], off
	s_mov_b32 m0, s52
	s_nop 0
	global_load_lds_dwordx4 v[236:237], off
	s_waitcnt vmcnt(8)
	s_waitcnt lgkmcnt(0)
	s_barrier
	s_waitcnt lgkmcnt(0)
	v_mfma_f32_16x16x32_bf16 v[94:97], v[146:149], v[178:181], 0
	v_mfma_f32_16x16x32_bf16 v[90:93], v[154:157], v[178:181], 0
	v_mfma_f32_16x16x32_bf16 v[86:89], v[146:149], v[186:189], 0
	v_mfma_f32_16x16x32_bf16 v[82:85], v[154:157], v[186:189], 0
	v_mfma_f32_16x16x32_bf16 v[78:81], v[146:149], v[194:197], 0
	v_mfma_f32_16x16x32_bf16 v[74:77], v[154:157], v[194:197], 0
	v_mfma_f32_16x16x32_bf16 v[70:73], v[146:149], v[202:205], 0
	v_mfma_f32_16x16x32_bf16 v[66:69], v[154:157], v[202:205], 0
	v_mfma_f32_16x16x32_bf16 v[94:97], v[150:153], v[182:185], v[94:97]
	v_mfma_f32_16x16x32_bf16 v[90:93], v[158:161], v[182:185], v[90:93]
	v_mfma_f32_16x16x32_bf16 v[86:89], v[150:153], v[190:193], v[86:89]
	v_mfma_f32_16x16x32_bf16 v[82:85], v[158:161], v[190:193], v[82:85]
	v_mfma_f32_16x16x32_bf16 v[78:81], v[150:153], v[198:201], v[78:81]
	v_mfma_f32_16x16x32_bf16 v[74:77], v[158:161], v[198:201], v[74:77]
	v_mfma_f32_16x16x32_bf16 v[70:73], v[150:153], v[214:217], v[70:73]
	v_mfma_f32_16x16x32_bf16 v[66:69], v[158:161], v[214:217], v[66:69]
	v_mfma_f32_16x16x32_bf16 v[30:33], v[162:165], v[178:181], 0
	v_mfma_f32_16x16x32_bf16 v[26:29], v[170:173], v[178:181], 0
	v_mfma_f32_16x16x32_bf16 v[22:25], v[162:165], v[186:189], 0
	v_mfma_f32_16x16x32_bf16 v[18:21], v[170:173], v[186:189], 0
	v_mfma_f32_16x16x32_bf16 v[14:17], v[162:165], v[194:197], 0
	v_mfma_f32_16x16x32_bf16 v[10:13], v[170:173], v[194:197], 0
	v_mfma_f32_16x16x32_bf16 v[6:9], v[162:165], v[202:205], 0
	v_mfma_f32_16x16x32_bf16 v[2:5], v[170:173], v[202:205], 0
	v_mfma_f32_16x16x32_bf16 v[30:33], v[166:169], v[182:185], v[30:33]
	v_mfma_f32_16x16x32_bf16 v[26:29], v[174:177], v[182:185], v[26:29]
	v_mfma_f32_16x16x32_bf16 v[22:25], v[166:169], v[190:193], v[22:25]
	v_mfma_f32_16x16x32_bf16 v[18:21], v[174:177], v[190:193], v[18:21]
	v_mfma_f32_16x16x32_bf16 v[14:17], v[166:169], v[198:201], v[14:17]
	v_mfma_f32_16x16x32_bf16 v[10:13], v[174:177], v[198:201], v[10:13]
	v_mfma_f32_16x16x32_bf16 v[6:9], v[166:169], v[214:217], v[6:9]
	v_mfma_f32_16x16x32_bf16 v[2:5], v[174:177], v[214:217], v[2:5]
	s_barrier
	s_add_i32 s31, 0, 0x18000
	v_add_u32_e32 v145, s31, v142
	s_add_i32 s62, 0, 0x1c000
	ds_read_b128 v[146:149], v145
	ds_read_b128 v[150:153], v145 offset:1024
	ds_read_b128 v[154:157], v145 offset:2048
	ds_read_b128 v[158:161], v145 offset:3072
	v_add_u32_e32 v145, s62, v142
	ds_read_b128 v[162:165], v145
	ds_read_b128 v[166:169], v145 offset:1024
	ds_read_b128 v[170:173], v145 offset:2048
	ds_read_b128 v[174:177], v145 offset:3072
	s_add_u32 s20, s20, s4
	s_addc_u32 s21, s21, s5
	s_mov_b32 m0, s53
	v_lshl_add_u64 v[238:239], s[20:21], 0, v[136:137]
	ds_read_b128 v[178:181], v144 offset:32768
	ds_read_b128 v[182:185], v144 offset:33792
	ds_read_b128 v[186:189], v144 offset:34816
	ds_read_b128 v[190:193], v144 offset:35840
	ds_read_b128 v[194:197], v144 offset:36864
	ds_read_b128 v[198:201], v144 offset:37888
	ds_read_b128 v[202:205], v144 offset:38912
	ds_read_b128 v[214:217], v144 offset:39936
	global_load_lds_dwordx4 v[238:239], off
	v_lshl_add_u64 v[238:239], s[20:21], 0, v[132:133]
	s_mov_b32 m0, s56
	s_nop 0
	global_load_lds_dwordx4 v[238:239], off
	s_waitcnt vmcnt(8)
	s_waitcnt lgkmcnt(0)
	s_barrier
	s_waitcnt lgkmcnt(0)
	v_mfma_f32_16x16x32_bf16 v[122:125], v[146:149], v[178:181], v[122:125]
	v_mfma_f32_16x16x32_bf16 v[126:129], v[154:157], v[178:181], v[126:129]
	v_mfma_f32_16x16x32_bf16 v[118:121], v[146:149], v[186:189], v[118:121]
	v_mfma_f32_16x16x32_bf16 v[114:117], v[154:157], v[186:189], v[114:117]
	v_mfma_f32_16x16x32_bf16 v[110:113], v[146:149], v[194:197], v[110:113]
	v_mfma_f32_16x16x32_bf16 v[106:109], v[154:157], v[194:197], v[106:109]
	v_mfma_f32_16x16x32_bf16 v[102:105], v[146:149], v[202:205], v[102:105]
	v_mfma_f32_16x16x32_bf16 v[98:101], v[154:157], v[202:205], v[98:101]
	v_mfma_f32_16x16x32_bf16 v[122:125], v[150:153], v[182:185], v[122:125]
	v_mfma_f32_16x16x32_bf16 v[126:129], v[158:161], v[182:185], v[126:129]
	v_mfma_f32_16x16x32_bf16 v[118:121], v[150:153], v[190:193], v[118:121]
	v_mfma_f32_16x16x32_bf16 v[114:117], v[158:161], v[190:193], v[114:117]
	v_mfma_f32_16x16x32_bf16 v[110:113], v[150:153], v[198:201], v[110:113]
	v_mfma_f32_16x16x32_bf16 v[106:109], v[158:161], v[198:201], v[106:109]
	v_mfma_f32_16x16x32_bf16 v[102:105], v[150:153], v[214:217], v[102:105]
	v_mfma_f32_16x16x32_bf16 v[98:101], v[158:161], v[214:217], v[98:101]
	v_mfma_f32_16x16x32_bf16 v[62:65], v[162:165], v[178:181], v[62:65]
	v_mfma_f32_16x16x32_bf16 v[58:61], v[170:173], v[178:181], v[58:61]
	v_mfma_f32_16x16x32_bf16 v[54:57], v[162:165], v[186:189], v[54:57]
	v_mfma_f32_16x16x32_bf16 v[50:53], v[170:173], v[186:189], v[50:53]
	v_mfma_f32_16x16x32_bf16 v[46:49], v[162:165], v[194:197], v[46:49]
	v_mfma_f32_16x16x32_bf16 v[42:45], v[170:173], v[194:197], v[42:45]
	v_mfma_f32_16x16x32_bf16 v[38:41], v[162:165], v[202:205], v[38:41]
	v_mfma_f32_16x16x32_bf16 v[34:37], v[170:173], v[202:205], v[34:37]
	v_mfma_f32_16x16x32_bf16 v[62:65], v[166:169], v[182:185], v[62:65]
	v_mfma_f32_16x16x32_bf16 v[58:61], v[174:177], v[182:185], v[58:61]
	v_mfma_f32_16x16x32_bf16 v[54:57], v[166:169], v[190:193], v[54:57]
	v_mfma_f32_16x16x32_bf16 v[50:53], v[174:177], v[190:193], v[50:53]
	v_mfma_f32_16x16x32_bf16 v[46:49], v[166:169], v[198:201], v[46:49]
	v_mfma_f32_16x16x32_bf16 v[42:45], v[174:177], v[198:201], v[42:45]
	v_mfma_f32_16x16x32_bf16 v[38:41], v[166:169], v[214:217], v[38:41]
	v_mfma_f32_16x16x32_bf16 v[34:37], v[174:177], v[214:217], v[34:37]
	s_barrier
	s_add_i32 s20, s31, s22
	v_lshl_add_u64 v[218:219], v[218:219], 0, s[60:61]
	s_mov_b32 m0, s20
	ds_read_b128 v[178:181], v144 offset:49152
	ds_read_b128 v[182:185], v144 offset:50176
	ds_read_b128 v[186:189], v144 offset:51200
	ds_read_b128 v[190:193], v144 offset:52224
	ds_read_b128 v[194:197], v144 offset:53248
	ds_read_b128 v[198:201], v144 offset:54272
	ds_read_b128 v[202:205], v144 offset:55296
	ds_read_b128 v[214:217], v144 offset:56320
	global_load_lds_dwordx4 v[218:219], off
	v_lshl_add_u64 v[218:219], v[220:221], 0, s[60:61]
	s_add_i32 m0, s20, 0x2000
	s_add_i32 s20, s62, s22
	global_load_lds_dwordx4 v[218:219], off
	v_lshl_add_u64 v[218:219], v[222:223], 0, s[60:61]
	s_mov_b32 m0, s20
	s_nop 0
	global_load_lds_dwordx4 v[218:219], off
	v_lshl_add_u64 v[218:219], v[224:225], 0, s[60:61]
	s_add_i32 m0, s20, 0x2000
	s_nop 0
	global_load_lds_dwordx4 v[218:219], off
	v_lshl_add_u64 v[218:219], v[226:227], 0, s[60:61]
	s_mov_b32 m0, s57
	s_nop 0
	global_load_lds_dwordx4 v[218:219], off
	v_lshl_add_u64 v[218:219], v[236:237], 0, s[60:61]
	s_mov_b32 m0, s65
	s_nop 0
	global_load_lds_dwordx4 v[218:219], off
	s_waitcnt vmcnt(8)
	s_waitcnt lgkmcnt(0)
	s_barrier
	s_waitcnt lgkmcnt(0)
	v_mfma_f32_16x16x32_bf16 v[94:97], v[146:149], v[178:181], v[94:97]
	v_mfma_f32_16x16x32_bf16 v[90:93], v[154:157], v[178:181], v[90:93]
	v_mfma_f32_16x16x32_bf16 v[86:89], v[146:149], v[186:189], v[86:89]
	v_mfma_f32_16x16x32_bf16 v[82:85], v[154:157], v[186:189], v[82:85]
	v_mfma_f32_16x16x32_bf16 v[78:81], v[146:149], v[194:197], v[78:81]
	v_mfma_f32_16x16x32_bf16 v[74:77], v[154:157], v[194:197], v[74:77]
	v_mfma_f32_16x16x32_bf16 v[70:73], v[146:149], v[202:205], v[70:73]
	v_mfma_f32_16x16x32_bf16 v[66:69], v[154:157], v[202:205], v[66:69]
	v_mfma_f32_16x16x32_bf16 v[94:97], v[150:153], v[182:185], v[94:97]
	v_mfma_f32_16x16x32_bf16 v[90:93], v[158:161], v[182:185], v[90:93]
	v_mfma_f32_16x16x32_bf16 v[86:89], v[150:153], v[190:193], v[86:89]
	v_mfma_f32_16x16x32_bf16 v[82:85], v[158:161], v[190:193], v[82:85]
	v_mfma_f32_16x16x32_bf16 v[78:81], v[150:153], v[198:201], v[78:81]
	v_mfma_f32_16x16x32_bf16 v[74:77], v[158:161], v[198:201], v[74:77]
	v_mfma_f32_16x16x32_bf16 v[70:73], v[150:153], v[214:217], v[70:73]
	v_mfma_f32_16x16x32_bf16 v[66:69], v[158:161], v[214:217], v[66:69]
	v_mfma_f32_16x16x32_bf16 v[30:33], v[162:165], v[178:181], v[30:33]
	v_mfma_f32_16x16x32_bf16 v[26:29], v[170:173], v[178:181], v[26:29]
	v_mfma_f32_16x16x32_bf16 v[22:25], v[162:165], v[186:189], v[22:25]
	v_mfma_f32_16x16x32_bf16 v[18:21], v[170:173], v[186:189], v[18:21]
	v_mfma_f32_16x16x32_bf16 v[14:17], v[162:165], v[194:197], v[14:17]
	v_mfma_f32_16x16x32_bf16 v[10:13], v[170:173], v[194:197], v[10:13]
	v_mfma_f32_16x16x32_bf16 v[6:9], v[162:165], v[202:205], v[6:9]
	v_mfma_f32_16x16x32_bf16 v[2:5], v[170:173], v[202:205], v[2:5]
	v_mfma_f32_16x16x32_bf16 v[30:33], v[166:169], v[182:185], v[30:33]
	v_mfma_f32_16x16x32_bf16 v[26:29], v[174:177], v[182:185], v[26:29]
	v_mfma_f32_16x16x32_bf16 v[22:25], v[166:169], v[190:193], v[22:25]
	v_mfma_f32_16x16x32_bf16 v[18:21], v[174:177], v[190:193], v[18:21]
	v_mfma_f32_16x16x32_bf16 v[14:17], v[166:169], v[198:201], v[14:17]
	v_mfma_f32_16x16x32_bf16 v[10:13], v[174:177], v[198:201], v[10:13]
	v_mfma_f32_16x16x32_bf16 v[6:9], v[166:169], v[214:217], v[6:9]
	v_mfma_f32_16x16x32_bf16 v[2:5], v[174:177], v[214:217], v[2:5]
	s_barrier
	s_add_u32 s18, s18, 0x100
	s_addc_u32 s19, s19, 0
	s_add_u32 s71, s71, 0x100
	s_addc_u32 s72, s72, 0
	s_cmp_ge_i32 s73, s10
	s_mov_b32 s20, s73
	s_cbranch_scc1 .LBB0_493
.LBB0_492:
	s_add_i32 s73, s20, 2
	s_add_u32 s31, s18, 0x80
	s_addc_u32 s21, s19, 0
	s_add_i32 s74, 0, 0x10000
	s_cmp_eq_u32 s11, s20
	s_cselect_b32 s21, s3, s21
	s_cselect_b32 s20, s2, s31
	v_add_u32_e32 v145, s74, v142
	s_cselect_b32 s63, s17, s72
	s_cselect_b32 s62, s16, s71
	s_add_i32 s31, 0, 0x14000
	ds_read_b128 v[146:149], v145
	ds_read_b128 v[150:153], v145 offset:1024
	ds_read_b128 v[154:157], v145 offset:2048
	ds_read_b128 v[158:161], v145 offset:3072
	v_add_u32_e32 v145, s31, v142
	ds_read_b128 v[162:165], v145
	ds_read_b128 v[166:169], v145 offset:1024
	ds_read_b128 v[170:173], v145 offset:2048
	ds_read_b128 v[174:177], v145 offset:3072
	v_lshl_add_u64 v[218:219], s[18:19], 0, v[138:139]
	s_add_i32 m0, s23, 0xc000
	ds_read_b128 v[178:181], v144
	ds_read_b128 v[182:185], v144 offset:1024
	ds_read_b128 v[186:189], v144 offset:2048
	ds_read_b128 v[190:193], v144 offset:3072
	ds_read_b128 v[194:197], v144 offset:4096
	ds_read_b128 v[198:201], v144 offset:5120
	ds_read_b128 v[202:205], v144 offset:6144
	ds_read_b128 v[214:217], v144 offset:7168
	global_load_lds_dwordx4 v[218:219], off
	v_lshl_add_u64 v[218:219], s[18:19], 0, v[140:141]
	s_add_i32 m0, s23, 0xe000
	s_nop 0
	global_load_lds_dwordx4 v[218:219], off
	s_waitcnt vmcnt(8)
	s_waitcnt lgkmcnt(0)
	s_barrier
	s_waitcnt lgkmcnt(0)
	v_mfma_f32_16x16x32_bf16 v[122:125], v[146:149], v[178:181], v[122:125]
	v_mfma_f32_16x16x32_bf16 v[126:129], v[154:157], v[178:181], v[126:129]
	v_mfma_f32_16x16x32_bf16 v[118:121], v[146:149], v[186:189], v[118:121]
	v_mfma_f32_16x16x32_bf16 v[114:117], v[154:157], v[186:189], v[114:117]
	v_mfma_f32_16x16x32_bf16 v[110:113], v[146:149], v[194:197], v[110:113]
	v_mfma_f32_16x16x32_bf16 v[106:109], v[154:157], v[194:197], v[106:109]
	v_mfma_f32_16x16x32_bf16 v[102:105], v[146:149], v[202:205], v[102:105]
	v_mfma_f32_16x16x32_bf16 v[98:101], v[154:157], v[202:205], v[98:101]
	v_mfma_f32_16x16x32_bf16 v[122:125], v[150:153], v[182:185], v[122:125]
	v_mfma_f32_16x16x32_bf16 v[126:129], v[158:161], v[182:185], v[126:129]
	v_mfma_f32_16x16x32_bf16 v[118:121], v[150:153], v[190:193], v[118:121]
	v_mfma_f32_16x16x32_bf16 v[114:117], v[158:161], v[190:193], v[114:117]
	v_mfma_f32_16x16x32_bf16 v[110:113], v[150:153], v[198:201], v[110:113]
	v_mfma_f32_16x16x32_bf16 v[106:109], v[158:161], v[198:201], v[106:109]
	v_mfma_f32_16x16x32_bf16 v[102:105], v[150:153], v[214:217], v[102:105]
	v_mfma_f32_16x16x32_bf16 v[98:101], v[158:161], v[214:217], v[98:101]
	v_mfma_f32_16x16x32_bf16 v[62:65], v[162:165], v[178:181], v[62:65]
	v_mfma_f32_16x16x32_bf16 v[58:61], v[170:173], v[178:181], v[58:61]
	v_mfma_f32_16x16x32_bf16 v[54:57], v[162:165], v[186:189], v[54:57]
	v_mfma_f32_16x16x32_bf16 v[50:53], v[170:173], v[186:189], v[50:53]
	v_mfma_f32_16x16x32_bf16 v[46:49], v[162:165], v[194:197], v[46:49]
	v_mfma_f32_16x16x32_bf16 v[42:45], v[170:173], v[194:197], v[42:45]
	v_mfma_f32_16x16x32_bf16 v[38:41], v[162:165], v[202:205], v[38:41]
	v_mfma_f32_16x16x32_bf16 v[34:37], v[170:173], v[202:205], v[34:37]
	v_mfma_f32_16x16x32_bf16 v[62:65], v[166:169], v[182:185], v[62:65]
	v_mfma_f32_16x16x32_bf16 v[58:61], v[174:177], v[182:185], v[58:61]
	v_mfma_f32_16x16x32_bf16 v[54:57], v[166:169], v[190:193], v[54:57]
	v_mfma_f32_16x16x32_bf16 v[50:53], v[174:177], v[190:193], v[50:53]
	v_mfma_f32_16x16x32_bf16 v[46:49], v[166:169], v[198:201], v[46:49]
	v_mfma_f32_16x16x32_bf16 v[42:45], v[174:177], v[198:201], v[42:45]
	v_mfma_f32_16x16x32_bf16 v[38:41], v[166:169], v[214:217], v[38:41]
	v_mfma_f32_16x16x32_bf16 v[34:37], v[174:177], v[214:217], v[34:37]
	s_barrier
	s_add_i32 s74, s74, s22
	v_lshl_add_u64 v[218:219], s[62:63], 0, v[134:135]
	s_mov_b32 m0, s74
	ds_read_b128 v[178:181], v144 offset:16384
	ds_read_b128 v[182:185], v144 offset:17408
	ds_read_b128 v[186:189], v144 offset:18432
	ds_read_b128 v[190:193], v144 offset:19456
	ds_read_b128 v[194:197], v144 offset:20480
	ds_read_b128 v[198:201], v144 offset:21504
	ds_read_b128 v[202:205], v144 offset:22528
	ds_read_b128 v[214:217], v144 offset:23552
	global_load_lds_dwordx4 v[218:219], off
	s_add_i32 m0, s74, 0x2000
	v_lshl_add_u64 v[220:221], s[62:63], 0, v[130:131]
	s_add_u32 s62, s62, s4
	s_addc_u32 s63, s63, s5
	s_add_i32 s31, s31, s22
	global_load_lds_dwordx4 v[220:221], off
	v_lshl_add_u64 v[222:223], s[62:63], 0, v[134:135]
	s_mov_b32 m0, s31
	v_lshl_add_u64 v[224:225], s[62:63], 0, v[130:131]
	global_load_lds_dwordx4 v[222:223], off
	s_add_i32 m0, s31, 0x2000
	v_lshl_add_u64 v[226:227], s[20:21], 0, v[136:137]
	global_load_lds_dwordx4 v[224:225], off
	s_mov_b32 m0, s23
	v_lshl_add_u64 v[236:237], s[20:21], 0, v[132:133]
	global_load_lds_dwordx4 v[226:227], off
	s_mov_b32 m0, s52
	s_nop 0
	global_load_lds_dwordx4 v[236:237], off
	s_waitcnt vmcnt(8)
	s_waitcnt lgkmcnt(0)
	s_barrier
	s_waitcnt lgkmcnt(0)
	v_mfma_f32_16x16x32_bf16 v[94:97], v[146:149], v[178:181], v[94:97]
	v_mfma_f32_16x16x32_bf16 v[90:93], v[154:157], v[178:181], v[90:93]
	v_mfma_f32_16x16x32_bf16 v[86:89], v[146:149], v[186:189], v[86:89]
	v_mfma_f32_16x16x32_bf16 v[82:85], v[154:157], v[186:189], v[82:85]
	v_mfma_f32_16x16x32_bf16 v[78:81], v[146:149], v[194:197], v[78:81]
	v_mfma_f32_16x16x32_bf16 v[74:77], v[154:157], v[194:197], v[74:77]
	v_mfma_f32_16x16x32_bf16 v[70:73], v[146:149], v[202:205], v[70:73]
	v_mfma_f32_16x16x32_bf16 v[66:69], v[154:157], v[202:205], v[66:69]
	v_mfma_f32_16x16x32_bf16 v[94:97], v[150:153], v[182:185], v[94:97]
	v_mfma_f32_16x16x32_bf16 v[90:93], v[158:161], v[182:185], v[90:93]
	v_mfma_f32_16x16x32_bf16 v[86:89], v[150:153], v[190:193], v[86:89]
	v_mfma_f32_16x16x32_bf16 v[82:85], v[158:161], v[190:193], v[82:85]
	v_mfma_f32_16x16x32_bf16 v[78:81], v[150:153], v[198:201], v[78:81]
	v_mfma_f32_16x16x32_bf16 v[74:77], v[158:161], v[198:201], v[74:77]
	v_mfma_f32_16x16x32_bf16 v[70:73], v[150:153], v[214:217], v[70:73]
	v_mfma_f32_16x16x32_bf16 v[66:69], v[158:161], v[214:217], v[66:69]
	v_mfma_f32_16x16x32_bf16 v[30:33], v[162:165], v[178:181], v[30:33]
	v_mfma_f32_16x16x32_bf16 v[26:29], v[170:173], v[178:181], v[26:29]
	v_mfma_f32_16x16x32_bf16 v[22:25], v[162:165], v[186:189], v[22:25]
	v_mfma_f32_16x16x32_bf16 v[18:21], v[170:173], v[186:189], v[18:21]
	v_mfma_f32_16x16x32_bf16 v[14:17], v[162:165], v[194:197], v[14:17]
	v_mfma_f32_16x16x32_bf16 v[10:13], v[170:173], v[194:197], v[10:13]
	v_mfma_f32_16x16x32_bf16 v[6:9], v[162:165], v[202:205], v[6:9]
	v_mfma_f32_16x16x32_bf16 v[2:5], v[170:173], v[202:205], v[2:5]
	v_mfma_f32_16x16x32_bf16 v[30:33], v[166:169], v[182:185], v[30:33]
	v_mfma_f32_16x16x32_bf16 v[26:29], v[174:177], v[182:185], v[26:29]
	v_mfma_f32_16x16x32_bf16 v[22:25], v[166:169], v[190:193], v[22:25]
	v_mfma_f32_16x16x32_bf16 v[18:21], v[174:177], v[190:193], v[18:21]
	v_mfma_f32_16x16x32_bf16 v[14:17], v[166:169], v[198:201], v[14:17]
	v_mfma_f32_16x16x32_bf16 v[10:13], v[174:177], v[198:201], v[10:13]
	v_mfma_f32_16x16x32_bf16 v[6:9], v[166:169], v[214:217], v[6:9]
	v_mfma_f32_16x16x32_bf16 v[2:5], v[174:177], v[214:217], v[2:5]
	s_barrier
	s_add_i32 s31, 0, 0x18000
	v_add_u32_e32 v145, s31, v142
	s_add_i32 s62, 0, 0x1c000
	ds_read_b128 v[146:149], v145
	ds_read_b128 v[150:153], v145 offset:1024
	ds_read_b128 v[154:157], v145 offset:2048
	ds_read_b128 v[158:161], v145 offset:3072
	v_add_u32_e32 v145, s62, v142
	ds_read_b128 v[162:165], v145
	ds_read_b128 v[166:169], v145 offset:1024
	ds_read_b128 v[170:173], v145 offset:2048
	ds_read_b128 v[174:177], v145 offset:3072
	s_add_u32 s20, s20, s4
	s_addc_u32 s21, s21, s5
	s_mov_b32 m0, s53
	v_lshl_add_u64 v[238:239], s[20:21], 0, v[136:137]
	ds_read_b128 v[178:181], v144 offset:32768
	ds_read_b128 v[182:185], v144 offset:33792
	ds_read_b128 v[186:189], v144 offset:34816
	ds_read_b128 v[190:193], v144 offset:35840
	ds_read_b128 v[194:197], v144 offset:36864
	ds_read_b128 v[198:201], v144 offset:37888
	ds_read_b128 v[202:205], v144 offset:38912
	ds_read_b128 v[214:217], v144 offset:39936
	global_load_lds_dwordx4 v[238:239], off
	v_lshl_add_u64 v[238:239], s[20:21], 0, v[132:133]
	s_mov_b32 m0, s56
	s_nop 0
	global_load_lds_dwordx4 v[238:239], off
	s_waitcnt vmcnt(8)
	s_waitcnt lgkmcnt(0)
	s_barrier
	s_waitcnt lgkmcnt(0)
	v_mfma_f32_16x16x32_bf16 v[122:125], v[146:149], v[178:181], v[122:125]
	v_mfma_f32_16x16x32_bf16 v[126:129], v[154:157], v[178:181], v[126:129]
	v_mfma_f32_16x16x32_bf16 v[118:121], v[146:149], v[186:189], v[118:121]
	v_mfma_f32_16x16x32_bf16 v[114:117], v[154:157], v[186:189], v[114:117]
	v_mfma_f32_16x16x32_bf16 v[110:113], v[146:149], v[194:197], v[110:113]
	v_mfma_f32_16x16x32_bf16 v[106:109], v[154:157], v[194:197], v[106:109]
	v_mfma_f32_16x16x32_bf16 v[102:105], v[146:149], v[202:205], v[102:105]
	v_mfma_f32_16x16x32_bf16 v[98:101], v[154:157], v[202:205], v[98:101]
	v_mfma_f32_16x16x32_bf16 v[122:125], v[150:153], v[182:185], v[122:125]
	v_mfma_f32_16x16x32_bf16 v[126:129], v[158:161], v[182:185], v[126:129]
	v_mfma_f32_16x16x32_bf16 v[118:121], v[150:153], v[190:193], v[118:121]
	v_mfma_f32_16x16x32_bf16 v[114:117], v[158:161], v[190:193], v[114:117]
	v_mfma_f32_16x16x32_bf16 v[110:113], v[150:153], v[198:201], v[110:113]
	v_mfma_f32_16x16x32_bf16 v[106:109], v[158:161], v[198:201], v[106:109]
	v_mfma_f32_16x16x32_bf16 v[102:105], v[150:153], v[214:217], v[102:105]
	v_mfma_f32_16x16x32_bf16 v[98:101], v[158:161], v[214:217], v[98:101]
	v_mfma_f32_16x16x32_bf16 v[62:65], v[162:165], v[178:181], v[62:65]
	v_mfma_f32_16x16x32_bf16 v[58:61], v[170:173], v[178:181], v[58:61]
	v_mfma_f32_16x16x32_bf16 v[54:57], v[162:165], v[186:189], v[54:57]
	v_mfma_f32_16x16x32_bf16 v[50:53], v[170:173], v[186:189], v[50:53]
	v_mfma_f32_16x16x32_bf16 v[46:49], v[162:165], v[194:197], v[46:49]
	v_mfma_f32_16x16x32_bf16 v[42:45], v[170:173], v[194:197], v[42:45]
	v_mfma_f32_16x16x32_bf16 v[38:41], v[162:165], v[202:205], v[38:41]
	v_mfma_f32_16x16x32_bf16 v[34:37], v[170:173], v[202:205], v[34:37]
	v_mfma_f32_16x16x32_bf16 v[62:65], v[166:169], v[182:185], v[62:65]
	v_mfma_f32_16x16x32_bf16 v[58:61], v[174:177], v[182:185], v[58:61]
	v_mfma_f32_16x16x32_bf16 v[54:57], v[166:169], v[190:193], v[54:57]
	v_mfma_f32_16x16x32_bf16 v[50:53], v[174:177], v[190:193], v[50:53]
	v_mfma_f32_16x16x32_bf16 v[46:49], v[166:169], v[198:201], v[46:49]
	v_mfma_f32_16x16x32_bf16 v[42:45], v[174:177], v[198:201], v[42:45]
	v_mfma_f32_16x16x32_bf16 v[38:41], v[166:169], v[214:217], v[38:41]
	v_mfma_f32_16x16x32_bf16 v[34:37], v[174:177], v[214:217], v[34:37]
	s_barrier
	s_add_i32 s20, s31, s22
	v_lshl_add_u64 v[218:219], v[218:219], 0, s[60:61]
	s_mov_b32 m0, s20
	ds_read_b128 v[178:181], v144 offset:49152
	ds_read_b128 v[182:185], v144 offset:50176
	ds_read_b128 v[186:189], v144 offset:51200
	ds_read_b128 v[190:193], v144 offset:52224
	ds_read_b128 v[194:197], v144 offset:53248
	ds_read_b128 v[198:201], v144 offset:54272
	ds_read_b128 v[202:205], v144 offset:55296
	ds_read_b128 v[214:217], v144 offset:56320
	global_load_lds_dwordx4 v[218:219], off
	v_lshl_add_u64 v[218:219], v[220:221], 0, s[60:61]
	s_add_i32 m0, s20, 0x2000
	s_add_i32 s20, s62, s22
	global_load_lds_dwordx4 v[218:219], off
	v_lshl_add_u64 v[218:219], v[222:223], 0, s[60:61]
	s_mov_b32 m0, s20
	s_nop 0
	global_load_lds_dwordx4 v[218:219], off
	v_lshl_add_u64 v[218:219], v[224:225], 0, s[60:61]
	s_add_i32 m0, s20, 0x2000
	s_nop 0
	global_load_lds_dwordx4 v[218:219], off
	v_lshl_add_u64 v[218:219], v[226:227], 0, s[60:61]
	s_mov_b32 m0, s57
	s_nop 0
	global_load_lds_dwordx4 v[218:219], off
	v_lshl_add_u64 v[218:219], v[236:237], 0, s[60:61]
	s_mov_b32 m0, s65
	s_nop 0
	global_load_lds_dwordx4 v[218:219], off
	s_waitcnt vmcnt(8)
	s_waitcnt lgkmcnt(0)
	s_barrier
	s_waitcnt lgkmcnt(0)
	v_mfma_f32_16x16x32_bf16 v[94:97], v[146:149], v[178:181], v[94:97]
	v_mfma_f32_16x16x32_bf16 v[90:93], v[154:157], v[178:181], v[90:93]
	v_mfma_f32_16x16x32_bf16 v[86:89], v[146:149], v[186:189], v[86:89]
	v_mfma_f32_16x16x32_bf16 v[82:85], v[154:157], v[186:189], v[82:85]
	v_mfma_f32_16x16x32_bf16 v[78:81], v[146:149], v[194:197], v[78:81]
	v_mfma_f32_16x16x32_bf16 v[74:77], v[154:157], v[194:197], v[74:77]
	v_mfma_f32_16x16x32_bf16 v[70:73], v[146:149], v[202:205], v[70:73]
	v_mfma_f32_16x16x32_bf16 v[66:69], v[154:157], v[202:205], v[66:69]
	v_mfma_f32_16x16x32_bf16 v[94:97], v[150:153], v[182:185], v[94:97]
	v_mfma_f32_16x16x32_bf16 v[90:93], v[158:161], v[182:185], v[90:93]
	v_mfma_f32_16x16x32_bf16 v[86:89], v[150:153], v[190:193], v[86:89]
	v_mfma_f32_16x16x32_bf16 v[82:85], v[158:161], v[190:193], v[82:85]
	v_mfma_f32_16x16x32_bf16 v[78:81], v[150:153], v[198:201], v[78:81]
	v_mfma_f32_16x16x32_bf16 v[74:77], v[158:161], v[198:201], v[74:77]
	v_mfma_f32_16x16x32_bf16 v[70:73], v[150:153], v[214:217], v[70:73]
	v_mfma_f32_16x16x32_bf16 v[66:69], v[158:161], v[214:217], v[66:69]
	v_mfma_f32_16x16x32_bf16 v[30:33], v[162:165], v[178:181], v[30:33]
	v_mfma_f32_16x16x32_bf16 v[26:29], v[170:173], v[178:181], v[26:29]
	v_mfma_f32_16x16x32_bf16 v[22:25], v[162:165], v[186:189], v[22:25]
	v_mfma_f32_16x16x32_bf16 v[18:21], v[170:173], v[186:189], v[18:21]
	v_mfma_f32_16x16x32_bf16 v[14:17], v[162:165], v[194:197], v[14:17]
	v_mfma_f32_16x16x32_bf16 v[10:13], v[170:173], v[194:197], v[10:13]
	v_mfma_f32_16x16x32_bf16 v[6:9], v[162:165], v[202:205], v[6:9]
	v_mfma_f32_16x16x32_bf16 v[2:5], v[170:173], v[202:205], v[2:5]
	v_mfma_f32_16x16x32_bf16 v[30:33], v[166:169], v[182:185], v[30:33]
	v_mfma_f32_16x16x32_bf16 v[26:29], v[174:177], v[182:185], v[26:29]
	v_mfma_f32_16x16x32_bf16 v[22:25], v[166:169], v[190:193], v[22:25]
	v_mfma_f32_16x16x32_bf16 v[18:21], v[174:177], v[190:193], v[18:21]
	v_mfma_f32_16x16x32_bf16 v[14:17], v[166:169], v[198:201], v[14:17]
	v_mfma_f32_16x16x32_bf16 v[10:13], v[174:177], v[198:201], v[10:13]
	v_mfma_f32_16x16x32_bf16 v[6:9], v[166:169], v[214:217], v[6:9]
	v_mfma_f32_16x16x32_bf16 v[2:5], v[174:177], v[214:217], v[2:5]
	s_barrier
	s_add_u32 s18, s18, 0x100
	s_addc_u32 s19, s19, 0
	s_add_u32 s71, s71, 0x100
	s_addc_u32 s72, s72, 0
	s_cmp_ge_i32 s73, s10
	s_mov_b32 s20, s73
	s_cbranch_scc0 .LBB0_492

.Lzgo_5:
	s_add_u32 s18, s18, 0x80
	s_addc_u32 s19, s19, 0
	s_add_u32 s71, s20, 0x100
	s_addc_u32 s72, s21, 0
	s_mov_b32 s20, 0
	s_add_i32 s73, s20, 2
	s_add_u32 s31, s18, 0x80
	s_addc_u32 s21, s19, 0
	s_add_i32 s74, 0, 0x10000
	s_cmp_eq_u32 s67, s20
	s_cselect_b32 s21, s3, s21
	s_cselect_b32 s20, s2, s31
	v_add_u32_e32 v149, s74, v146
	s_cselect_b32 s63, s17, s72
	s_cselect_b32 s62, s16, s71
	s_add_i32 s31, 0, 0x14000
	ds_read_b128 v[130:133], v149
	ds_read_b128 v[142:145], v149 offset:1024
	ds_read_b128 v[150:153], v149 offset:2048
	ds_read_b128 v[154:157], v149 offset:3072
	v_add_u32_e32 v149, s31, v146
	ds_read_b128 v[158:161], v149
	ds_read_b128 v[162:165], v149 offset:1024
	ds_read_b128 v[166:169], v149 offset:2048
	ds_read_b128 v[170:173], v149 offset:3072
	v_lshl_add_u64 v[214:215], s[18:19], 0, v[138:139]
	s_add_i32 m0, s23, 0xc000
	ds_read_b128 v[174:177], v148
	ds_read_b128 v[178:181], v148 offset:1024
	ds_read_b128 v[182:185], v148 offset:2048
	ds_read_b128 v[186:189], v148 offset:3072
	ds_read_b128 v[190:193], v148 offset:4096
	ds_read_b128 v[194:197], v148 offset:5120
	ds_read_b128 v[198:201], v148 offset:6144
	ds_read_b128 v[202:205], v148 offset:7168
	global_load_lds_dwordx4 v[214:215], off
	v_lshl_add_u64 v[214:215], s[18:19], 0, v[140:141]
	s_add_i32 m0, s23, 0xe000
	s_nop 0
	global_load_lds_dwordx4 v[214:215], off
	s_waitcnt vmcnt(8)
	s_waitcnt lgkmcnt(0)
	s_barrier
	s_waitcnt lgkmcnt(0)
	v_mfma_f32_16x16x32_bf16 v[126:129], v[130:133], v[174:177], 0
	v_mfma_f32_16x16x32_bf16 v[94:97], v[150:153], v[174:177], 0
	v_mfma_f32_16x16x32_bf16 v[122:125], v[130:133], v[182:185], 0
	v_mfma_f32_16x16x32_bf16 v[90:93], v[150:153], v[182:185], 0
	v_mfma_f32_16x16x32_bf16 v[118:121], v[130:133], v[190:193], 0
	v_mfma_f32_16x16x32_bf16 v[86:89], v[150:153], v[190:193], 0
	v_mfma_f32_16x16x32_bf16 v[114:117], v[130:133], v[198:201], 0
	v_mfma_f32_16x16x32_bf16 v[82:85], v[150:153], v[198:201], 0
	v_mfma_f32_16x16x32_bf16 v[126:129], v[142:145], v[178:181], v[126:129]
	v_mfma_f32_16x16x32_bf16 v[94:97], v[154:157], v[178:181], v[94:97]
	v_mfma_f32_16x16x32_bf16 v[122:125], v[142:145], v[186:189], v[122:125]
	v_mfma_f32_16x16x32_bf16 v[90:93], v[154:157], v[186:189], v[90:93]
	v_mfma_f32_16x16x32_bf16 v[118:121], v[142:145], v[194:197], v[118:121]
	v_mfma_f32_16x16x32_bf16 v[86:89], v[154:157], v[194:197], v[86:89]
	v_mfma_f32_16x16x32_bf16 v[114:117], v[142:145], v[202:205], v[114:117]
	v_mfma_f32_16x16x32_bf16 v[82:85], v[154:157], v[202:205], v[82:85]
	v_mfma_f32_16x16x32_bf16 v[62:65], v[158:161], v[174:177], 0
	v_mfma_f32_16x16x32_bf16 v[30:33], v[166:169], v[174:177], 0
	v_mfma_f32_16x16x32_bf16 v[58:61], v[158:161], v[182:185], 0
	v_mfma_f32_16x16x32_bf16 v[26:29], v[166:169], v[182:185], 0
	v_mfma_f32_16x16x32_bf16 v[54:57], v[158:161], v[190:193], 0
	v_mfma_f32_16x16x32_bf16 v[22:25], v[166:169], v[190:193], 0
	v_mfma_f32_16x16x32_bf16 v[50:53], v[158:161], v[198:201], 0
	v_mfma_f32_16x16x32_bf16 v[18:21], v[166:169], v[198:201], 0
	v_mfma_f32_16x16x32_bf16 v[62:65], v[162:165], v[178:181], v[62:65]
	v_mfma_f32_16x16x32_bf16 v[30:33], v[170:173], v[178:181], v[30:33]
	v_mfma_f32_16x16x32_bf16 v[58:61], v[162:165], v[186:189], v[58:61]
	v_mfma_f32_16x16x32_bf16 v[26:29], v[170:173], v[186:189], v[26:29]
	v_mfma_f32_16x16x32_bf16 v[54:57], v[162:165], v[194:197], v[54:57]
	v_mfma_f32_16x16x32_bf16 v[22:25], v[170:173], v[194:197], v[22:25]
	v_mfma_f32_16x16x32_bf16 v[50:53], v[162:165], v[202:205], v[50:53]
	v_mfma_f32_16x16x32_bf16 v[18:21], v[170:173], v[202:205], v[18:21]
	s_barrier
	s_add_i32 s74, s74, s22
	v_lshl_add_u64 v[214:215], s[62:63], 0, v[136:137]
	s_mov_b32 m0, s74
	ds_read_b128 v[174:177], v148 offset:16384
	ds_read_b128 v[178:181], v148 offset:17408
	ds_read_b128 v[182:185], v148 offset:18432
	ds_read_b128 v[186:189], v148 offset:19456
	ds_read_b128 v[190:193], v148 offset:20480
	ds_read_b128 v[194:197], v148 offset:21504
	ds_read_b128 v[198:201], v148 offset:22528
	ds_read_b128 v[202:205], v148 offset:23552
	global_load_lds_dwordx4 v[214:215], off
	s_add_i32 m0, s74, 0x2000
	v_lshl_add_u64 v[216:217], s[62:63], 0, v[134:135]
	s_add_u32 s62, s62, s4
	s_addc_u32 s63, s63, s5
	s_add_i32 s31, s31, s22
	global_load_lds_dwordx4 v[216:217], off
	v_lshl_add_u64 v[218:219], s[62:63], 0, v[136:137]
	s_mov_b32 m0, s31
	v_lshl_add_u64 v[220:221], s[62:63], 0, v[134:135]
	global_load_lds_dwordx4 v[218:219], off
	s_add_i32 m0, s31, 0x2000
	v_lshl_add_u64 v[222:223], s[20:21], 0, v[136:137]
	global_load_lds_dwordx4 v[220:221], off
	s_mov_b32 m0, s23
	v_lshl_add_u64 v[224:225], s[20:21], 0, v[134:135]
	global_load_lds_dwordx4 v[222:223], off
	s_mov_b32 m0, s52
	s_nop 0
	global_load_lds_dwordx4 v[224:225], off
	s_waitcnt vmcnt(8)
	s_waitcnt lgkmcnt(0)
	s_barrier
	s_waitcnt lgkmcnt(0)
	v_mfma_f32_16x16x32_bf16 v[110:113], v[130:133], v[174:177], 0
	v_mfma_f32_16x16x32_bf16 v[78:81], v[150:153], v[174:177], 0
	v_mfma_f32_16x16x32_bf16 v[106:109], v[130:133], v[182:185], 0
	v_mfma_f32_16x16x32_bf16 v[74:77], v[150:153], v[182:185], 0
	v_mfma_f32_16x16x32_bf16 v[102:105], v[130:133], v[190:193], 0
	v_mfma_f32_16x16x32_bf16 v[70:73], v[150:153], v[190:193], 0
	v_mfma_f32_16x16x32_bf16 v[98:101], v[130:133], v[198:201], 0
	v_mfma_f32_16x16x32_bf16 v[66:69], v[150:153], v[198:201], 0
	v_mfma_f32_16x16x32_bf16 v[110:113], v[142:145], v[178:181], v[110:113]
	v_mfma_f32_16x16x32_bf16 v[78:81], v[154:157], v[178:181], v[78:81]
	v_mfma_f32_16x16x32_bf16 v[106:109], v[142:145], v[186:189], v[106:109]
	v_mfma_f32_16x16x32_bf16 v[74:77], v[154:157], v[186:189], v[74:77]
	v_mfma_f32_16x16x32_bf16 v[102:105], v[142:145], v[194:197], v[102:105]
	v_mfma_f32_16x16x32_bf16 v[70:73], v[154:157], v[194:197], v[70:73]
	v_mfma_f32_16x16x32_bf16 v[98:101], v[142:145], v[202:205], v[98:101]
	v_mfma_f32_16x16x32_bf16 v[66:69], v[154:157], v[202:205], v[66:69]
	v_mfma_f32_16x16x32_bf16 v[46:49], v[158:161], v[174:177], 0
	v_mfma_f32_16x16x32_bf16 v[14:17], v[166:169], v[174:177], 0
	v_mfma_f32_16x16x32_bf16 v[42:45], v[158:161], v[182:185], 0
	v_mfma_f32_16x16x32_bf16 v[10:13], v[166:169], v[182:185], 0
	v_mfma_f32_16x16x32_bf16 v[38:41], v[158:161], v[190:193], 0
	v_mfma_f32_16x16x32_bf16 v[6:9], v[166:169], v[190:193], 0
	v_mfma_f32_16x16x32_bf16 v[34:37], v[158:161], v[198:201], 0
	v_mfma_f32_16x16x32_bf16 v[2:5], v[166:169], v[198:201], 0
	v_mfma_f32_16x16x32_bf16 v[46:49], v[162:165], v[178:181], v[46:49]
	v_mfma_f32_16x16x32_bf16 v[14:17], v[170:173], v[178:181], v[14:17]
	v_mfma_f32_16x16x32_bf16 v[42:45], v[162:165], v[186:189], v[42:45]
	v_mfma_f32_16x16x32_bf16 v[10:13], v[170:173], v[186:189], v[10:13]
	v_mfma_f32_16x16x32_bf16 v[38:41], v[162:165], v[194:197], v[38:41]
	v_mfma_f32_16x16x32_bf16 v[6:9], v[170:173], v[194:197], v[6:9]
	v_mfma_f32_16x16x32_bf16 v[34:37], v[162:165], v[202:205], v[34:37]
	v_mfma_f32_16x16x32_bf16 v[2:5], v[170:173], v[202:205], v[2:5]
	s_barrier
	s_add_i32 s31, 0, 0x18000
	v_add_u32_e32 v149, s31, v146
	s_add_i32 s62, 0, 0x1c000
	ds_read_b128 v[130:133], v149
	ds_read_b128 v[142:145], v149 offset:1024
	ds_read_b128 v[150:153], v149 offset:2048
	ds_read_b128 v[154:157], v149 offset:3072
	v_add_u32_e32 v149, s62, v146
	ds_read_b128 v[158:161], v149
	ds_read_b128 v[162:165], v149 offset:1024
	ds_read_b128 v[166:169], v149 offset:2048
	ds_read_b128 v[170:173], v149 offset:3072
	s_add_u32 s20, s20, s4
	s_addc_u32 s21, s21, s5
	s_mov_b32 m0, s53
	v_lshl_add_u64 v[226:227], s[20:21], 0, v[136:137]
	ds_read_b128 v[174:177], v148 offset:32768
	ds_read_b128 v[178:181], v148 offset:33792
	ds_read_b128 v[182:185], v148 offset:34816
	ds_read_b128 v[186:189], v148 offset:35840
	ds_read_b128 v[190:193], v148 offset:36864
	ds_read_b128 v[194:197], v148 offset:37888
	ds_read_b128 v[198:201], v148 offset:38912
	ds_read_b128 v[202:205], v148 offset:39936
	global_load_lds_dwordx4 v[226:227], off
	v_lshl_add_u64 v[226:227], s[20:21], 0, v[134:135]
	s_mov_b32 m0, s56
	s_nop 0
	global_load_lds_dwordx4 v[226:227], off
	s_waitcnt vmcnt(8)
	s_waitcnt lgkmcnt(0)
	s_barrier
	s_waitcnt lgkmcnt(0)
	v_mfma_f32_16x16x32_bf16 v[126:129], v[130:133], v[174:177], v[126:129]
	v_mfma_f32_16x16x32_bf16 v[94:97], v[150:153], v[174:177], v[94:97]
	v_mfma_f32_16x16x32_bf16 v[122:125], v[130:133], v[182:185], v[122:125]
	v_mfma_f32_16x16x32_bf16 v[90:93], v[150:153], v[182:185], v[90:93]
	v_mfma_f32_16x16x32_bf16 v[118:121], v[130:133], v[190:193], v[118:121]
	v_mfma_f32_16x16x32_bf16 v[86:89], v[150:153], v[190:193], v[86:89]
	v_mfma_f32_16x16x32_bf16 v[114:117], v[130:133], v[198:201], v[114:117]
	v_mfma_f32_16x16x32_bf16 v[82:85], v[150:153], v[198:201], v[82:85]
	v_mfma_f32_16x16x32_bf16 v[126:129], v[142:145], v[178:181], v[126:129]
	v_mfma_f32_16x16x32_bf16 v[94:97], v[154:157], v[178:181], v[94:97]
	v_mfma_f32_16x16x32_bf16 v[122:125], v[142:145], v[186:189], v[122:125]
	v_mfma_f32_16x16x32_bf16 v[90:93], v[154:157], v[186:189], v[90:93]
	v_mfma_f32_16x16x32_bf16 v[118:121], v[142:145], v[194:197], v[118:121]
	v_mfma_f32_16x16x32_bf16 v[86:89], v[154:157], v[194:197], v[86:89]
	v_mfma_f32_16x16x32_bf16 v[114:117], v[142:145], v[202:205], v[114:117]
	v_mfma_f32_16x16x32_bf16 v[82:85], v[154:157], v[202:205], v[82:85]
	v_mfma_f32_16x16x32_bf16 v[62:65], v[158:161], v[174:177], v[62:65]
	v_mfma_f32_16x16x32_bf16 v[30:33], v[166:169], v[174:177], v[30:33]
	v_mfma_f32_16x16x32_bf16 v[58:61], v[158:161], v[182:185], v[58:61]
	v_mfma_f32_16x16x32_bf16 v[26:29], v[166:169], v[182:185], v[26:29]
	v_mfma_f32_16x16x32_bf16 v[54:57], v[158:161], v[190:193], v[54:57]
	v_mfma_f32_16x16x32_bf16 v[22:25], v[166:169], v[190:193], v[22:25]
	v_mfma_f32_16x16x32_bf16 v[50:53], v[158:161], v[198:201], v[50:53]
	v_mfma_f32_16x16x32_bf16 v[18:21], v[166:169], v[198:201], v[18:21]
	v_mfma_f32_16x16x32_bf16 v[62:65], v[162:165], v[178:181], v[62:65]
	v_mfma_f32_16x16x32_bf16 v[30:33], v[170:173], v[178:181], v[30:33]
	v_mfma_f32_16x16x32_bf16 v[58:61], v[162:165], v[186:189], v[58:61]
	v_mfma_f32_16x16x32_bf16 v[26:29], v[170:173], v[186:189], v[26:29]
	v_mfma_f32_16x16x32_bf16 v[54:57], v[162:165], v[194:197], v[54:57]
	v_mfma_f32_16x16x32_bf16 v[22:25], v[170:173], v[194:197], v[22:25]
	v_mfma_f32_16x16x32_bf16 v[50:53], v[162:165], v[202:205], v[50:53]
	v_mfma_f32_16x16x32_bf16 v[18:21], v[170:173], v[202:205], v[18:21]
	s_barrier
	s_add_i32 s20, s31, s22
	v_lshl_add_u64 v[214:215], v[214:215], 0, s[60:61]
	s_mov_b32 m0, s20
	ds_read_b128 v[174:177], v148 offset:49152
	ds_read_b128 v[178:181], v148 offset:50176
	ds_read_b128 v[182:185], v148 offset:51200
	ds_read_b128 v[186:189], v148 offset:52224
	ds_read_b128 v[190:193], v148 offset:53248
	ds_read_b128 v[194:197], v148 offset:54272
	ds_read_b128 v[198:201], v148 offset:55296
	ds_read_b128 v[202:205], v148 offset:56320
	global_load_lds_dwordx4 v[214:215], off
	v_lshl_add_u64 v[214:215], v[216:217], 0, s[60:61]
	s_add_i32 m0, s20, 0x2000
	s_add_i32 s20, s62, s22
	global_load_lds_dwordx4 v[214:215], off
	v_lshl_add_u64 v[214:215], v[218:219], 0, s[60:61]
	s_mov_b32 m0, s20
	s_nop 0
	global_load_lds_dwordx4 v[214:215], off
	v_lshl_add_u64 v[214:215], v[220:221], 0, s[60:61]
	s_add_i32 m0, s20, 0x2000
	s_nop 0
	global_load_lds_dwordx4 v[214:215], off
	v_lshl_add_u64 v[214:215], v[222:223], 0, s[60:61]
	s_mov_b32 m0, s57
	s_nop 0
	global_load_lds_dwordx4 v[214:215], off
	v_lshl_add_u64 v[214:215], v[224:225], 0, s[60:61]
	s_mov_b32 m0, s65
	s_nop 0
	global_load_lds_dwordx4 v[214:215], off
	s_waitcnt vmcnt(8)
	s_waitcnt lgkmcnt(0)
	s_barrier
	s_waitcnt lgkmcnt(0)
	v_mfma_f32_16x16x32_bf16 v[110:113], v[130:133], v[174:177], v[110:113]
	v_mfma_f32_16x16x32_bf16 v[78:81], v[150:153], v[174:177], v[78:81]
	v_mfma_f32_16x16x32_bf16 v[106:109], v[130:133], v[182:185], v[106:109]
	v_mfma_f32_16x16x32_bf16 v[74:77], v[150:153], v[182:185], v[74:77]
	v_mfma_f32_16x16x32_bf16 v[102:105], v[130:133], v[190:193], v[102:105]
	v_mfma_f32_16x16x32_bf16 v[70:73], v[150:153], v[190:193], v[70:73]
	v_mfma_f32_16x16x32_bf16 v[98:101], v[130:133], v[198:201], v[98:101]
	v_mfma_f32_16x16x32_bf16 v[66:69], v[150:153], v[198:201], v[66:69]
	v_mfma_f32_16x16x32_bf16 v[110:113], v[142:145], v[178:181], v[110:113]
	v_mfma_f32_16x16x32_bf16 v[78:81], v[154:157], v[178:181], v[78:81]
	v_mfma_f32_16x16x32_bf16 v[106:109], v[142:145], v[186:189], v[106:109]
	v_mfma_f32_16x16x32_bf16 v[74:77], v[154:157], v[186:189], v[74:77]
	v_mfma_f32_16x16x32_bf16 v[102:105], v[142:145], v[194:197], v[102:105]
	v_mfma_f32_16x16x32_bf16 v[70:73], v[154:157], v[194:197], v[70:73]
	v_mfma_f32_16x16x32_bf16 v[98:101], v[142:145], v[202:205], v[98:101]
	v_mfma_f32_16x16x32_bf16 v[66:69], v[154:157], v[202:205], v[66:69]
	v_mfma_f32_16x16x32_bf16 v[46:49], v[158:161], v[174:177], v[46:49]
	v_mfma_f32_16x16x32_bf16 v[14:17], v[166:169], v[174:177], v[14:17]
	v_mfma_f32_16x16x32_bf16 v[42:45], v[158:161], v[182:185], v[42:45]
	v_mfma_f32_16x16x32_bf16 v[10:13], v[166:169], v[182:185], v[10:13]
	v_mfma_f32_16x16x32_bf16 v[38:41], v[158:161], v[190:193], v[38:41]
	v_mfma_f32_16x16x32_bf16 v[6:9], v[166:169], v[190:193], v[6:9]
	v_mfma_f32_16x16x32_bf16 v[34:37], v[158:161], v[198:201], v[34:37]
	v_mfma_f32_16x16x32_bf16 v[2:5], v[166:169], v[198:201], v[2:5]
	v_mfma_f32_16x16x32_bf16 v[46:49], v[162:165], v[178:181], v[46:49]
	v_mfma_f32_16x16x32_bf16 v[14:17], v[170:173], v[178:181], v[14:17]
	v_mfma_f32_16x16x32_bf16 v[42:45], v[162:165], v[186:189], v[42:45]
	v_mfma_f32_16x16x32_bf16 v[10:13], v[170:173], v[186:189], v[10:13]
	v_mfma_f32_16x16x32_bf16 v[38:41], v[162:165], v[194:197], v[38:41]
	v_mfma_f32_16x16x32_bf16 v[6:9], v[170:173], v[194:197], v[6:9]
	v_mfma_f32_16x16x32_bf16 v[34:37], v[162:165], v[202:205], v[34:37]
	v_mfma_f32_16x16x32_bf16 v[2:5], v[170:173], v[202:205], v[2:5]
	s_barrier
	s_add_u32 s18, s18, 0x100
	s_addc_u32 s19, s19, 0
	s_add_u32 s71, s71, 0x100
	s_addc_u32 s72, s72, 0
	s_cmp_ge_i32 s73, s66
	s_mov_b32 s20, s73
	s_cbranch_scc1 .LBB0_1013
.LBB0_1012:
	s_add_i32 s73, s20, 2
	s_add_u32 s31, s18, 0x80
	s_addc_u32 s21, s19, 0
	s_add_i32 s74, 0, 0x10000
	s_cmp_eq_u32 s67, s20
	s_cselect_b32 s21, s3, s21
	s_cselect_b32 s20, s2, s31
	v_add_u32_e32 v149, s74, v146
	s_cselect_b32 s63, s17, s72
	s_cselect_b32 s62, s16, s71
	s_add_i32 s31, 0, 0x14000
	ds_read_b128 v[130:133], v149
	ds_read_b128 v[142:145], v149 offset:1024
	ds_read_b128 v[150:153], v149 offset:2048
	ds_read_b128 v[154:157], v149 offset:3072
	v_add_u32_e32 v149, s31, v146
	ds_read_b128 v[158:161], v149
	ds_read_b128 v[162:165], v149 offset:1024
	ds_read_b128 v[166:169], v149 offset:2048
	ds_read_b128 v[170:173], v149 offset:3072
	v_lshl_add_u64 v[214:215], s[18:19], 0, v[138:139]
	s_add_i32 m0, s23, 0xc000
	ds_read_b128 v[174:177], v148
	ds_read_b128 v[178:181], v148 offset:1024
	ds_read_b128 v[182:185], v148 offset:2048
	ds_read_b128 v[186:189], v148 offset:3072
	ds_read_b128 v[190:193], v148 offset:4096
	ds_read_b128 v[194:197], v148 offset:5120
	ds_read_b128 v[198:201], v148 offset:6144
	ds_read_b128 v[202:205], v148 offset:7168
	global_load_lds_dwordx4 v[214:215], off
	v_lshl_add_u64 v[214:215], s[18:19], 0, v[140:141]
	s_add_i32 m0, s23, 0xe000
	s_nop 0
	global_load_lds_dwordx4 v[214:215], off
	s_waitcnt vmcnt(8)
	s_waitcnt lgkmcnt(0)
	s_barrier
	s_waitcnt lgkmcnt(0)
	v_mfma_f32_16x16x32_bf16 v[126:129], v[130:133], v[174:177], v[126:129]
	v_mfma_f32_16x16x32_bf16 v[94:97], v[150:153], v[174:177], v[94:97]
	v_mfma_f32_16x16x32_bf16 v[122:125], v[130:133], v[182:185], v[122:125]
	v_mfma_f32_16x16x32_bf16 v[90:93], v[150:153], v[182:185], v[90:93]
	v_mfma_f32_16x16x32_bf16 v[118:121], v[130:133], v[190:193], v[118:121]
	v_mfma_f32_16x16x32_bf16 v[86:89], v[150:153], v[190:193], v[86:89]
	v_mfma_f32_16x16x32_bf16 v[114:117], v[130:133], v[198:201], v[114:117]
	v_mfma_f32_16x16x32_bf16 v[82:85], v[150:153], v[198:201], v[82:85]
	v_mfma_f32_16x16x32_bf16 v[126:129], v[142:145], v[178:181], v[126:129]
	v_mfma_f32_16x16x32_bf16 v[94:97], v[154:157], v[178:181], v[94:97]
	v_mfma_f32_16x16x32_bf16 v[122:125], v[142:145], v[186:189], v[122:125]
	v_mfma_f32_16x16x32_bf16 v[90:93], v[154:157], v[186:189], v[90:93]
	v_mfma_f32_16x16x32_bf16 v[118:121], v[142:145], v[194:197], v[118:121]
	v_mfma_f32_16x16x32_bf16 v[86:89], v[154:157], v[194:197], v[86:89]
	v_mfma_f32_16x16x32_bf16 v[114:117], v[142:145], v[202:205], v[114:117]
	v_mfma_f32_16x16x32_bf16 v[82:85], v[154:157], v[202:205], v[82:85]
	v_mfma_f32_16x16x32_bf16 v[62:65], v[158:161], v[174:177], v[62:65]
	v_mfma_f32_16x16x32_bf16 v[30:33], v[166:169], v[174:177], v[30:33]
	v_mfma_f32_16x16x32_bf16 v[58:61], v[158:161], v[182:185], v[58:61]
	v_mfma_f32_16x16x32_bf16 v[26:29], v[166:169], v[182:185], v[26:29]
	v_mfma_f32_16x16x32_bf16 v[54:57], v[158:161], v[190:193], v[54:57]
	v_mfma_f32_16x16x32_bf16 v[22:25], v[166:169], v[190:193], v[22:25]
	v_mfma_f32_16x16x32_bf16 v[50:53], v[158:161], v[198:201], v[50:53]
	v_mfma_f32_16x16x32_bf16 v[18:21], v[166:169], v[198:201], v[18:21]
	v_mfma_f32_16x16x32_bf16 v[62:65], v[162:165], v[178:181], v[62:65]
	v_mfma_f32_16x16x32_bf16 v[30:33], v[170:173], v[178:181], v[30:33]
	v_mfma_f32_16x16x32_bf16 v[58:61], v[162:165], v[186:189], v[58:61]
	v_mfma_f32_16x16x32_bf16 v[26:29], v[170:173], v[186:189], v[26:29]
	v_mfma_f32_16x16x32_bf16 v[54:57], v[162:165], v[194:197], v[54:57]
	v_mfma_f32_16x16x32_bf16 v[22:25], v[170:173], v[194:197], v[22:25]
	v_mfma_f32_16x16x32_bf16 v[50:53], v[162:165], v[202:205], v[50:53]
	v_mfma_f32_16x16x32_bf16 v[18:21], v[170:173], v[202:205], v[18:21]
	s_barrier
	s_add_i32 s74, s74, s22
	v_lshl_add_u64 v[214:215], s[62:63], 0, v[136:137]
	s_mov_b32 m0, s74
	ds_read_b128 v[174:177], v148 offset:16384
	ds_read_b128 v[178:181], v148 offset:17408
	ds_read_b128 v[182:185], v148 offset:18432
	ds_read_b128 v[186:189], v148 offset:19456
	ds_read_b128 v[190:193], v148 offset:20480
	ds_read_b128 v[194:197], v148 offset:21504
	ds_read_b128 v[198:201], v148 offset:22528
	ds_read_b128 v[202:205], v148 offset:23552
	global_load_lds_dwordx4 v[214:215], off
	s_add_i32 m0, s74, 0x2000
	v_lshl_add_u64 v[216:217], s[62:63], 0, v[134:135]
	s_add_u32 s62, s62, s4
	s_addc_u32 s63, s63, s5
	s_add_i32 s31, s31, s22
	global_load_lds_dwordx4 v[216:217], off
	v_lshl_add_u64 v[218:219], s[62:63], 0, v[136:137]
	s_mov_b32 m0, s31
	v_lshl_add_u64 v[220:221], s[62:63], 0, v[134:135]
	global_load_lds_dwordx4 v[218:219], off
	s_add_i32 m0, s31, 0x2000
	v_lshl_add_u64 v[222:223], s[20:21], 0, v[136:137]
	global_load_lds_dwordx4 v[220:221], off
	s_mov_b32 m0, s23
	v_lshl_add_u64 v[224:225], s[20:21], 0, v[134:135]
	global_load_lds_dwordx4 v[222:223], off
	s_mov_b32 m0, s52
	s_nop 0
	global_load_lds_dwordx4 v[224:225], off
	s_waitcnt vmcnt(8)
	s_waitcnt lgkmcnt(0)
	s_barrier
	s_waitcnt lgkmcnt(0)
	v_mfma_f32_16x16x32_bf16 v[110:113], v[130:133], v[174:177], v[110:113]
	v_mfma_f32_16x16x32_bf16 v[78:81], v[150:153], v[174:177], v[78:81]
	v_mfma_f32_16x16x32_bf16 v[106:109], v[130:133], v[182:185], v[106:109]
	v_mfma_f32_16x16x32_bf16 v[74:77], v[150:153], v[182:185], v[74:77]
	v_mfma_f32_16x16x32_bf16 v[102:105], v[130:133], v[190:193], v[102:105]
	v_mfma_f32_16x16x32_bf16 v[70:73], v[150:153], v[190:193], v[70:73]
	v_mfma_f32_16x16x32_bf16 v[98:101], v[130:133], v[198:201], v[98:101]
	v_mfma_f32_16x16x32_bf16 v[66:69], v[150:153], v[198:201], v[66:69]
	v_mfma_f32_16x16x32_bf16 v[110:113], v[142:145], v[178:181], v[110:113]
	v_mfma_f32_16x16x32_bf16 v[78:81], v[154:157], v[178:181], v[78:81]
	v_mfma_f32_16x16x32_bf16 v[106:109], v[142:145], v[186:189], v[106:109]
	v_mfma_f32_16x16x32_bf16 v[74:77], v[154:157], v[186:189], v[74:77]
	v_mfma_f32_16x16x32_bf16 v[102:105], v[142:145], v[194:197], v[102:105]
	v_mfma_f32_16x16x32_bf16 v[70:73], v[154:157], v[194:197], v[70:73]
	v_mfma_f32_16x16x32_bf16 v[98:101], v[142:145], v[202:205], v[98:101]
	v_mfma_f32_16x16x32_bf16 v[66:69], v[154:157], v[202:205], v[66:69]
	v_mfma_f32_16x16x32_bf16 v[46:49], v[158:161], v[174:177], v[46:49]
	v_mfma_f32_16x16x32_bf16 v[14:17], v[166:169], v[174:177], v[14:17]
	v_mfma_f32_16x16x32_bf16 v[42:45], v[158:161], v[182:185], v[42:45]
	v_mfma_f32_16x16x32_bf16 v[10:13], v[166:169], v[182:185], v[10:13]
	v_mfma_f32_16x16x32_bf16 v[38:41], v[158:161], v[190:193], v[38:41]
	v_mfma_f32_16x16x32_bf16 v[6:9], v[166:169], v[190:193], v[6:9]
	v_mfma_f32_16x16x32_bf16 v[34:37], v[158:161], v[198:201], v[34:37]
	v_mfma_f32_16x16x32_bf16 v[2:5], v[166:169], v[198:201], v[2:5]
	v_mfma_f32_16x16x32_bf16 v[46:49], v[162:165], v[178:181], v[46:49]
	v_mfma_f32_16x16x32_bf16 v[14:17], v[170:173], v[178:181], v[14:17]
	v_mfma_f32_16x16x32_bf16 v[42:45], v[162:165], v[186:189], v[42:45]
	v_mfma_f32_16x16x32_bf16 v[10:13], v[170:173], v[186:189], v[10:13]
	v_mfma_f32_16x16x32_bf16 v[38:41], v[162:165], v[194:197], v[38:41]
	v_mfma_f32_16x16x32_bf16 v[6:9], v[170:173], v[194:197], v[6:9]
	v_mfma_f32_16x16x32_bf16 v[34:37], v[162:165], v[202:205], v[34:37]
	v_mfma_f32_16x16x32_bf16 v[2:5], v[170:173], v[202:205], v[2:5]
	s_barrier
	s_add_i32 s31, 0, 0x18000
	v_add_u32_e32 v149, s31, v146
	s_add_i32 s62, 0, 0x1c000
	ds_read_b128 v[130:133], v149
	ds_read_b128 v[142:145], v149 offset:1024
	ds_read_b128 v[150:153], v149 offset:2048
	ds_read_b128 v[154:157], v149 offset:3072
	v_add_u32_e32 v149, s62, v146
	ds_read_b128 v[158:161], v149
	ds_read_b128 v[162:165], v149 offset:1024
	ds_read_b128 v[166:169], v149 offset:2048
	ds_read_b128 v[170:173], v149 offset:3072
	s_add_u32 s20, s20, s4
	s_addc_u32 s21, s21, s5
	s_mov_b32 m0, s53
	v_lshl_add_u64 v[226:227], s[20:21], 0, v[136:137]
	ds_read_b128 v[174:177], v148 offset:32768
	ds_read_b128 v[178:181], v148 offset:33792
	ds_read_b128 v[182:185], v148 offset:34816
	ds_read_b128 v[186:189], v148 offset:35840
	ds_read_b128 v[190:193], v148 offset:36864
	ds_read_b128 v[194:197], v148 offset:37888
	ds_read_b128 v[198:201], v148 offset:38912
	ds_read_b128 v[202:205], v148 offset:39936
	global_load_lds_dwordx4 v[226:227], off
	v_lshl_add_u64 v[226:227], s[20:21], 0, v[134:135]
	s_mov_b32 m0, s56
	s_nop 0
	global_load_lds_dwordx4 v[226:227], off
	s_waitcnt vmcnt(8)
	s_waitcnt lgkmcnt(0)
	s_barrier
	s_waitcnt lgkmcnt(0)
	v_mfma_f32_16x16x32_bf16 v[126:129], v[130:133], v[174:177], v[126:129]
	v_mfma_f32_16x16x32_bf16 v[94:97], v[150:153], v[174:177], v[94:97]
	v_mfma_f32_16x16x32_bf16 v[122:125], v[130:133], v[182:185], v[122:125]
	v_mfma_f32_16x16x32_bf16 v[90:93], v[150:153], v[182:185], v[90:93]
	v_mfma_f32_16x16x32_bf16 v[118:121], v[130:133], v[190:193], v[118:121]
	v_mfma_f32_16x16x32_bf16 v[86:89], v[150:153], v[190:193], v[86:89]
	v_mfma_f32_16x16x32_bf16 v[114:117], v[130:133], v[198:201], v[114:117]
	v_mfma_f32_16x16x32_bf16 v[82:85], v[150:153], v[198:201], v[82:85]
	v_mfma_f32_16x16x32_bf16 v[126:129], v[142:145], v[178:181], v[126:129]
	v_mfma_f32_16x16x32_bf16 v[94:97], v[154:157], v[178:181], v[94:97]
	v_mfma_f32_16x16x32_bf16 v[122:125], v[142:145], v[186:189], v[122:125]
	v_mfma_f32_16x16x32_bf16 v[90:93], v[154:157], v[186:189], v[90:93]
	v_mfma_f32_16x16x32_bf16 v[118:121], v[142:145], v[194:197], v[118:121]
	v_mfma_f32_16x16x32_bf16 v[86:89], v[154:157], v[194:197], v[86:89]
	v_mfma_f32_16x16x32_bf16 v[114:117], v[142:145], v[202:205], v[114:117]
	v_mfma_f32_16x16x32_bf16 v[82:85], v[154:157], v[202:205], v[82:85]
	v_mfma_f32_16x16x32_bf16 v[62:65], v[158:161], v[174:177], v[62:65]
	v_mfma_f32_16x16x32_bf16 v[30:33], v[166:169], v[174:177], v[30:33]
	v_mfma_f32_16x16x32_bf16 v[58:61], v[158:161], v[182:185], v[58:61]
	v_mfma_f32_16x16x32_bf16 v[26:29], v[166:169], v[182:185], v[26:29]
	v_mfma_f32_16x16x32_bf16 v[54:57], v[158:161], v[190:193], v[54:57]
	v_mfma_f32_16x16x32_bf16 v[22:25], v[166:169], v[190:193], v[22:25]
	v_mfma_f32_16x16x32_bf16 v[50:53], v[158:161], v[198:201], v[50:53]
	v_mfma_f32_16x16x32_bf16 v[18:21], v[166:169], v[198:201], v[18:21]
	v_mfma_f32_16x16x32_bf16 v[62:65], v[162:165], v[178:181], v[62:65]
	v_mfma_f32_16x16x32_bf16 v[30:33], v[170:173], v[178:181], v[30:33]
	v_mfma_f32_16x16x32_bf16 v[58:61], v[162:165], v[186:189], v[58:61]
	v_mfma_f32_16x16x32_bf16 v[26:29], v[170:173], v[186:189], v[26:29]
	v_mfma_f32_16x16x32_bf16 v[54:57], v[162:165], v[194:197], v[54:57]
	v_mfma_f32_16x16x32_bf16 v[22:25], v[170:173], v[194:197], v[22:25]
	v_mfma_f32_16x16x32_bf16 v[50:53], v[162:165], v[202:205], v[50:53]
	v_mfma_f32_16x16x32_bf16 v[18:21], v[170:173], v[202:205], v[18:21]
	s_barrier
	s_add_i32 s20, s31, s22
	v_lshl_add_u64 v[214:215], v[214:215], 0, s[60:61]
	s_mov_b32 m0, s20
	ds_read_b128 v[174:177], v148 offset:49152
	ds_read_b128 v[178:181], v148 offset:50176
	ds_read_b128 v[182:185], v148 offset:51200
	ds_read_b128 v[186:189], v148 offset:52224
	ds_read_b128 v[190:193], v148 offset:53248
	ds_read_b128 v[194:197], v148 offset:54272
	ds_read_b128 v[198:201], v148 offset:55296
	ds_read_b128 v[202:205], v148 offset:56320
	global_load_lds_dwordx4 v[214:215], off
	v_lshl_add_u64 v[214:215], v[216:217], 0, s[60:61]
	s_add_i32 m0, s20, 0x2000
	s_add_i32 s20, s62, s22
	global_load_lds_dwordx4 v[214:215], off
	v_lshl_add_u64 v[214:215], v[218:219], 0, s[60:61]
	s_mov_b32 m0, s20
	s_nop 0
	global_load_lds_dwordx4 v[214:215], off
	v_lshl_add_u64 v[214:215], v[220:221], 0, s[60:61]
	s_add_i32 m0, s20, 0x2000
	s_nop 0
	global_load_lds_dwordx4 v[214:215], off
	v_lshl_add_u64 v[214:215], v[222:223], 0, s[60:61]
	s_mov_b32 m0, s57
	s_nop 0
	global_load_lds_dwordx4 v[214:215], off
	v_lshl_add_u64 v[214:215], v[224:225], 0, s[60:61]
	s_mov_b32 m0, s65
	s_nop 0
	global_load_lds_dwordx4 v[214:215], off
	s_waitcnt vmcnt(8)
	s_waitcnt lgkmcnt(0)
	s_barrier
	s_waitcnt lgkmcnt(0)
	v_mfma_f32_16x16x32_bf16 v[110:113], v[130:133], v[174:177], v[110:113]
	v_mfma_f32_16x16x32_bf16 v[78:81], v[150:153], v[174:177], v[78:81]
	v_mfma_f32_16x16x32_bf16 v[106:109], v[130:133], v[182:185], v[106:109]
	v_mfma_f32_16x16x32_bf16 v[74:77], v[150:153], v[182:185], v[74:77]
	v_mfma_f32_16x16x32_bf16 v[102:105], v[130:133], v[190:193], v[102:105]
	v_mfma_f32_16x16x32_bf16 v[70:73], v[150:153], v[190:193], v[70:73]
	v_mfma_f32_16x16x32_bf16 v[98:101], v[130:133], v[198:201], v[98:101]
	v_mfma_f32_16x16x32_bf16 v[66:69], v[150:153], v[198:201], v[66:69]
	v_mfma_f32_16x16x32_bf16 v[110:113], v[142:145], v[178:181], v[110:113]
	v_mfma_f32_16x16x32_bf16 v[78:81], v[154:157], v[178:181], v[78:81]
	v_mfma_f32_16x16x32_bf16 v[106:109], v[142:145], v[186:189], v[106:109]
	v_mfma_f32_16x16x32_bf16 v[74:77], v[154:157], v[186:189], v[74:77]
	v_mfma_f32_16x16x32_bf16 v[102:105], v[142:145], v[194:197], v[102:105]
	v_mfma_f32_16x16x32_bf16 v[70:73], v[154:157], v[194:197], v[70:73]
	v_mfma_f32_16x16x32_bf16 v[98:101], v[142:145], v[202:205], v[98:101]
	v_mfma_f32_16x16x32_bf16 v[66:69], v[154:157], v[202:205], v[66:69]
	v_mfma_f32_16x16x32_bf16 v[46:49], v[158:161], v[174:177], v[46:49]
	v_mfma_f32_16x16x32_bf16 v[14:17], v[166:169], v[174:177], v[14:17]
	v_mfma_f32_16x16x32_bf16 v[42:45], v[158:161], v[182:185], v[42:45]
	v_mfma_f32_16x16x32_bf16 v[10:13], v[166:169], v[182:185], v[10:13]
	v_mfma_f32_16x16x32_bf16 v[38:41], v[158:161], v[190:193], v[38:41]
	v_mfma_f32_16x16x32_bf16 v[6:9], v[166:169], v[190:193], v[6:9]
	v_mfma_f32_16x16x32_bf16 v[34:37], v[158:161], v[198:201], v[34:37]
	v_mfma_f32_16x16x32_bf16 v[2:5], v[166:169], v[198:201], v[2:5]
	v_mfma_f32_16x16x32_bf16 v[46:49], v[162:165], v[178:181], v[46:49]
	v_mfma_f32_16x16x32_bf16 v[14:17], v[170:173], v[178:181], v[14:17]
	v_mfma_f32_16x16x32_bf16 v[42:45], v[162:165], v[186:189], v[42:45]
	v_mfma_f32_16x16x32_bf16 v[10:13], v[170:173], v[186:189], v[10:13]
	v_mfma_f32_16x16x32_bf16 v[38:41], v[162:165], v[194:197], v[38:41]
	v_mfma_f32_16x16x32_bf16 v[6:9], v[170:173], v[194:197], v[6:9]
	v_mfma_f32_16x16x32_bf16 v[34:37], v[162:165], v[202:205], v[34:37]
	v_mfma_f32_16x16x32_bf16 v[2:5], v[170:173], v[202:205], v[2:5]
	s_barrier
	s_add_u32 s18, s18, 0x100
	s_addc_u32 s19, s19, 0
	s_add_u32 s71, s71, 0x100
	s_addc_u32 s72, s72, 0
	s_cmp_ge_i32 s73, s66
	s_mov_b32 s20, s73
	s_cbranch_scc0 .LBB0_1012

.LBB0_1141:
	s_add_u32 s0, s6, 0x80
	s_addc_u32 s1, s7, 0
	s_add_u32 s6, s4, 0x100
	s_addc_u32 s7, s5, 0
	s_mov_b32 s4, 0
	s_add_i32 s9, s4, 2
	s_add_u32 s10, s0, 0x80
	s_addc_u32 s5, s1, 0
	s_add_i32 s31, 0, 0x10000
	s_cmp_eq_u32 s77, s4
	s_cselect_b32 s5, s23, s5
	s_cselect_b32 s4, s22, s10
	v_add_u32_e32 v1, s31, v165
	s_cselect_b32 s11, s67, s7
	s_cselect_b32 s10, s66, s6
	s_add_i32 s53, 0, 0x14000
	ds_read_b128 v[82:85], v1
	ds_read_b128 v[86:89], v1 offset:1024
	ds_read_b128 v[138:141], v1 offset:2048
	ds_read_b128 v[142:145], v1 offset:3072
	v_add_u32_e32 v1, s53, v165
	ds_read_b128 v[158:161], v1
	ds_read_b128 v[168:171], v1 offset:1024
	ds_read_b128 v[172:175], v1 offset:2048
	ds_read_b128 v[176:179], v1 offset:3072
	v_lshl_add_u64 v[162:163], s[0:1], 0, v[154:155]
	s_add_i32 m0, s70, 0xc000
	ds_read_b128 v[180:183], v167
	ds_read_b128 v[184:187], v167 offset:1024
	ds_read_b128 v[188:191], v167 offset:2048
	ds_read_b128 v[192:195], v167 offset:3072
	ds_read_b128 v[196:199], v167 offset:4096
	ds_read_b128 v[200:203], v167 offset:5120
	ds_read_b128 v[214:217], v167 offset:6144
	ds_read_b128 v[218:221], v167 offset:7168
	global_load_lds_dwordx4 v[162:163], off
	v_lshl_add_u64 v[162:163], s[0:1], 0, v[156:157]
	s_add_i32 m0, s70, 0xe000
	s_nop 0
	global_load_lds_dwordx4 v[162:163], off
	s_waitcnt vmcnt(8)
	s_waitcnt lgkmcnt(0)
	s_barrier
	s_waitcnt lgkmcnt(0)
	v_mfma_f32_16x16x32_bf16 v[134:137], v[82:85], v[180:183], 0
	v_mfma_f32_16x16x32_bf16 v[130:133], v[138:141], v[180:183], 0
	v_mfma_f32_16x16x32_bf16 v[126:129], v[82:85], v[188:191], 0
	v_mfma_f32_16x16x32_bf16 v[122:125], v[138:141], v[188:191], 0
	v_mfma_f32_16x16x32_bf16 v[118:121], v[82:85], v[196:199], 0
	v_mfma_f32_16x16x32_bf16 v[114:117], v[138:141], v[196:199], 0
	v_mfma_f32_16x16x32_bf16 v[110:113], v[82:85], v[214:217], 0
	v_mfma_f32_16x16x32_bf16 v[106:109], v[138:141], v[214:217], 0
	v_mfma_f32_16x16x32_bf16 v[134:137], v[86:89], v[184:187], v[134:137]
	v_mfma_f32_16x16x32_bf16 v[130:133], v[142:145], v[184:187], v[130:133]
	v_mfma_f32_16x16x32_bf16 v[126:129], v[86:89], v[192:195], v[126:129]
	v_mfma_f32_16x16x32_bf16 v[122:125], v[142:145], v[192:195], v[122:125]
	v_mfma_f32_16x16x32_bf16 v[118:121], v[86:89], v[200:203], v[118:121]
	v_mfma_f32_16x16x32_bf16 v[114:117], v[142:145], v[200:203], v[114:117]
	v_mfma_f32_16x16x32_bf16 v[110:113], v[86:89], v[218:221], v[110:113]
	v_mfma_f32_16x16x32_bf16 v[106:109], v[142:145], v[218:221], v[106:109]
	v_mfma_f32_16x16x32_bf16 v[62:65], v[158:161], v[180:183], 0
	v_mfma_f32_16x16x32_bf16 v[58:61], v[172:175], v[180:183], 0
	v_mfma_f32_16x16x32_bf16 v[54:57], v[158:161], v[188:191], 0
	v_mfma_f32_16x16x32_bf16 v[50:53], v[172:175], v[188:191], 0
	v_mfma_f32_16x16x32_bf16 v[46:49], v[158:161], v[196:199], 0
	v_mfma_f32_16x16x32_bf16 v[42:45], v[172:175], v[196:199], 0
	v_mfma_f32_16x16x32_bf16 v[38:41], v[158:161], v[214:217], 0
	v_mfma_f32_16x16x32_bf16 v[34:37], v[172:175], v[214:217], 0
	v_mfma_f32_16x16x32_bf16 v[62:65], v[168:171], v[184:187], v[62:65]
	v_mfma_f32_16x16x32_bf16 v[58:61], v[176:179], v[184:187], v[58:61]
	v_mfma_f32_16x16x32_bf16 v[54:57], v[168:171], v[192:195], v[54:57]
	v_mfma_f32_16x16x32_bf16 v[50:53], v[176:179], v[192:195], v[50:53]
	v_mfma_f32_16x16x32_bf16 v[46:49], v[168:171], v[200:203], v[46:49]
	v_mfma_f32_16x16x32_bf16 v[42:45], v[176:179], v[200:203], v[42:45]
	v_mfma_f32_16x16x32_bf16 v[38:41], v[168:171], v[218:221], v[38:41]
	v_mfma_f32_16x16x32_bf16 v[34:37], v[176:179], v[218:221], v[34:37]
	s_barrier
	s_add_i32 s31, s31, s65
	v_lshl_add_u64 v[162:163], s[10:11], 0, v[150:151]
	s_mov_b32 m0, s31
	ds_read_b128 v[180:183], v167 offset:16384
	ds_read_b128 v[184:187], v167 offset:17408
	ds_read_b128 v[188:191], v167 offset:18432
	ds_read_b128 v[192:195], v167 offset:19456
	ds_read_b128 v[196:199], v167 offset:20480
	ds_read_b128 v[200:203], v167 offset:21504
	ds_read_b128 v[214:217], v167 offset:22528
	ds_read_b128 v[218:221], v167 offset:23552
	global_load_lds_dwordx4 v[162:163], off
	s_add_i32 m0, s31, 0x2000
	v_lshl_add_u64 v[204:205], s[10:11], 0, v[146:147]
	s_add_u32 s10, s10, s12
	s_addc_u32 s11, s11, s13
	s_add_i32 s31, s53, s65
	global_load_lds_dwordx4 v[204:205], off
	v_lshl_add_u64 v[222:223], s[10:11], 0, v[150:151]
	s_mov_b32 m0, s31
	v_lshl_add_u64 v[224:225], s[10:11], 0, v[146:147]
	global_load_lds_dwordx4 v[222:223], off
	s_add_i32 m0, s31, 0x2000
	v_lshl_add_u64 v[226:227], s[4:5], 0, v[152:153]
	global_load_lds_dwordx4 v[224:225], off
	s_mov_b32 m0, s70
	v_lshl_add_u64 v[236:237], s[4:5], 0, v[148:149]
	global_load_lds_dwordx4 v[226:227], off
	s_mov_b32 m0, s71
	s_nop 0
	global_load_lds_dwordx4 v[236:237], off
	s_waitcnt vmcnt(8)
	s_waitcnt lgkmcnt(0)
	s_barrier
	s_waitcnt lgkmcnt(0)
	v_mfma_f32_16x16x32_bf16 v[102:105], v[82:85], v[180:183], 0
	v_mfma_f32_16x16x32_bf16 v[98:101], v[138:141], v[180:183], 0
	v_mfma_f32_16x16x32_bf16 v[94:97], v[82:85], v[188:191], 0
	v_mfma_f32_16x16x32_bf16 v[90:93], v[138:141], v[188:191], 0
	v_mfma_f32_16x16x32_bf16 v[78:81], v[82:85], v[196:199], 0
	v_mfma_f32_16x16x32_bf16 v[74:77], v[138:141], v[196:199], 0
	v_mfma_f32_16x16x32_bf16 v[70:73], v[82:85], v[214:217], 0
	v_mfma_f32_16x16x32_bf16 v[66:69], v[138:141], v[214:217], 0
	v_mfma_f32_16x16x32_bf16 v[102:105], v[86:89], v[184:187], v[102:105]
	v_mfma_f32_16x16x32_bf16 v[98:101], v[142:145], v[184:187], v[98:101]
	v_mfma_f32_16x16x32_bf16 v[94:97], v[86:89], v[192:195], v[94:97]
	v_mfma_f32_16x16x32_bf16 v[90:93], v[142:145], v[192:195], v[90:93]
	v_mfma_f32_16x16x32_bf16 v[78:81], v[86:89], v[200:203], v[78:81]
	v_mfma_f32_16x16x32_bf16 v[74:77], v[142:145], v[200:203], v[74:77]
	v_mfma_f32_16x16x32_bf16 v[70:73], v[86:89], v[218:221], v[70:73]
	v_mfma_f32_16x16x32_bf16 v[66:69], v[142:145], v[218:221], v[66:69]
	v_mfma_f32_16x16x32_bf16 v[30:33], v[158:161], v[180:183], 0
	v_mfma_f32_16x16x32_bf16 v[26:29], v[172:175], v[180:183], 0
	v_mfma_f32_16x16x32_bf16 v[22:25], v[158:161], v[188:191], 0
	v_mfma_f32_16x16x32_bf16 v[18:21], v[172:175], v[188:191], 0
	v_mfma_f32_16x16x32_bf16 v[14:17], v[158:161], v[196:199], 0
	v_mfma_f32_16x16x32_bf16 v[10:13], v[172:175], v[196:199], 0
	v_mfma_f32_16x16x32_bf16 v[6:9], v[158:161], v[214:217], 0
	v_mfma_f32_16x16x32_bf16 v[2:5], v[172:175], v[214:217], 0
	v_mfma_f32_16x16x32_bf16 v[30:33], v[168:171], v[184:187], v[30:33]
	v_mfma_f32_16x16x32_bf16 v[26:29], v[176:179], v[184:187], v[26:29]
	v_mfma_f32_16x16x32_bf16 v[22:25], v[168:171], v[192:195], v[22:25]
	v_mfma_f32_16x16x32_bf16 v[18:21], v[176:179], v[192:195], v[18:21]
	v_mfma_f32_16x16x32_bf16 v[14:17], v[168:171], v[200:203], v[14:17]
	v_mfma_f32_16x16x32_bf16 v[10:13], v[176:179], v[200:203], v[10:13]
	v_mfma_f32_16x16x32_bf16 v[6:9], v[168:171], v[218:221], v[6:9]
	v_mfma_f32_16x16x32_bf16 v[2:5], v[176:179], v[218:221], v[2:5]
	s_barrier
	s_add_i32 s10, 0, 0x18000
	v_add_u32_e32 v1, s10, v165
	s_add_i32 s11, 0, 0x1c000
	ds_read_b128 v[82:85], v1
	ds_read_b128 v[86:89], v1 offset:1024
	ds_read_b128 v[138:141], v1 offset:2048
	ds_read_b128 v[142:145], v1 offset:3072
	v_add_u32_e32 v1, s11, v165
	ds_read_b128 v[158:161], v1
	ds_read_b128 v[168:171], v1 offset:1024
	ds_read_b128 v[172:175], v1 offset:2048
	ds_read_b128 v[176:179], v1 offset:3072
	s_add_u32 s4, s4, s12
	s_addc_u32 s5, s5, s13
	s_mov_b32 m0, s72
	v_lshl_add_u64 v[238:239], s[4:5], 0, v[152:153]
	ds_read_b128 v[180:183], v167 offset:32768
	ds_read_b128 v[184:187], v167 offset:33792
	ds_read_b128 v[188:191], v167 offset:34816
	ds_read_b128 v[192:195], v167 offset:35840
	ds_read_b128 v[196:199], v167 offset:36864
	ds_read_b128 v[200:203], v167 offset:37888
	ds_read_b128 v[214:217], v167 offset:38912
	ds_read_b128 v[218:221], v167 offset:39936
	global_load_lds_dwordx4 v[238:239], off
	v_lshl_add_u64 v[238:239], s[4:5], 0, v[148:149]
	s_mov_b32 m0, s73
	s_nop 0
	global_load_lds_dwordx4 v[238:239], off
	s_waitcnt vmcnt(8)
	s_waitcnt lgkmcnt(0)
	s_barrier
	s_waitcnt lgkmcnt(0)
	v_mfma_f32_16x16x32_bf16 v[134:137], v[82:85], v[180:183], v[134:137]
	v_mfma_f32_16x16x32_bf16 v[130:133], v[138:141], v[180:183], v[130:133]
	v_mfma_f32_16x16x32_bf16 v[126:129], v[82:85], v[188:191], v[126:129]
	v_mfma_f32_16x16x32_bf16 v[122:125], v[138:141], v[188:191], v[122:125]
	v_mfma_f32_16x16x32_bf16 v[118:121], v[82:85], v[196:199], v[118:121]
	v_mfma_f32_16x16x32_bf16 v[114:117], v[138:141], v[196:199], v[114:117]
	v_mfma_f32_16x16x32_bf16 v[110:113], v[82:85], v[214:217], v[110:113]
	v_mfma_f32_16x16x32_bf16 v[106:109], v[138:141], v[214:217], v[106:109]
	v_mfma_f32_16x16x32_bf16 v[134:137], v[86:89], v[184:187], v[134:137]
	v_mfma_f32_16x16x32_bf16 v[130:133], v[142:145], v[184:187], v[130:133]
	v_mfma_f32_16x16x32_bf16 v[126:129], v[86:89], v[192:195], v[126:129]
	v_mfma_f32_16x16x32_bf16 v[122:125], v[142:145], v[192:195], v[122:125]
	v_mfma_f32_16x16x32_bf16 v[118:121], v[86:89], v[200:203], v[118:121]
	v_mfma_f32_16x16x32_bf16 v[114:117], v[142:145], v[200:203], v[114:117]
	v_mfma_f32_16x16x32_bf16 v[110:113], v[86:89], v[218:221], v[110:113]
	v_mfma_f32_16x16x32_bf16 v[106:109], v[142:145], v[218:221], v[106:109]
	v_mfma_f32_16x16x32_bf16 v[62:65], v[158:161], v[180:183], v[62:65]
	v_mfma_f32_16x16x32_bf16 v[58:61], v[172:175], v[180:183], v[58:61]
	v_mfma_f32_16x16x32_bf16 v[54:57], v[158:161], v[188:191], v[54:57]
	v_mfma_f32_16x16x32_bf16 v[50:53], v[172:175], v[188:191], v[50:53]
	v_mfma_f32_16x16x32_bf16 v[46:49], v[158:161], v[196:199], v[46:49]
	v_mfma_f32_16x16x32_bf16 v[42:45], v[172:175], v[196:199], v[42:45]
	v_mfma_f32_16x16x32_bf16 v[38:41], v[158:161], v[214:217], v[38:41]
	v_mfma_f32_16x16x32_bf16 v[34:37], v[172:175], v[214:217], v[34:37]
	v_mfma_f32_16x16x32_bf16 v[62:65], v[168:171], v[184:187], v[62:65]
	v_mfma_f32_16x16x32_bf16 v[58:61], v[176:179], v[184:187], v[58:61]
	v_mfma_f32_16x16x32_bf16 v[54:57], v[168:171], v[192:195], v[54:57]
	v_mfma_f32_16x16x32_bf16 v[50:53], v[176:179], v[192:195], v[50:53]
	v_mfma_f32_16x16x32_bf16 v[46:49], v[168:171], v[200:203], v[46:49]
	v_mfma_f32_16x16x32_bf16 v[42:45], v[176:179], v[200:203], v[42:45]
	v_mfma_f32_16x16x32_bf16 v[38:41], v[168:171], v[218:221], v[38:41]
	v_mfma_f32_16x16x32_bf16 v[34:37], v[176:179], v[218:221], v[34:37]
	s_barrier
	s_add_i32 s4, s10, s65
	v_lshl_add_u64 v[162:163], v[162:163], 0, s[60:61]
	s_mov_b32 m0, s4
	ds_read_b128 v[180:183], v167 offset:49152
	ds_read_b128 v[184:187], v167 offset:50176
	ds_read_b128 v[188:191], v167 offset:51200
	ds_read_b128 v[192:195], v167 offset:52224
	ds_read_b128 v[196:199], v167 offset:53248
	ds_read_b128 v[200:203], v167 offset:54272
	ds_read_b128 v[214:217], v167 offset:55296
	ds_read_b128 v[218:221], v167 offset:56320
	global_load_lds_dwordx4 v[162:163], off
	v_lshl_add_u64 v[162:163], v[204:205], 0, s[60:61]
	s_add_i32 m0, s4, 0x2000
	s_add_i32 s4, s11, s65
	global_load_lds_dwordx4 v[162:163], off
	v_lshl_add_u64 v[162:163], v[222:223], 0, s[60:61]
	s_mov_b32 m0, s4
	s_nop 0
	global_load_lds_dwordx4 v[162:163], off
	v_lshl_add_u64 v[162:163], v[224:225], 0, s[60:61]
	s_add_i32 m0, s4, 0x2000
	s_nop 0
	global_load_lds_dwordx4 v[162:163], off
	v_lshl_add_u64 v[162:163], v[226:227], 0, s[60:61]
	s_mov_b32 m0, s74
	s_nop 0
	global_load_lds_dwordx4 v[162:163], off
	v_lshl_add_u64 v[162:163], v[236:237], 0, s[60:61]
	s_mov_b32 m0, s75
	s_nop 0
	global_load_lds_dwordx4 v[162:163], off
	s_waitcnt vmcnt(8)
	s_waitcnt lgkmcnt(0)
	s_barrier
	s_waitcnt lgkmcnt(0)
	v_mfma_f32_16x16x32_bf16 v[102:105], v[82:85], v[180:183], v[102:105]
	v_mfma_f32_16x16x32_bf16 v[98:101], v[138:141], v[180:183], v[98:101]
	v_mfma_f32_16x16x32_bf16 v[94:97], v[82:85], v[188:191], v[94:97]
	v_mfma_f32_16x16x32_bf16 v[90:93], v[138:141], v[188:191], v[90:93]
	v_mfma_f32_16x16x32_bf16 v[78:81], v[82:85], v[196:199], v[78:81]
	v_mfma_f32_16x16x32_bf16 v[74:77], v[138:141], v[196:199], v[74:77]
	v_mfma_f32_16x16x32_bf16 v[70:73], v[82:85], v[214:217], v[70:73]
	v_mfma_f32_16x16x32_bf16 v[66:69], v[138:141], v[214:217], v[66:69]
	v_mfma_f32_16x16x32_bf16 v[102:105], v[86:89], v[184:187], v[102:105]
	v_mfma_f32_16x16x32_bf16 v[98:101], v[142:145], v[184:187], v[98:101]
	v_mfma_f32_16x16x32_bf16 v[94:97], v[86:89], v[192:195], v[94:97]
	v_mfma_f32_16x16x32_bf16 v[90:93], v[142:145], v[192:195], v[90:93]
	v_mfma_f32_16x16x32_bf16 v[78:81], v[86:89], v[200:203], v[78:81]
	v_mfma_f32_16x16x32_bf16 v[74:77], v[142:145], v[200:203], v[74:77]
	v_mfma_f32_16x16x32_bf16 v[70:73], v[86:89], v[218:221], v[70:73]
	v_mfma_f32_16x16x32_bf16 v[66:69], v[142:145], v[218:221], v[66:69]
	v_mfma_f32_16x16x32_bf16 v[30:33], v[158:161], v[180:183], v[30:33]
	v_mfma_f32_16x16x32_bf16 v[26:29], v[172:175], v[180:183], v[26:29]
	v_mfma_f32_16x16x32_bf16 v[22:25], v[158:161], v[188:191], v[22:25]
	v_mfma_f32_16x16x32_bf16 v[18:21], v[172:175], v[188:191], v[18:21]
	v_mfma_f32_16x16x32_bf16 v[14:17], v[158:161], v[196:199], v[14:17]
	v_mfma_f32_16x16x32_bf16 v[10:13], v[172:175], v[196:199], v[10:13]
	v_mfma_f32_16x16x32_bf16 v[6:9], v[158:161], v[214:217], v[6:9]
	v_mfma_f32_16x16x32_bf16 v[2:5], v[172:175], v[214:217], v[2:5]
	v_mfma_f32_16x16x32_bf16 v[30:33], v[168:171], v[184:187], v[30:33]
	v_mfma_f32_16x16x32_bf16 v[26:29], v[176:179], v[184:187], v[26:29]
	v_mfma_f32_16x16x32_bf16 v[22:25], v[168:171], v[192:195], v[22:25]
	v_mfma_f32_16x16x32_bf16 v[18:21], v[176:179], v[192:195], v[18:21]
	v_mfma_f32_16x16x32_bf16 v[14:17], v[168:171], v[200:203], v[14:17]
	v_mfma_f32_16x16x32_bf16 v[10:13], v[176:179], v[200:203], v[10:13]
	v_mfma_f32_16x16x32_bf16 v[6:9], v[168:171], v[218:221], v[6:9]
	v_mfma_f32_16x16x32_bf16 v[2:5], v[176:179], v[218:221], v[2:5]
	s_barrier
	s_add_u32 s0, s0, 0x100
	s_addc_u32 s1, s1, 0
	s_add_u32 s6, s6, 0x100
	s_addc_u32 s7, s7, 0
	s_cmp_ge_i32 s9, s76
	s_mov_b32 s4, s9
	s_cbranch_scc1 .Lin1_exit
.LBB0_1142:
	s_add_i32 s9, s4, 2
	s_add_u32 s10, s0, 0x80
	s_addc_u32 s5, s1, 0
	s_add_i32 s31, 0, 0x10000
	s_cmp_eq_u32 s77, s4
	s_cselect_b32 s5, s23, s5
	s_cselect_b32 s4, s22, s10
	v_add_u32_e32 v1, s31, v165
	s_cselect_b32 s11, s67, s7
	s_cselect_b32 s10, s66, s6
	s_add_i32 s53, 0, 0x14000
	ds_read_b128 v[82:85], v1
	ds_read_b128 v[86:89], v1 offset:1024
	ds_read_b128 v[138:141], v1 offset:2048
	ds_read_b128 v[142:145], v1 offset:3072
	v_add_u32_e32 v1, s53, v165
	ds_read_b128 v[158:161], v1
	ds_read_b128 v[168:171], v1 offset:1024
	ds_read_b128 v[172:175], v1 offset:2048
	ds_read_b128 v[176:179], v1 offset:3072
	v_lshl_add_u64 v[162:163], s[0:1], 0, v[154:155]
	s_add_i32 m0, s70, 0xc000
	ds_read_b128 v[180:183], v167
	ds_read_b128 v[184:187], v167 offset:1024
	ds_read_b128 v[188:191], v167 offset:2048
	ds_read_b128 v[192:195], v167 offset:3072
	ds_read_b128 v[196:199], v167 offset:4096
	ds_read_b128 v[200:203], v167 offset:5120
	ds_read_b128 v[214:217], v167 offset:6144
	ds_read_b128 v[218:221], v167 offset:7168
	global_load_lds_dwordx4 v[162:163], off
	v_lshl_add_u64 v[162:163], s[0:1], 0, v[156:157]
	s_add_i32 m0, s70, 0xe000
	s_nop 0
	global_load_lds_dwordx4 v[162:163], off
	s_waitcnt vmcnt(8)
	s_waitcnt lgkmcnt(0)
	s_barrier
	s_waitcnt lgkmcnt(0)
	v_mfma_f32_16x16x32_bf16 v[134:137], v[82:85], v[180:183], v[134:137]
	v_mfma_f32_16x16x32_bf16 v[130:133], v[138:141], v[180:183], v[130:133]
	v_mfma_f32_16x16x32_bf16 v[126:129], v[82:85], v[188:191], v[126:129]
	v_mfma_f32_16x16x32_bf16 v[122:125], v[138:141], v[188:191], v[122:125]
	v_mfma_f32_16x16x32_bf16 v[118:121], v[82:85], v[196:199], v[118:121]
	v_mfma_f32_16x16x32_bf16 v[114:117], v[138:141], v[196:199], v[114:117]
	v_mfma_f32_16x16x32_bf16 v[110:113], v[82:85], v[214:217], v[110:113]
	v_mfma_f32_16x16x32_bf16 v[106:109], v[138:141], v[214:217], v[106:109]
	v_mfma_f32_16x16x32_bf16 v[134:137], v[86:89], v[184:187], v[134:137]
	v_mfma_f32_16x16x32_bf16 v[130:133], v[142:145], v[184:187], v[130:133]
	v_mfma_f32_16x16x32_bf16 v[126:129], v[86:89], v[192:195], v[126:129]
	v_mfma_f32_16x16x32_bf16 v[122:125], v[142:145], v[192:195], v[122:125]
	v_mfma_f32_16x16x32_bf16 v[118:121], v[86:89], v[200:203], v[118:121]
	v_mfma_f32_16x16x32_bf16 v[114:117], v[142:145], v[200:203], v[114:117]
	v_mfma_f32_16x16x32_bf16 v[110:113], v[86:89], v[218:221], v[110:113]
	v_mfma_f32_16x16x32_bf16 v[106:109], v[142:145], v[218:221], v[106:109]
	v_mfma_f32_16x16x32_bf16 v[62:65], v[158:161], v[180:183], v[62:65]
	v_mfma_f32_16x16x32_bf16 v[58:61], v[172:175], v[180:183], v[58:61]
	v_mfma_f32_16x16x32_bf16 v[54:57], v[158:161], v[188:191], v[54:57]
	v_mfma_f32_16x16x32_bf16 v[50:53], v[172:175], v[188:191], v[50:53]
	v_mfma_f32_16x16x32_bf16 v[46:49], v[158:161], v[196:199], v[46:49]
	v_mfma_f32_16x16x32_bf16 v[42:45], v[172:175], v[196:199], v[42:45]
	v_mfma_f32_16x16x32_bf16 v[38:41], v[158:161], v[214:217], v[38:41]
	v_mfma_f32_16x16x32_bf16 v[34:37], v[172:175], v[214:217], v[34:37]
	v_mfma_f32_16x16x32_bf16 v[62:65], v[168:171], v[184:187], v[62:65]
	v_mfma_f32_16x16x32_bf16 v[58:61], v[176:179], v[184:187], v[58:61]
	v_mfma_f32_16x16x32_bf16 v[54:57], v[168:171], v[192:195], v[54:57]
	v_mfma_f32_16x16x32_bf16 v[50:53], v[176:179], v[192:195], v[50:53]
	v_mfma_f32_16x16x32_bf16 v[46:49], v[168:171], v[200:203], v[46:49]
	v_mfma_f32_16x16x32_bf16 v[42:45], v[176:179], v[200:203], v[42:45]
	v_mfma_f32_16x16x32_bf16 v[38:41], v[168:171], v[218:221], v[38:41]
	v_mfma_f32_16x16x32_bf16 v[34:37], v[176:179], v[218:221], v[34:37]
	s_barrier
	s_add_i32 s31, s31, s65
	v_lshl_add_u64 v[162:163], s[10:11], 0, v[150:151]
	s_mov_b32 m0, s31
	ds_read_b128 v[180:183], v167 offset:16384
	ds_read_b128 v[184:187], v167 offset:17408
	ds_read_b128 v[188:191], v167 offset:18432
	ds_read_b128 v[192:195], v167 offset:19456
	ds_read_b128 v[196:199], v167 offset:20480
	ds_read_b128 v[200:203], v167 offset:21504
	ds_read_b128 v[214:217], v167 offset:22528
	ds_read_b128 v[218:221], v167 offset:23552
	global_load_lds_dwordx4 v[162:163], off
	s_add_i32 m0, s31, 0x2000
	v_lshl_add_u64 v[204:205], s[10:11], 0, v[146:147]
	s_add_u32 s10, s10, s12
	s_addc_u32 s11, s11, s13
	s_add_i32 s31, s53, s65
	global_load_lds_dwordx4 v[204:205], off
	v_lshl_add_u64 v[222:223], s[10:11], 0, v[150:151]
	s_mov_b32 m0, s31
	v_lshl_add_u64 v[224:225], s[10:11], 0, v[146:147]
	global_load_lds_dwordx4 v[222:223], off
	s_add_i32 m0, s31, 0x2000
	v_lshl_add_u64 v[226:227], s[4:5], 0, v[152:153]
	global_load_lds_dwordx4 v[224:225], off
	s_mov_b32 m0, s70
	v_lshl_add_u64 v[236:237], s[4:5], 0, v[148:149]
	global_load_lds_dwordx4 v[226:227], off
	s_mov_b32 m0, s71
	s_nop 0
	global_load_lds_dwordx4 v[236:237], off
	s_waitcnt vmcnt(8)
	s_waitcnt lgkmcnt(0)
	s_barrier
	s_waitcnt lgkmcnt(0)
	v_mfma_f32_16x16x32_bf16 v[102:105], v[82:85], v[180:183], v[102:105]
	v_mfma_f32_16x16x32_bf16 v[98:101], v[138:141], v[180:183], v[98:101]
	v_mfma_f32_16x16x32_bf16 v[94:97], v[82:85], v[188:191], v[94:97]
	v_mfma_f32_16x16x32_bf16 v[90:93], v[138:141], v[188:191], v[90:93]
	v_mfma_f32_16x16x32_bf16 v[78:81], v[82:85], v[196:199], v[78:81]
	v_mfma_f32_16x16x32_bf16 v[74:77], v[138:141], v[196:199], v[74:77]
	v_mfma_f32_16x16x32_bf16 v[70:73], v[82:85], v[214:217], v[70:73]
	v_mfma_f32_16x16x32_bf16 v[66:69], v[138:141], v[214:217], v[66:69]
	v_mfma_f32_16x16x32_bf16 v[102:105], v[86:89], v[184:187], v[102:105]
	v_mfma_f32_16x16x32_bf16 v[98:101], v[142:145], v[184:187], v[98:101]
	v_mfma_f32_16x16x32_bf16 v[94:97], v[86:89], v[192:195], v[94:97]
	v_mfma_f32_16x16x32_bf16 v[90:93], v[142:145], v[192:195], v[90:93]
	v_mfma_f32_16x16x32_bf16 v[78:81], v[86:89], v[200:203], v[78:81]
	v_mfma_f32_16x16x32_bf16 v[74:77], v[142:145], v[200:203], v[74:77]
	v_mfma_f32_16x16x32_bf16 v[70:73], v[86:89], v[218:221], v[70:73]
	v_mfma_f32_16x16x32_bf16 v[66:69], v[142:145], v[218:221], v[66:69]
	v_mfma_f32_16x16x32_bf16 v[30:33], v[158:161], v[180:183], v[30:33]
	v_mfma_f32_16x16x32_bf16 v[26:29], v[172:175], v[180:183], v[26:29]
	v_mfma_f32_16x16x32_bf16 v[22:25], v[158:161], v[188:191], v[22:25]
	v_mfma_f32_16x16x32_bf16 v[18:21], v[172:175], v[188:191], v[18:21]
	v_mfma_f32_16x16x32_bf16 v[14:17], v[158:161], v[196:199], v[14:17]
	v_mfma_f32_16x16x32_bf16 v[10:13], v[172:175], v[196:199], v[10:13]
	v_mfma_f32_16x16x32_bf16 v[6:9], v[158:161], v[214:217], v[6:9]
	v_mfma_f32_16x16x32_bf16 v[2:5], v[172:175], v[214:217], v[2:5]
	v_mfma_f32_16x16x32_bf16 v[30:33], v[168:171], v[184:187], v[30:33]
	v_mfma_f32_16x16x32_bf16 v[26:29], v[176:179], v[184:187], v[26:29]
	v_mfma_f32_16x16x32_bf16 v[22:25], v[168:171], v[192:195], v[22:25]
	v_mfma_f32_16x16x32_bf16 v[18:21], v[176:179], v[192:195], v[18:21]
	v_mfma_f32_16x16x32_bf16 v[14:17], v[168:171], v[200:203], v[14:17]
	v_mfma_f32_16x16x32_bf16 v[10:13], v[176:179], v[200:203], v[10:13]
	v_mfma_f32_16x16x32_bf16 v[6:9], v[168:171], v[218:221], v[6:9]
	v_mfma_f32_16x16x32_bf16 v[2:5], v[176:179], v[218:221], v[2:5]
	s_barrier
	s_add_i32 s10, 0, 0x18000
	v_add_u32_e32 v1, s10, v165
	s_add_i32 s11, 0, 0x1c000
	ds_read_b128 v[82:85], v1
	ds_read_b128 v[86:89], v1 offset:1024
	ds_read_b128 v[138:141], v1 offset:2048
	ds_read_b128 v[142:145], v1 offset:3072
	v_add_u32_e32 v1, s11, v165
	ds_read_b128 v[158:161], v1
	ds_read_b128 v[168:171], v1 offset:1024
	ds_read_b128 v[172:175], v1 offset:2048
	ds_read_b128 v[176:179], v1 offset:3072
	s_add_u32 s4, s4, s12
	s_addc_u32 s5, s5, s13
	s_mov_b32 m0, s72
	v_lshl_add_u64 v[238:239], s[4:5], 0, v[152:153]
	ds_read_b128 v[180:183], v167 offset:32768
	ds_read_b128 v[184:187], v167 offset:33792
	ds_read_b128 v[188:191], v167 offset:34816
	ds_read_b128 v[192:195], v167 offset:35840
	ds_read_b128 v[196:199], v167 offset:36864
	ds_read_b128 v[200:203], v167 offset:37888
	ds_read_b128 v[214:217], v167 offset:38912
	ds_read_b128 v[218:221], v167 offset:39936
	global_load_lds_dwordx4 v[238:239], off
	v_lshl_add_u64 v[238:239], s[4:5], 0, v[148:149]
	s_mov_b32 m0, s73
	s_nop 0
	global_load_lds_dwordx4 v[238:239], off
	s_waitcnt vmcnt(8)
	s_waitcnt lgkmcnt(0)
	s_barrier
	s_waitcnt lgkmcnt(0)
	v_mfma_f32_16x16x32_bf16 v[134:137], v[82:85], v[180:183], v[134:137]
	v_mfma_f32_16x16x32_bf16 v[130:133], v[138:141], v[180:183], v[130:133]
	v_mfma_f32_16x16x32_bf16 v[126:129], v[82:85], v[188:191], v[126:129]
	v_mfma_f32_16x16x32_bf16 v[122:125], v[138:141], v[188:191], v[122:125]
	v_mfma_f32_16x16x32_bf16 v[118:121], v[82:85], v[196:199], v[118:121]
	v_mfma_f32_16x16x32_bf16 v[114:117], v[138:141], v[196:199], v[114:117]
	v_mfma_f32_16x16x32_bf16 v[110:113], v[82:85], v[214:217], v[110:113]
	v_mfma_f32_16x16x32_bf16 v[106:109], v[138:141], v[214:217], v[106:109]
	v_mfma_f32_16x16x32_bf16 v[134:137], v[86:89], v[184:187], v[134:137]
	v_mfma_f32_16x16x32_bf16 v[130:133], v[142:145], v[184:187], v[130:133]
	v_mfma_f32_16x16x32_bf16 v[126:129], v[86:89], v[192:195], v[126:129]
	v_mfma_f32_16x16x32_bf16 v[122:125], v[142:145], v[192:195], v[122:125]
	v_mfma_f32_16x16x32_bf16 v[118:121], v[86:89], v[200:203], v[118:121]
	v_mfma_f32_16x16x32_bf16 v[114:117], v[142:145], v[200:203], v[114:117]
	v_mfma_f32_16x16x32_bf16 v[110:113], v[86:89], v[218:221], v[110:113]
	v_mfma_f32_16x16x32_bf16 v[106:109], v[142:145], v[218:221], v[106:109]
	v_mfma_f32_16x16x32_bf16 v[62:65], v[158:161], v[180:183], v[62:65]
	v_mfma_f32_16x16x32_bf16 v[58:61], v[172:175], v[180:183], v[58:61]
	v_mfma_f32_16x16x32_bf16 v[54:57], v[158:161], v[188:191], v[54:57]
	v_mfma_f32_16x16x32_bf16 v[50:53], v[172:175], v[188:191], v[50:53]
	v_mfma_f32_16x16x32_bf16 v[46:49], v[158:161], v[196:199], v[46:49]
	v_mfma_f32_16x16x32_bf16 v[42:45], v[172:175], v[196:199], v[42:45]
	v_mfma_f32_16x16x32_bf16 v[38:41], v[158:161], v[214:217], v[38:41]
	v_mfma_f32_16x16x32_bf16 v[34:37], v[172:175], v[214:217], v[34:37]
	v_mfma_f32_16x16x32_bf16 v[62:65], v[168:171], v[184:187], v[62:65]
	v_mfma_f32_16x16x32_bf16 v[58:61], v[176:179], v[184:187], v[58:61]
	v_mfma_f32_16x16x32_bf16 v[54:57], v[168:171], v[192:195], v[54:57]
	v_mfma_f32_16x16x32_bf16 v[50:53], v[176:179], v[192:195], v[50:53]
	v_mfma_f32_16x16x32_bf16 v[46:49], v[168:171], v[200:203], v[46:49]
	v_mfma_f32_16x16x32_bf16 v[42:45], v[176:179], v[200:203], v[42:45]
	v_mfma_f32_16x16x32_bf16 v[38:41], v[168:171], v[218:221], v[38:41]
	v_mfma_f32_16x16x32_bf16 v[34:37], v[176:179], v[218:221], v[34:37]
	s_barrier
	s_add_i32 s4, s10, s65
	v_lshl_add_u64 v[162:163], v[162:163], 0, s[60:61]
	s_mov_b32 m0, s4
	ds_read_b128 v[180:183], v167 offset:49152
	ds_read_b128 v[184:187], v167 offset:50176
	ds_read_b128 v[188:191], v167 offset:51200
	ds_read_b128 v[192:195], v167 offset:52224
	ds_read_b128 v[196:199], v167 offset:53248
	ds_read_b128 v[200:203], v167 offset:54272
	ds_read_b128 v[214:217], v167 offset:55296
	ds_read_b128 v[218:221], v167 offset:56320
	global_load_lds_dwordx4 v[162:163], off
	v_lshl_add_u64 v[162:163], v[204:205], 0, s[60:61]
	s_add_i32 m0, s4, 0x2000
	s_add_i32 s4, s11, s65
	global_load_lds_dwordx4 v[162:163], off
	v_lshl_add_u64 v[162:163], v[222:223], 0, s[60:61]
	s_mov_b32 m0, s4
	s_nop 0
	global_load_lds_dwordx4 v[162:163], off
	v_lshl_add_u64 v[162:163], v[224:225], 0, s[60:61]
	s_add_i32 m0, s4, 0x2000
	s_nop 0
	global_load_lds_dwordx4 v[162:163], off
	v_lshl_add_u64 v[162:163], v[226:227], 0, s[60:61]
	s_mov_b32 m0, s74
	s_nop 0
	global_load_lds_dwordx4 v[162:163], off
	v_lshl_add_u64 v[162:163], v[236:237], 0, s[60:61]
	s_mov_b32 m0, s75
	s_nop 0
	global_load_lds_dwordx4 v[162:163], off
	s_waitcnt vmcnt(8)
	s_waitcnt lgkmcnt(0)
	s_barrier
	s_waitcnt lgkmcnt(0)
	v_mfma_f32_16x16x32_bf16 v[102:105], v[82:85], v[180:183], v[102:105]
	v_mfma_f32_16x16x32_bf16 v[98:101], v[138:141], v[180:183], v[98:101]
	v_mfma_f32_16x16x32_bf16 v[94:97], v[82:85], v[188:191], v[94:97]
	v_mfma_f32_16x16x32_bf16 v[90:93], v[138:141], v[188:191], v[90:93]
	v_mfma_f32_16x16x32_bf16 v[78:81], v[82:85], v[196:199], v[78:81]
	v_mfma_f32_16x16x32_bf16 v[74:77], v[138:141], v[196:199], v[74:77]
	v_mfma_f32_16x16x32_bf16 v[70:73], v[82:85], v[214:217], v[70:73]
	v_mfma_f32_16x16x32_bf16 v[66:69], v[138:141], v[214:217], v[66:69]
	v_mfma_f32_16x16x32_bf16 v[102:105], v[86:89], v[184:187], v[102:105]
	v_mfma_f32_16x16x32_bf16 v[98:101], v[142:145], v[184:187], v[98:101]
	v_mfma_f32_16x16x32_bf16 v[94:97], v[86:89], v[192:195], v[94:97]
	v_mfma_f32_16x16x32_bf16 v[90:93], v[142:145], v[192:195], v[90:93]
	v_mfma_f32_16x16x32_bf16 v[78:81], v[86:89], v[200:203], v[78:81]
	v_mfma_f32_16x16x32_bf16 v[74:77], v[142:145], v[200:203], v[74:77]
	v_mfma_f32_16x16x32_bf16 v[70:73], v[86:89], v[218:221], v[70:73]
	v_mfma_f32_16x16x32_bf16 v[66:69], v[142:145], v[218:221], v[66:69]
	v_mfma_f32_16x16x32_bf16 v[30:33], v[158:161], v[180:183], v[30:33]
	v_mfma_f32_16x16x32_bf16 v[26:29], v[172:175], v[180:183], v[26:29]
	v_mfma_f32_16x16x32_bf16 v[22:25], v[158:161], v[188:191], v[22:25]
	v_mfma_f32_16x16x32_bf16 v[18:21], v[172:175], v[188:191], v[18:21]
	v_mfma_f32_16x16x32_bf16 v[14:17], v[158:161], v[196:199], v[14:17]
	v_mfma_f32_16x16x32_bf16 v[10:13], v[172:175], v[196:199], v[10:13]
	v_mfma_f32_16x16x32_bf16 v[6:9], v[158:161], v[214:217], v[6:9]
	v_mfma_f32_16x16x32_bf16 v[2:5], v[172:175], v[214:217], v[2:5]
	v_mfma_f32_16x16x32_bf16 v[30:33], v[168:171], v[184:187], v[30:33]
	v_mfma_f32_16x16x32_bf16 v[26:29], v[176:179], v[184:187], v[26:29]
	v_mfma_f32_16x16x32_bf16 v[22:25], v[168:171], v[192:195], v[22:25]
	v_mfma_f32_16x16x32_bf16 v[18:21], v[176:179], v[192:195], v[18:21]
	v_mfma_f32_16x16x32_bf16 v[14:17], v[168:171], v[200:203], v[14:17]
	v_mfma_f32_16x16x32_bf16 v[10:13], v[176:179], v[200:203], v[10:13]
	v_mfma_f32_16x16x32_bf16 v[6:9], v[168:171], v[218:221], v[6:9]
	v_mfma_f32_16x16x32_bf16 v[2:5], v[176:179], v[218:221], v[2:5]
	s_barrier
	s_add_u32 s0, s0, 0x100
	s_addc_u32 s1, s1, 0
	s_add_u32 s6, s6, 0x100
	s_addc_u32 s7, s7, 0
	s_cmp_ge_i32 s9, s76
	s_mov_b32 s4, s9
	s_cbranch_scc0 .LBB0_1142
